# on top of MFMA-head trim: load segments use one combined s_waitcnt and SGPR-base DMA addressing (fewer VALU in loader stream)
# speedup vs baseline: 1.0122x; 1.0038x over previous
; #define PG8_STAGE(bufoff, gbase, voff) do { _Pragma("unroll") for (int _i = 0; _i < 2; ++_i) \
;         __builtin_amdgcn_global_load_lds((const unsigned*)((const char*)(gbase) + (voff)[_i]), (LAS unsigned*)(lds + (bufoff) + ldsw + _i * 8192), 16, 0, 0); } while (0)
; #define PG8_LDA(dst, b, h) do { _Pragma("unroll") for (int m = 0; m < 4; ++m) _Pragma("unroll") for (int k = 0; k < 2; ++k) dst[m][k] = *(const LAS bf16x8*)(lds + PG8_SA(b, h) + aoff + m * 2048 + k * 1024); } while (0)
; #define PG8_LDB(dst, b, h) do { _Pragma("unroll") for (int n = 0; n < 2; ++n) _Pragma("unroll") for (int k = 0; k < 2; ++k) dst[n][k] = *(const LAS bf16x8*)(lds + PG8_SB(b, h) + boff + n * 2048 + k * 1024); } while (0)
; #define PG8_MMA(ai, bj, At, Bt) do { __builtin_amdgcn_s_setprio(1); _Pragma("unroll") for (int m = 0; m < 4; ++m) _Pragma("unroll") for (int n = 0; n < 2; ++n) _Pragma("unroll") for (int k = 0; k < 2; ++k) \
;         acc[ai][bj][m][n] = __builtin_amdgcn_mfma_f32_16x16x32_bf16(Bt[n][k], At[m][k], acc[ai][bj][m][n], 0, 0, 0); __builtin_amdgcn_s_setprio(0); } while (0)
; #define PG8_WAIT_V(n) asm volatile("s_waitcnt vmcnt(" #n ")" ::: "memory")
; #define PG8_BAR __builtin_amdgcn_s_barrier()
; template <class Epi, class Sched, bool ABLK = false, bool ALIGN_EPI = true, bool SP2 = true, bool BBLK = true>
; __device__ __forceinline__ void gemm_phase(LAS unsigned char* lds, const Gemm g, const Sched& S, const Epi& E) {
;     ...
;             const bool last = (t == nt - 2);
;             const char* a1 = a_tile(uA, tbA + t + 1);
;             const char* a2 = last ? a_tile(nuA, ntbA) : a_tile(uA, tbA + t + 2); const char* b2 = last ? nB : cB + (size_t)(t + 2) * kstepB;
;             const char* a3 = last ? a_tile(nuA, ntbA + 1) : a_tile(uA, tbA + t + 3); const char* b3 = b2 + kstepB;
;             if (last && has_next) S.a_ready(nxt);
;             if constexpr (SP2) {
;             PG8_LDB(B0, 0, 0); PG8_LDB(B1, 0, 1); PG8_SCHED; PG8_LDA(At, 0, 0); PG8_STAGE(PG8_SA(1, 1), a1 + hstepA, voffA);
;             PG8_WAIT_V(8); PG8_WAIT_L(0); PG8_BAR; PG8_MMA(0, 0, At, B0); PG8_MMA(0, 1, At, B1); PG8_BAR; PG8_SCHED;
;             PG8_LDA(At, 0, 1); PG8_STAGE(PG8_SB(0, 0), b2, voffB); PG8_STAGE(PG8_SB(0, 1), b2 + hstepB, voffB); PG8_STAGE(PG8_SA(0, 0), a2, voffA);
;             PG8_WAIT_V(8); PG8_WAIT_L(0); PG8_BAR; PG8_MMA(1, 0, At, B0); PG8_MMA(1, 1, At, B1); PG8_BAR; PG8_SCHED;
.LBB0_350:
	ds_read_b128 v[152:155], v148
	ds_read_b128 v[156:159], v148 offset:1024
	ds_read_b128 v[160:163], v148 offset:2048
	ds_read_b128 v[164:167], v148 offset:3072
	ds_read_b128 v[168:171], v149
	ds_read_b128 v[172:175], v149 offset:1024
	ds_read_b128 v[176:179], v149 offset:2048
	ds_read_b128 v[180:183], v149 offset:3072
	s_add_u32 s28, s24, s26
	s_addc_u32 s29, s25, s27
	s_add_u32 s34, s28, 0x100
	s_addc_u32 s35, s29, 0
	s_add_u32 s28, s28, 0x180
	s_addc_u32 s29, s29, 0
	s_cmpk_eq_i32 s26, 0xf00
	s_cselect_b32 s29, s51, s29
	s_cselect_b32 s28, s50, s28
	s_cselect_b32 s31, s9, s53
	s_cselect_b32 s30, s11, s52
	s_cselect_b32 s35, s4, s35
	s_cselect_b32 s34, s5, s34
	s_mov_b32 m0, s49
	v_lshl_add_u64 v[216:217], v[142:143], 0, s[26:27]
	ds_read_b128 v[184:187], v150
	ds_read_b128 v[188:191], v150 offset:1024
	ds_read_b128 v[192:195], v150 offset:2048
	ds_read_b128 v[196:199], v150 offset:3072
	ds_read_b128 v[200:203], v150 offset:4096
	ds_read_b128 v[204:207], v150 offset:5120
	ds_read_b128 v[208:211], v150 offset:6144
	ds_read_b128 v[212:215], v150 offset:7168
	global_load_lds_dwordx4 v[216:217], off
	v_lshl_add_u64 v[216:217], v[144:145], 0, s[26:27]
	s_add_i32 m0, s21, 0xe000
	s_nop 0
	global_load_lds_dwordx4 v[216:217], off
	s_waitcnt vmcnt(8) lgkmcnt(0)
	s_barrier
	v_mfma_f32_16x16x32_bf16 v[122:125], v[152:155], v[184:187], v[122:125]
	v_mfma_f32_16x16x32_bf16 v[118:121], v[160:163], v[184:187], v[118:121]
	v_mfma_f32_16x16x32_bf16 v[106:109], v[152:155], v[192:195], v[106:109]
	v_mfma_f32_16x16x32_bf16 v[102:105], v[160:163], v[192:195], v[102:105]
	v_mfma_f32_16x16x32_bf16 v[90:93], v[152:155], v[200:203], v[90:93]
	v_mfma_f32_16x16x32_bf16 v[86:89], v[160:163], v[200:203], v[86:89]
	v_mfma_f32_16x16x32_bf16 v[74:77], v[152:155], v[208:211], v[74:77]
	v_mfma_f32_16x16x32_bf16 v[70:73], v[160:163], v[208:211], v[70:73]
	v_mfma_f32_16x16x32_bf16 v[122:125], v[156:159], v[188:191], v[122:125]
	v_mfma_f32_16x16x32_bf16 v[118:121], v[164:167], v[188:191], v[118:121]
	v_mfma_f32_16x16x32_bf16 v[106:109], v[156:159], v[196:199], v[106:109]
	v_mfma_f32_16x16x32_bf16 v[102:105], v[164:167], v[196:199], v[102:105]
	v_mfma_f32_16x16x32_bf16 v[90:93], v[156:159], v[204:207], v[90:93]
	v_mfma_f32_16x16x32_bf16 v[86:89], v[164:167], v[204:207], v[86:89]
	v_mfma_f32_16x16x32_bf16 v[74:77], v[156:159], v[212:215], v[74:77]
	v_mfma_f32_16x16x32_bf16 v[70:73], v[164:167], v[212:215], v[70:73]
	v_mfma_f32_16x16x32_bf16 v[126:129], v[168:171], v[184:187], v[126:129]
	v_mfma_f32_16x16x32_bf16 v[114:117], v[176:179], v[184:187], v[114:117]
	v_mfma_f32_16x16x32_bf16 v[110:113], v[168:171], v[192:195], v[110:113]
	v_mfma_f32_16x16x32_bf16 v[98:101], v[176:179], v[192:195], v[98:101]
	v_mfma_f32_16x16x32_bf16 v[94:97], v[168:171], v[200:203], v[94:97]
	v_mfma_f32_16x16x32_bf16 v[82:85], v[176:179], v[200:203], v[82:85]
	v_mfma_f32_16x16x32_bf16 v[78:81], v[168:171], v[208:211], v[78:81]
	v_mfma_f32_16x16x32_bf16 v[66:69], v[176:179], v[208:211], v[66:69]
	v_mfma_f32_16x16x32_bf16 v[126:129], v[172:175], v[188:191], v[126:129]
	v_mfma_f32_16x16x32_bf16 v[114:117], v[180:183], v[188:191], v[114:117]
	v_mfma_f32_16x16x32_bf16 v[110:113], v[172:175], v[196:199], v[110:113]
	v_mfma_f32_16x16x32_bf16 v[98:101], v[180:183], v[196:199], v[98:101]
	v_mfma_f32_16x16x32_bf16 v[94:97], v[172:175], v[204:207], v[94:97]
	v_mfma_f32_16x16x32_bf16 v[82:85], v[180:183], v[204:207], v[82:85]
	v_mfma_f32_16x16x32_bf16 v[78:81], v[172:175], v[212:215], v[78:81]
	v_mfma_f32_16x16x32_bf16 v[66:69], v[180:183], v[212:215], v[66:69]
	s_barrier
	s_add_i32 s55, s44, s33
	s_mov_b32 m0, s55
	ds_read_b128 v[184:187], v150 offset:16384
	ds_read_b128 v[188:191], v150 offset:17408
	ds_read_b128 v[192:195], v150 offset:18432
	ds_read_b128 v[196:199], v150 offset:19456
	ds_read_b128 v[200:203], v150 offset:20480
	ds_read_b128 v[204:207], v150 offset:21504
	ds_read_b128 v[208:211], v150 offset:22528
	ds_read_b128 v[212:215], v150 offset:23552
	global_load_lds_dwordx4 v134, s[30:31]
	s_add_i32 m0, s55, 0x2000
	s_add_u32 s56, s30, 0x4000
	s_addc_u32 s57, s31, 0
	s_add_i32 s55, s45, s33
	global_load_lds_dwordx4 v130, s[30:31]
	s_mov_b32 m0, s55
	s_nop 0
	global_load_lds_dwordx4 v134, s[56:57]
	s_add_i32 m0, s55, 0x2000
	s_nop 0
	global_load_lds_dwordx4 v130, s[56:57]
	s_mov_b32 m0, s21
	s_nop 0
	global_load_lds_dwordx4 v136, s[34:35]
	s_mov_b32 m0, s23
	s_nop 0
	global_load_lds_dwordx4 v132, s[34:35]
	s_waitcnt vmcnt(8) lgkmcnt(0)
	s_barrier
	v_mfma_f32_16x16x32_bf16 v[58:61], v[152:155], v[184:187], v[58:61]
	v_mfma_f32_16x16x32_bf16 v[54:57], v[160:163], v[184:187], v[54:57]
	v_mfma_f32_16x16x32_bf16 v[42:45], v[152:155], v[192:195], v[42:45]
	v_mfma_f32_16x16x32_bf16 v[38:41], v[160:163], v[192:195], v[38:41]
	v_mfma_f32_16x16x32_bf16 v[26:29], v[152:155], v[200:203], v[26:29]
	v_mfma_f32_16x16x32_bf16 v[22:25], v[160:163], v[200:203], v[22:25]
	v_mfma_f32_16x16x32_bf16 v[10:13], v[152:155], v[208:211], v[10:13]
	v_mfma_f32_16x16x32_bf16 v[6:9], v[160:163], v[208:211], v[6:9]
	v_mfma_f32_16x16x32_bf16 v[58:61], v[156:159], v[188:191], v[58:61]
	v_mfma_f32_16x16x32_bf16 v[54:57], v[164:167], v[188:191], v[54:57]
	v_mfma_f32_16x16x32_bf16 v[42:45], v[156:159], v[196:199], v[42:45]
	v_mfma_f32_16x16x32_bf16 v[38:41], v[164:167], v[196:199], v[38:41]
	v_mfma_f32_16x16x32_bf16 v[26:29], v[156:159], v[204:207], v[26:29]
	v_mfma_f32_16x16x32_bf16 v[22:25], v[164:167], v[204:207], v[22:25]
	v_mfma_f32_16x16x32_bf16 v[10:13], v[156:159], v[212:215], v[10:13]
	v_mfma_f32_16x16x32_bf16 v[6:9], v[164:167], v[212:215], v[6:9]
	v_mfma_f32_16x16x32_bf16 v[62:65], v[168:171], v[184:187], v[62:65]
	v_mfma_f32_16x16x32_bf16 v[50:53], v[176:179], v[184:187], v[50:53]
	v_mfma_f32_16x16x32_bf16 v[46:49], v[168:171], v[192:195], v[46:49]
	v_mfma_f32_16x16x32_bf16 v[34:37], v[176:179], v[192:195], v[34:37]
	v_mfma_f32_16x16x32_bf16 v[30:33], v[168:171], v[200:203], v[30:33]
	v_mfma_f32_16x16x32_bf16 v[18:21], v[176:179], v[200:203], v[18:21]
	v_mfma_f32_16x16x32_bf16 v[14:17], v[168:171], v[208:211], v[14:17]
	v_mfma_f32_16x16x32_bf16 v[2:5], v[176:179], v[208:211], v[2:5]
	v_mfma_f32_16x16x32_bf16 v[62:65], v[172:175], v[188:191], v[62:65]
	v_mfma_f32_16x16x32_bf16 v[50:53], v[180:183], v[188:191], v[50:53]
	v_mfma_f32_16x16x32_bf16 v[46:49], v[172:175], v[196:199], v[46:49]
	v_mfma_f32_16x16x32_bf16 v[34:37], v[180:183], v[196:199], v[34:37]
	v_mfma_f32_16x16x32_bf16 v[30:33], v[172:175], v[204:207], v[30:33]
	v_mfma_f32_16x16x32_bf16 v[18:21], v[180:183], v[204:207], v[18:21]
	v_mfma_f32_16x16x32_bf16 v[14:17], v[172:175], v[212:215], v[14:17]
	v_mfma_f32_16x16x32_bf16 v[2:5], v[180:183], v[212:215], v[2:5]
	s_barrier
; #define PG8_STAGE(bufoff, gbase, voff) do { _Pragma("unroll") for (int _i = 0; _i < 2; ++_i) \
;         __builtin_amdgcn_global_load_lds((const unsigned*)((const char*)(gbase) + (voff)[_i]), (LAS unsigned*)(lds + (bufoff) + ldsw + _i * 8192), 16, 0, 0); } while (0)
; #define PG8_LDA(dst, b, h) do { _Pragma("unroll") for (int m = 0; m < 4; ++m) _Pragma("unroll") for (int k = 0; k < 2; ++k) dst[m][k] = *(const LAS bf16x8*)(lds + PG8_SA(b, h) + aoff + m * 2048 + k * 1024); } while (0)
; #define PG8_LDB(dst, b, h) do { _Pragma("unroll") for (int n = 0; n < 2; ++n) _Pragma("unroll") for (int k = 0; k < 2; ++k) dst[n][k] = *(const LAS bf16x8*)(lds + PG8_SB(b, h) + boff + n * 2048 + k * 1024); } while (0)
; #define PG8_MMA(ai, bj, At, Bt) do { __builtin_amdgcn_s_setprio(1); _Pragma("unroll") for (int m = 0; m < 4; ++m) _Pragma("unroll") for (int n = 0; n < 2; ++n) _Pragma("unroll") for (int k = 0; k < 2; ++k) \
;         acc[ai][bj][m][n] = __builtin_amdgcn_mfma_f32_16x16x32_bf16(Bt[n][k], At[m][k], acc[ai][bj][m][n], 0, 0, 0); __builtin_amdgcn_s_setprio(0); } while (0)
; #define PG8_WAIT_V(n) asm volatile("s_waitcnt vmcnt(" #n ")" ::: "memory")
; #define PG8_WAIT_L(n) asm volatile("s_waitcnt lgkmcnt(" #n ")" ::: "memory")
; #define PG8_BAR __builtin_amdgcn_s_barrier()
; #define PG8_SCHED __builtin_amdgcn_sched_barrier(0)
; template <class Epi, class Sched, bool ABLK = false, bool ALIGN_EPI = true, bool SP2 = true, bool BBLK = true>
; __device__ __forceinline__ void gemm_phase(LAS unsigned char* lds, const Gemm g, const Sched& S, const Epi& E) {
;     ...
;             PG8_LDB(B0, 1, 0); PG8_LDB(B1, 1, 1); PG8_SCHED; PG8_LDA(At, 1, 0); PG8_STAGE(PG8_SA(0, 1), a2 + hstepA, voffA);
;             PG8_WAIT_V(8); PG8_WAIT_L(0); PG8_BAR; PG8_MMA(0, 0, At, B0); PG8_MMA(0, 1, At, B1); PG8_BAR; PG8_SCHED;
;             PG8_LDA(At, 1, 1); PG8_STAGE(PG8_SB(1, 0), b3, voffB); PG8_STAGE(PG8_SB(1, 1), b3 + hstepB, voffB); PG8_STAGE(PG8_SA(1, 0), a3, voffA);
;             PG8_WAIT_V(8); PG8_WAIT_L(0); PG8_BAR; PG8_MMA(1, 0, At, B0); PG8_MMA(1, 1, At, B1); PG8_BAR; PG8_SCHED;
	s_add_i32 s55, 0, 0x18000
	v_add_u32_e32 v151, s55, v146
	s_add_i32 s56, 0, 0x1c000
	ds_read_b128 v[152:155], v151
	ds_read_b128 v[156:159], v151 offset:1024
	ds_read_b128 v[160:163], v151 offset:2048
	ds_read_b128 v[164:167], v151 offset:3072
	v_add_u32_e32 v151, s56, v146
	ds_read_b128 v[168:171], v151
	ds_read_b128 v[172:175], v151 offset:1024
	ds_read_b128 v[176:179], v151 offset:2048
	ds_read_b128 v[180:183], v151 offset:3072
	s_add_u32 s34, s34, 0x80000
	s_addc_u32 s35, s35, 0
	s_mov_b32 m0, s39
	ds_read_b128 v[184:187], v150 offset:32768
	ds_read_b128 v[188:191], v150 offset:33792
	ds_read_b128 v[192:195], v150 offset:34816
	ds_read_b128 v[196:199], v150 offset:35840
	ds_read_b128 v[200:203], v150 offset:36864
	ds_read_b128 v[204:207], v150 offset:37888
	ds_read_b128 v[208:211], v150 offset:38912
	ds_read_b128 v[212:215], v150 offset:39936
	global_load_lds_dwordx4 v136, s[34:35]
	s_mov_b32 m0, s40
	s_nop 0
	global_load_lds_dwordx4 v132, s[34:35]
	s_waitcnt vmcnt(8) lgkmcnt(0)
	s_barrier
	v_mfma_f32_16x16x32_bf16 v[122:125], v[152:155], v[184:187], v[122:125]
	v_mfma_f32_16x16x32_bf16 v[118:121], v[160:163], v[184:187], v[118:121]
	v_mfma_f32_16x16x32_bf16 v[106:109], v[152:155], v[192:195], v[106:109]
	v_mfma_f32_16x16x32_bf16 v[102:105], v[160:163], v[192:195], v[102:105]
	v_mfma_f32_16x16x32_bf16 v[90:93], v[152:155], v[200:203], v[90:93]
	v_mfma_f32_16x16x32_bf16 v[86:89], v[160:163], v[200:203], v[86:89]
	v_mfma_f32_16x16x32_bf16 v[74:77], v[152:155], v[208:211], v[74:77]
	v_mfma_f32_16x16x32_bf16 v[70:73], v[160:163], v[208:211], v[70:73]
	v_mfma_f32_16x16x32_bf16 v[122:125], v[156:159], v[188:191], v[122:125]
	v_mfma_f32_16x16x32_bf16 v[118:121], v[164:167], v[188:191], v[118:121]
	v_mfma_f32_16x16x32_bf16 v[106:109], v[156:159], v[196:199], v[106:109]
	v_mfma_f32_16x16x32_bf16 v[102:105], v[164:167], v[196:199], v[102:105]
	v_mfma_f32_16x16x32_bf16 v[90:93], v[156:159], v[204:207], v[90:93]
	v_mfma_f32_16x16x32_bf16 v[86:89], v[164:167], v[204:207], v[86:89]
	v_mfma_f32_16x16x32_bf16 v[74:77], v[156:159], v[212:215], v[74:77]
	v_mfma_f32_16x16x32_bf16 v[70:73], v[164:167], v[212:215], v[70:73]
	v_mfma_f32_16x16x32_bf16 v[126:129], v[168:171], v[184:187], v[126:129]
	v_mfma_f32_16x16x32_bf16 v[114:117], v[176:179], v[184:187], v[114:117]
	v_mfma_f32_16x16x32_bf16 v[110:113], v[168:171], v[192:195], v[110:113]
	v_mfma_f32_16x16x32_bf16 v[98:101], v[176:179], v[192:195], v[98:101]
	v_mfma_f32_16x16x32_bf16 v[94:97], v[168:171], v[200:203], v[94:97]
	v_mfma_f32_16x16x32_bf16 v[82:85], v[176:179], v[200:203], v[82:85]
	v_mfma_f32_16x16x32_bf16 v[78:81], v[168:171], v[208:211], v[78:81]
	v_mfma_f32_16x16x32_bf16 v[66:69], v[176:179], v[208:211], v[66:69]
	v_mfma_f32_16x16x32_bf16 v[126:129], v[172:175], v[188:191], v[126:129]
	v_mfma_f32_16x16x32_bf16 v[114:117], v[180:183], v[188:191], v[114:117]
	v_mfma_f32_16x16x32_bf16 v[110:113], v[172:175], v[196:199], v[110:113]
	v_mfma_f32_16x16x32_bf16 v[98:101], v[180:183], v[196:199], v[98:101]
	v_mfma_f32_16x16x32_bf16 v[94:97], v[172:175], v[204:207], v[94:97]
	v_mfma_f32_16x16x32_bf16 v[82:85], v[180:183], v[204:207], v[82:85]
	v_mfma_f32_16x16x32_bf16 v[78:81], v[172:175], v[212:215], v[78:81]
	v_mfma_f32_16x16x32_bf16 v[66:69], v[180:183], v[212:215], v[66:69]
	s_barrier
	s_add_u32 s34, s30, 0x8000
	s_addc_u32 s35, s31, 0
	s_add_i32 s55, s55, s33
	s_mov_b32 m0, s55
	ds_read_b128 v[184:187], v150 offset:49152
	ds_read_b128 v[188:191], v150 offset:50176
	ds_read_b128 v[192:195], v150 offset:51200
	ds_read_b128 v[196:199], v150 offset:52224
	ds_read_b128 v[200:203], v150 offset:53248
	ds_read_b128 v[204:207], v150 offset:54272
	ds_read_b128 v[208:211], v150 offset:55296
	ds_read_b128 v[212:215], v150 offset:56320
	global_load_lds_dwordx4 v134, s[34:35]
	s_add_i32 m0, s55, 0x2000
	s_add_u32 s30, s30, 0xc000
	v_lshl_add_u64 v[216:217], s[34:35], 0, v[130:131]
	s_addc_u32 s31, s31, 0
	s_add_i32 s34, s56, s33
	global_load_lds_dwordx4 v[216:217], off
	s_mov_b32 m0, s34
	s_nop 0
	global_load_lds_dwordx4 v134, s[30:31]
	s_add_i32 m0, s34, 0x2000
	s_nop 0
	global_load_lds_dwordx4 v130, s[30:31]
	s_mov_b32 m0, s42
	s_nop 0
	global_load_lds_dwordx4 v136, s[28:29]
	s_mov_b32 m0, s43
	s_nop 0
	global_load_lds_dwordx4 v132, s[28:29]
	s_waitcnt vmcnt(8) lgkmcnt(0)
	s_barrier
	v_mfma_f32_16x16x32_bf16 v[58:61], v[152:155], v[184:187], v[58:61]
	v_mfma_f32_16x16x32_bf16 v[54:57], v[160:163], v[184:187], v[54:57]
	v_mfma_f32_16x16x32_bf16 v[42:45], v[152:155], v[192:195], v[42:45]
	v_mfma_f32_16x16x32_bf16 v[38:41], v[160:163], v[192:195], v[38:41]
	v_mfma_f32_16x16x32_bf16 v[26:29], v[152:155], v[200:203], v[26:29]
	v_mfma_f32_16x16x32_bf16 v[22:25], v[160:163], v[200:203], v[22:25]
	v_mfma_f32_16x16x32_bf16 v[10:13], v[152:155], v[208:211], v[10:13]
	v_mfma_f32_16x16x32_bf16 v[6:9], v[160:163], v[208:211], v[6:9]
	v_mfma_f32_16x16x32_bf16 v[58:61], v[156:159], v[188:191], v[58:61]
	v_mfma_f32_16x16x32_bf16 v[54:57], v[164:167], v[188:191], v[54:57]
	v_mfma_f32_16x16x32_bf16 v[42:45], v[156:159], v[196:199], v[42:45]
	v_mfma_f32_16x16x32_bf16 v[38:41], v[164:167], v[196:199], v[38:41]
	v_mfma_f32_16x16x32_bf16 v[26:29], v[156:159], v[204:207], v[26:29]
	v_mfma_f32_16x16x32_bf16 v[22:25], v[164:167], v[204:207], v[22:25]
	v_mfma_f32_16x16x32_bf16 v[10:13], v[156:159], v[212:215], v[10:13]
	v_mfma_f32_16x16x32_bf16 v[6:9], v[164:167], v[212:215], v[6:9]
	v_mfma_f32_16x16x32_bf16 v[62:65], v[168:171], v[184:187], v[62:65]
	v_mfma_f32_16x16x32_bf16 v[50:53], v[176:179], v[184:187], v[50:53]
	v_mfma_f32_16x16x32_bf16 v[46:49], v[168:171], v[192:195], v[46:49]
	v_mfma_f32_16x16x32_bf16 v[34:37], v[176:179], v[192:195], v[34:37]
	v_mfma_f32_16x16x32_bf16 v[30:33], v[168:171], v[200:203], v[30:33]
	v_mfma_f32_16x16x32_bf16 v[18:21], v[176:179], v[200:203], v[18:21]
	v_mfma_f32_16x16x32_bf16 v[14:17], v[168:171], v[208:211], v[14:17]
	v_mfma_f32_16x16x32_bf16 v[2:5], v[176:179], v[208:211], v[2:5]
	v_mfma_f32_16x16x32_bf16 v[62:65], v[172:175], v[188:191], v[62:65]
	v_mfma_f32_16x16x32_bf16 v[50:53], v[180:183], v[188:191], v[50:53]
	v_mfma_f32_16x16x32_bf16 v[46:49], v[172:175], v[196:199], v[46:49]
	v_mfma_f32_16x16x32_bf16 v[34:37], v[180:183], v[196:199], v[34:37]
	v_mfma_f32_16x16x32_bf16 v[30:33], v[172:175], v[204:207], v[30:33]
	v_mfma_f32_16x16x32_bf16 v[18:21], v[180:183], v[204:207], v[18:21]
	v_mfma_f32_16x16x32_bf16 v[14:17], v[172:175], v[212:215], v[14:17]
	v_mfma_f32_16x16x32_bf16 v[2:5], v[180:183], v[212:215], v[2:5]
	s_barrier
	s_add_i32 s54, s54, 2
	s_add_u32 s26, s26, 0x100
	s_addc_u32 s27, s27, 0
	s_add_u32 s52, s52, 0x10000
	s_addc_u32 s53, s53, 0
	s_cmp_gt_u32 s54, 29
	s_cbranch_scc0 .LBB0_350
	s_and_b64 vcc, exec, s[6:7]
	s_cbranch_vccz .LBB0_353
	s_barrier

; #define PG8_STAGE(bufoff, gbase, voff) do { _Pragma("unroll") for (int _i = 0; _i < 2; ++_i) \
;         __builtin_amdgcn_global_load_lds((const unsigned*)((const char*)(gbase) + (voff)[_i]), (LAS unsigned*)(lds + (bufoff) + ldsw + _i * 8192), 16, 0, 0); } while (0)
; #define PG8_LDA(dst, b, h) do { _Pragma("unroll") for (int m = 0; m < 4; ++m) _Pragma("unroll") for (int k = 0; k < 2; ++k) dst[m][k] = *(const LAS bf16x8*)(lds + PG8_SA(b, h) + aoff + m * 2048 + k * 1024); } while (0)
; #define PG8_LDB(dst, b, h) do { _Pragma("unroll") for (int n = 0; n < 2; ++n) _Pragma("unroll") for (int k = 0; k < 2; ++k) dst[n][k] = *(const LAS bf16x8*)(lds + PG8_SB(b, h) + boff + n * 2048 + k * 1024); } while (0)
; #define PG8_MMA(ai, bj, At, Bt) do { __builtin_amdgcn_s_setprio(1); _Pragma("unroll") for (int m = 0; m < 4; ++m) _Pragma("unroll") for (int n = 0; n < 2; ++n) _Pragma("unroll") for (int k = 0; k < 2; ++k) \
;         acc[ai][bj][m][n] = __builtin_amdgcn_mfma_f32_16x16x32_bf16(Bt[n][k], At[m][k], acc[ai][bj][m][n], 0, 0, 0); __builtin_amdgcn_s_setprio(0); } while (0)
; #define PG8_WAIT_V(n) asm volatile("s_waitcnt vmcnt(" #n ")" ::: "memory")
; template <class Epi, class Sched, bool ABLK = false, bool ALIGN_EPI = true, bool SP2 = true, bool BBLK = true>
; __device__ __forceinline__ void gemm_phase(LAS unsigned char* lds, const Gemm g, const Sched& S, const Epi& E) {
;     ...
;         for (int t = 0; t < nt; t += 2) {
;             const bool last = (t == nt - 2);
;             const char* a1 = a_tile(uA, tbA + t + 1);
;             const char* a2 = last ? a_tile(nuA, ntbA) : a_tile(uA, tbA + t + 2); const char* b2 = last ? nB : cB + (size_t)(t + 2) * kstepB;
;             const char* a3 = last ? a_tile(nuA, ntbA + 1) : a_tile(uA, tbA + t + 3); const char* b3 = b2 + kstepB;
;             if (last && has_next) S.a_ready(nxt);
;             if constexpr (SP2) {
;             PG8_LDB(B0, 0, 0); PG8_LDB(B1, 0, 1); PG8_SCHED; PG8_LDA(At, 0, 0); PG8_STAGE(PG8_SA(1, 1), a1 + hstepA, voffA);
;             PG8_WAIT_V(8); PG8_WAIT_L(0); PG8_BAR; PG8_MMA(0, 0, At, B0); PG8_MMA(0, 1, At, B1); PG8_BAR; PG8_SCHED;
;             PG8_LDA(At, 0, 1); PG8_STAGE(PG8_SB(0, 0), b2, voffB); PG8_STAGE(PG8_SB(0, 1), b2 + hstepB, voffB); PG8_STAGE(PG8_SA(0, 0), a2, voffA);
;             PG8_WAIT_V(8); PG8_WAIT_L(0); PG8_BAR; PG8_MMA(1, 0, At, B0); PG8_MMA(1, 1, At, B1); PG8_BAR; PG8_SCHED;
.LBB0_475:
	ds_read_b128 v[172:175], v168
	ds_read_b128 v[176:179], v168 offset:1024
	ds_read_b128 v[180:183], v168 offset:2048
	ds_read_b128 v[184:187], v168 offset:3072
	ds_read_b128 v[188:191], v169
	ds_read_b128 v[192:195], v169 offset:1024
	ds_read_b128 v[196:199], v169 offset:2048
	ds_read_b128 v[200:203], v169 offset:3072
	s_add_u32 s30, s26, s28
	s_addc_u32 s31, s27, s29
	s_add_u32 s36, s30, 0x100
	s_addc_u32 s37, s31, 0
	s_add_u32 s30, s30, 0x180
	s_addc_u32 s31, s31, 0
	s_cmpk_eq_i32 s28, 0xf00
	s_cselect_b32 s31, s57, s31
	s_cselect_b32 s30, s23, s30
	s_cselect_b32 s35, s11, s59
	s_cselect_b32 s34, s13, s58
	s_cselect_b32 s37, s4, s37
	s_cselect_b32 s36, s5, s36
	s_mov_b32 m0, s53
	v_lshl_add_u64 v[236:237], v[164:165], 0, s[28:29]
	ds_read_b128 v[204:207], v170
	ds_read_b128 v[208:211], v170 offset:1024
	ds_read_b128 v[212:215], v170 offset:2048
	ds_read_b128 v[216:219], v170 offset:3072
	ds_read_b128 v[220:223], v170 offset:4096
	ds_read_b128 v[224:227], v170 offset:5120
	ds_read_b128 v[228:231], v170 offset:6144
	ds_read_b128 v[232:235], v170 offset:7168
	global_load_lds_dwordx4 v[236:237], off
	v_lshl_add_u64 v[236:237], v[166:167], 0, s[28:29]
	s_mov_b32 m0, s54
	s_nop 0
	global_load_lds_dwordx4 v[236:237], off
	s_waitcnt vmcnt(8) lgkmcnt(0)
	s_barrier
	v_mfma_f32_16x16x32_bf16 v[126:129], v[172:175], v[204:207], v[126:129]
	v_mfma_f32_16x16x32_bf16 v[122:125], v[180:183], v[204:207], v[122:125]
	v_mfma_f32_16x16x32_bf16 v[110:113], v[172:175], v[212:215], v[110:113]
	v_mfma_f32_16x16x32_bf16 v[106:109], v[180:183], v[212:215], v[106:109]
	v_mfma_f32_16x16x32_bf16 v[94:97], v[172:175], v[220:223], v[94:97]
	v_mfma_f32_16x16x32_bf16 v[90:93], v[180:183], v[220:223], v[90:93]
	v_mfma_f32_16x16x32_bf16 v[78:81], v[172:175], v[228:231], v[78:81]
	v_mfma_f32_16x16x32_bf16 v[74:77], v[180:183], v[228:231], v[74:77]
	v_mfma_f32_16x16x32_bf16 v[126:129], v[176:179], v[208:211], v[126:129]
	v_mfma_f32_16x16x32_bf16 v[122:125], v[184:187], v[208:211], v[122:125]
	v_mfma_f32_16x16x32_bf16 v[110:113], v[176:179], v[216:219], v[110:113]
	v_mfma_f32_16x16x32_bf16 v[106:109], v[184:187], v[216:219], v[106:109]
	v_mfma_f32_16x16x32_bf16 v[94:97], v[176:179], v[224:227], v[94:97]
	v_mfma_f32_16x16x32_bf16 v[90:93], v[184:187], v[224:227], v[90:93]
	v_mfma_f32_16x16x32_bf16 v[78:81], v[176:179], v[232:235], v[78:81]
	v_mfma_f32_16x16x32_bf16 v[74:77], v[184:187], v[232:235], v[74:77]
	v_mfma_f32_16x16x32_bf16 v[118:121], v[188:191], v[204:207], v[118:121]
	v_mfma_f32_16x16x32_bf16 v[114:117], v[196:199], v[204:207], v[114:117]
	v_mfma_f32_16x16x32_bf16 v[102:105], v[188:191], v[212:215], v[102:105]
	v_mfma_f32_16x16x32_bf16 v[98:101], v[196:199], v[212:215], v[98:101]
	v_mfma_f32_16x16x32_bf16 v[86:89], v[188:191], v[220:223], v[86:89]
	v_mfma_f32_16x16x32_bf16 v[82:85], v[196:199], v[220:223], v[82:85]
	v_mfma_f32_16x16x32_bf16 v[70:73], v[188:191], v[228:231], v[70:73]
	v_mfma_f32_16x16x32_bf16 v[66:69], v[196:199], v[228:231], v[66:69]
	v_mfma_f32_16x16x32_bf16 v[118:121], v[192:195], v[208:211], v[118:121]
	v_mfma_f32_16x16x32_bf16 v[114:117], v[200:203], v[208:211], v[114:117]
	v_mfma_f32_16x16x32_bf16 v[102:105], v[192:195], v[216:219], v[102:105]
	v_mfma_f32_16x16x32_bf16 v[98:101], v[200:203], v[216:219], v[98:101]
	v_mfma_f32_16x16x32_bf16 v[86:89], v[192:195], v[224:227], v[86:89]
	v_mfma_f32_16x16x32_bf16 v[82:85], v[200:203], v[224:227], v[82:85]
	v_mfma_f32_16x16x32_bf16 v[70:73], v[192:195], v[232:235], v[70:73]
	v_mfma_f32_16x16x32_bf16 v[66:69], v[200:203], v[232:235], v[66:69]
	s_barrier
	s_mov_b32 m0, s55
	s_add_u32 s62, s34, 0x4000
	ds_read_b128 v[204:207], v170 offset:16384
	ds_read_b128 v[208:211], v170 offset:17408
	ds_read_b128 v[212:215], v170 offset:18432
	ds_read_b128 v[216:219], v170 offset:19456
	ds_read_b128 v[220:223], v170 offset:20480
	ds_read_b128 v[224:227], v170 offset:21504
	ds_read_b128 v[228:231], v170 offset:22528
	ds_read_b128 v[232:235], v170 offset:23552
	global_load_lds_dwordx4 v134, s[34:35]
	s_mov_b32 m0, s56
	s_addc_u32 s63, s35, 0
	s_add_i32 s61, s52, s40
	global_load_lds_dwordx4 v130, s[34:35]
	s_mov_b32 m0, s61
	s_nop 0
	global_load_lds_dwordx4 v134, s[62:63]
	s_add_i32 m0, s61, 0x2000
	s_nop 0
	global_load_lds_dwordx4 v130, s[62:63]
	s_mov_b32 m0, s25
	s_nop 0
	global_load_lds_dwordx4 v136, s[36:37]
	s_mov_b32 m0, s43
	s_nop 0
	global_load_lds_dwordx4 v132, s[36:37]
	s_waitcnt vmcnt(8) lgkmcnt(0)
	s_barrier
	v_mfma_f32_16x16x32_bf16 v[62:65], v[172:175], v[204:207], v[62:65]
	v_mfma_f32_16x16x32_bf16 v[58:61], v[180:183], v[204:207], v[58:61]
	v_mfma_f32_16x16x32_bf16 v[46:49], v[172:175], v[212:215], v[46:49]
	v_mfma_f32_16x16x32_bf16 v[42:45], v[180:183], v[212:215], v[42:45]
	v_mfma_f32_16x16x32_bf16 v[30:33], v[172:175], v[220:223], v[30:33]
	v_mfma_f32_16x16x32_bf16 v[26:29], v[180:183], v[220:223], v[26:29]
	v_mfma_f32_16x16x32_bf16 v[14:17], v[172:175], v[228:231], v[14:17]
	v_mfma_f32_16x16x32_bf16 v[10:13], v[180:183], v[228:231], v[10:13]
	v_mfma_f32_16x16x32_bf16 v[62:65], v[176:179], v[208:211], v[62:65]
	v_mfma_f32_16x16x32_bf16 v[58:61], v[184:187], v[208:211], v[58:61]
	v_mfma_f32_16x16x32_bf16 v[46:49], v[176:179], v[216:219], v[46:49]
	v_mfma_f32_16x16x32_bf16 v[42:45], v[184:187], v[216:219], v[42:45]
	v_mfma_f32_16x16x32_bf16 v[30:33], v[176:179], v[224:227], v[30:33]
	v_mfma_f32_16x16x32_bf16 v[26:29], v[184:187], v[224:227], v[26:29]
	v_mfma_f32_16x16x32_bf16 v[14:17], v[176:179], v[232:235], v[14:17]
	v_mfma_f32_16x16x32_bf16 v[10:13], v[184:187], v[232:235], v[10:13]
	v_mfma_f32_16x16x32_bf16 v[54:57], v[188:191], v[204:207], v[54:57]
	v_mfma_f32_16x16x32_bf16 v[50:53], v[196:199], v[204:207], v[50:53]
	v_mfma_f32_16x16x32_bf16 v[38:41], v[188:191], v[212:215], v[38:41]
	v_mfma_f32_16x16x32_bf16 v[34:37], v[196:199], v[212:215], v[34:37]
	v_mfma_f32_16x16x32_bf16 v[22:25], v[188:191], v[220:223], v[22:25]
	v_mfma_f32_16x16x32_bf16 v[18:21], v[196:199], v[220:223], v[18:21]
	v_mfma_f32_16x16x32_bf16 v[6:9], v[188:191], v[228:231], v[6:9]
	v_mfma_f32_16x16x32_bf16 v[2:5], v[196:199], v[228:231], v[2:5]
	v_mfma_f32_16x16x32_bf16 v[54:57], v[192:195], v[208:211], v[54:57]
	v_mfma_f32_16x16x32_bf16 v[50:53], v[200:203], v[208:211], v[50:53]
	v_mfma_f32_16x16x32_bf16 v[38:41], v[192:195], v[216:219], v[38:41]
	v_mfma_f32_16x16x32_bf16 v[34:37], v[200:203], v[216:219], v[34:37]
	v_mfma_f32_16x16x32_bf16 v[22:25], v[192:195], v[224:227], v[22:25]
	v_mfma_f32_16x16x32_bf16 v[18:21], v[200:203], v[224:227], v[18:21]
	v_mfma_f32_16x16x32_bf16 v[6:9], v[192:195], v[232:235], v[6:9]
	v_mfma_f32_16x16x32_bf16 v[2:5], v[200:203], v[232:235], v[2:5]
	s_barrier
; #define PG8_STAGE(bufoff, gbase, voff) do { _Pragma("unroll") for (int _i = 0; _i < 2; ++_i) \
;         __builtin_amdgcn_global_load_lds((const unsigned*)((const char*)(gbase) + (voff)[_i]), (LAS unsigned*)(lds + (bufoff) + ldsw + _i * 8192), 16, 0, 0); } while (0)
; #define PG8_LDA(dst, b, h) do { _Pragma("unroll") for (int m = 0; m < 4; ++m) _Pragma("unroll") for (int k = 0; k < 2; ++k) dst[m][k] = *(const LAS bf16x8*)(lds + PG8_SA(b, h) + aoff + m * 2048 + k * 1024); } while (0)
; #define PG8_LDB(dst, b, h) do { _Pragma("unroll") for (int n = 0; n < 2; ++n) _Pragma("unroll") for (int k = 0; k < 2; ++k) dst[n][k] = *(const LAS bf16x8*)(lds + PG8_SB(b, h) + boff + n * 2048 + k * 1024); } while (0)
; #define PG8_MMA(ai, bj, At, Bt) do { __builtin_amdgcn_s_setprio(1); _Pragma("unroll") for (int m = 0; m < 4; ++m) _Pragma("unroll") for (int n = 0; n < 2; ++n) _Pragma("unroll") for (int k = 0; k < 2; ++k) \
;         acc[ai][bj][m][n] = __builtin_amdgcn_mfma_f32_16x16x32_bf16(Bt[n][k], At[m][k], acc[ai][bj][m][n], 0, 0, 0); __builtin_amdgcn_s_setprio(0); } while (0)
; #define PG8_WAIT_V(n) asm volatile("s_waitcnt vmcnt(" #n ")" ::: "memory")
; #define PG8_WAIT_L(n) asm volatile("s_waitcnt lgkmcnt(" #n ")" ::: "memory")
; #define PG8_BAR __builtin_amdgcn_s_barrier()
; #define PG8_SCHED __builtin_amdgcn_sched_barrier(0)
; template <class Epi, class Sched, bool ABLK = false, bool ALIGN_EPI = true, bool SP2 = true, bool BBLK = true>
; __device__ __forceinline__ void gemm_phase(LAS unsigned char* lds, const Gemm g, const Sched& S, const Epi& E) {
;     ...
;         for (int t = 0; t < nt; t += 2) {
;             const bool last = (t == nt - 2);
;     ...
;             PG8_LDB(B0, 1, 0); PG8_LDB(B1, 1, 1); PG8_SCHED; PG8_LDA(At, 1, 0); PG8_STAGE(PG8_SA(0, 1), a2 + hstepA, voffA);
;             PG8_WAIT_V(8); PG8_WAIT_L(0); PG8_BAR; PG8_MMA(0, 0, At, B0); PG8_MMA(0, 1, At, B1); PG8_BAR; PG8_SCHED;
;             PG8_LDA(At, 1, 1); PG8_STAGE(PG8_SB(1, 0), b3, voffB); PG8_STAGE(PG8_SB(1, 1), b3 + hstepB, voffB); PG8_STAGE(PG8_SA(1, 0), a3, voffA);
;             PG8_WAIT_V(8); PG8_WAIT_L(0); PG8_BAR; PG8_MMA(1, 0, At, B0); PG8_MMA(1, 1, At, B1); PG8_BAR; PG8_SCHED;
	s_add_i32 s61, 0, 0x18000
	v_add_u32_e32 v171, s61, v1
	s_add_i32 s62, 0, 0x1c000
	ds_read_b128 v[172:175], v171
	ds_read_b128 v[176:179], v171 offset:1024
	ds_read_b128 v[180:183], v171 offset:2048
	ds_read_b128 v[184:187], v171 offset:3072
	v_add_u32_e32 v171, s62, v1
	ds_read_b128 v[188:191], v171
	ds_read_b128 v[192:195], v171 offset:1024
	ds_read_b128 v[196:199], v171 offset:2048
	ds_read_b128 v[200:203], v171 offset:3072
	s_add_u32 s36, s36, 0x80000
	s_addc_u32 s37, s37, 0
	s_mov_b32 m0, s46
	ds_read_b128 v[204:207], v170 offset:32768
	ds_read_b128 v[208:211], v170 offset:33792
	ds_read_b128 v[212:215], v170 offset:34816
	ds_read_b128 v[216:219], v170 offset:35840
	ds_read_b128 v[220:223], v170 offset:36864
	ds_read_b128 v[224:227], v170 offset:37888
	ds_read_b128 v[228:231], v170 offset:38912
	ds_read_b128 v[232:235], v170 offset:39936
	global_load_lds_dwordx4 v136, s[36:37]
	s_mov_b32 m0, s47
	s_nop 0
	global_load_lds_dwordx4 v132, s[36:37]
	s_waitcnt vmcnt(8) lgkmcnt(0)
	s_barrier
	v_mfma_f32_16x16x32_bf16 v[126:129], v[172:175], v[204:207], v[126:129]
	v_mfma_f32_16x16x32_bf16 v[122:125], v[180:183], v[204:207], v[122:125]
	v_mfma_f32_16x16x32_bf16 v[110:113], v[172:175], v[212:215], v[110:113]
	v_mfma_f32_16x16x32_bf16 v[106:109], v[180:183], v[212:215], v[106:109]
	v_mfma_f32_16x16x32_bf16 v[94:97], v[172:175], v[220:223], v[94:97]
	v_mfma_f32_16x16x32_bf16 v[90:93], v[180:183], v[220:223], v[90:93]
	v_mfma_f32_16x16x32_bf16 v[78:81], v[172:175], v[228:231], v[78:81]
	v_mfma_f32_16x16x32_bf16 v[74:77], v[180:183], v[228:231], v[74:77]
	v_mfma_f32_16x16x32_bf16 v[126:129], v[176:179], v[208:211], v[126:129]
	v_mfma_f32_16x16x32_bf16 v[122:125], v[184:187], v[208:211], v[122:125]
	v_mfma_f32_16x16x32_bf16 v[110:113], v[176:179], v[216:219], v[110:113]
	v_mfma_f32_16x16x32_bf16 v[106:109], v[184:187], v[216:219], v[106:109]
	v_mfma_f32_16x16x32_bf16 v[94:97], v[176:179], v[224:227], v[94:97]
	v_mfma_f32_16x16x32_bf16 v[90:93], v[184:187], v[224:227], v[90:93]
	v_mfma_f32_16x16x32_bf16 v[78:81], v[176:179], v[232:235], v[78:81]
	v_mfma_f32_16x16x32_bf16 v[74:77], v[184:187], v[232:235], v[74:77]
	v_mfma_f32_16x16x32_bf16 v[118:121], v[188:191], v[204:207], v[118:121]
	v_mfma_f32_16x16x32_bf16 v[114:117], v[196:199], v[204:207], v[114:117]
	v_mfma_f32_16x16x32_bf16 v[102:105], v[188:191], v[212:215], v[102:105]
	v_mfma_f32_16x16x32_bf16 v[98:101], v[196:199], v[212:215], v[98:101]
	v_mfma_f32_16x16x32_bf16 v[86:89], v[188:191], v[220:223], v[86:89]
	v_mfma_f32_16x16x32_bf16 v[82:85], v[196:199], v[220:223], v[82:85]
	v_mfma_f32_16x16x32_bf16 v[70:73], v[188:191], v[228:231], v[70:73]
	v_mfma_f32_16x16x32_bf16 v[66:69], v[196:199], v[228:231], v[66:69]
	v_mfma_f32_16x16x32_bf16 v[118:121], v[192:195], v[208:211], v[118:121]
	v_mfma_f32_16x16x32_bf16 v[114:117], v[200:203], v[208:211], v[114:117]
	v_mfma_f32_16x16x32_bf16 v[102:105], v[192:195], v[216:219], v[102:105]
	v_mfma_f32_16x16x32_bf16 v[98:101], v[200:203], v[216:219], v[98:101]
	v_mfma_f32_16x16x32_bf16 v[86:89], v[192:195], v[224:227], v[86:89]
	v_mfma_f32_16x16x32_bf16 v[82:85], v[200:203], v[224:227], v[82:85]
	v_mfma_f32_16x16x32_bf16 v[70:73], v[192:195], v[232:235], v[70:73]
	v_mfma_f32_16x16x32_bf16 v[66:69], v[200:203], v[232:235], v[66:69]
	s_barrier
	s_add_u32 s36, s34, 0x8000
	s_addc_u32 s37, s35, 0
	s_add_i32 s61, s61, s40
	s_mov_b32 m0, s61
	ds_read_b128 v[204:207], v170 offset:49152
	ds_read_b128 v[208:211], v170 offset:50176
	ds_read_b128 v[212:215], v170 offset:51200
	ds_read_b128 v[216:219], v170 offset:52224
	ds_read_b128 v[220:223], v170 offset:53248
	ds_read_b128 v[224:227], v170 offset:54272
	ds_read_b128 v[228:231], v170 offset:55296
	ds_read_b128 v[232:235], v170 offset:56320
	global_load_lds_dwordx4 v134, s[36:37]
	s_add_i32 m0, s61, 0x2000
	s_add_u32 s34, s34, 0xc000
	v_lshl_add_u64 v[236:237], s[36:37], 0, v[130:131]
	s_addc_u32 s35, s35, 0
	s_add_i32 s36, s62, s40
	global_load_lds_dwordx4 v[236:237], off
	s_mov_b32 m0, s36
	s_nop 0
	global_load_lds_dwordx4 v134, s[34:35]
	s_add_i32 m0, s36, 0x2000
	s_nop 0
	global_load_lds_dwordx4 v130, s[34:35]
	s_mov_b32 m0, s50
	s_nop 0
	global_load_lds_dwordx4 v136, s[30:31]
	s_mov_b32 m0, s51
	s_nop 0
	global_load_lds_dwordx4 v132, s[30:31]
	s_waitcnt vmcnt(8) lgkmcnt(0)
	s_barrier
	v_mfma_f32_16x16x32_bf16 v[62:65], v[172:175], v[204:207], v[62:65]
	v_mfma_f32_16x16x32_bf16 v[58:61], v[180:183], v[204:207], v[58:61]
	v_mfma_f32_16x16x32_bf16 v[46:49], v[172:175], v[212:215], v[46:49]
	v_mfma_f32_16x16x32_bf16 v[42:45], v[180:183], v[212:215], v[42:45]
	v_mfma_f32_16x16x32_bf16 v[30:33], v[172:175], v[220:223], v[30:33]
	v_mfma_f32_16x16x32_bf16 v[26:29], v[180:183], v[220:223], v[26:29]
	v_mfma_f32_16x16x32_bf16 v[14:17], v[172:175], v[228:231], v[14:17]
	v_mfma_f32_16x16x32_bf16 v[10:13], v[180:183], v[228:231], v[10:13]
	v_mfma_f32_16x16x32_bf16 v[62:65], v[176:179], v[208:211], v[62:65]
	v_mfma_f32_16x16x32_bf16 v[58:61], v[184:187], v[208:211], v[58:61]
	v_mfma_f32_16x16x32_bf16 v[46:49], v[176:179], v[216:219], v[46:49]
	v_mfma_f32_16x16x32_bf16 v[42:45], v[184:187], v[216:219], v[42:45]
	v_mfma_f32_16x16x32_bf16 v[30:33], v[176:179], v[224:227], v[30:33]
	v_mfma_f32_16x16x32_bf16 v[26:29], v[184:187], v[224:227], v[26:29]
	v_mfma_f32_16x16x32_bf16 v[14:17], v[176:179], v[232:235], v[14:17]
	v_mfma_f32_16x16x32_bf16 v[10:13], v[184:187], v[232:235], v[10:13]
	v_mfma_f32_16x16x32_bf16 v[54:57], v[188:191], v[204:207], v[54:57]
	v_mfma_f32_16x16x32_bf16 v[50:53], v[196:199], v[204:207], v[50:53]
	v_mfma_f32_16x16x32_bf16 v[38:41], v[188:191], v[212:215], v[38:41]
	v_mfma_f32_16x16x32_bf16 v[34:37], v[196:199], v[212:215], v[34:37]
	v_mfma_f32_16x16x32_bf16 v[22:25], v[188:191], v[220:223], v[22:25]
	v_mfma_f32_16x16x32_bf16 v[18:21], v[196:199], v[220:223], v[18:21]
	v_mfma_f32_16x16x32_bf16 v[6:9], v[188:191], v[228:231], v[6:9]
	v_mfma_f32_16x16x32_bf16 v[2:5], v[196:199], v[228:231], v[2:5]
	v_mfma_f32_16x16x32_bf16 v[54:57], v[192:195], v[208:211], v[54:57]
	v_mfma_f32_16x16x32_bf16 v[50:53], v[200:203], v[208:211], v[50:53]
	v_mfma_f32_16x16x32_bf16 v[38:41], v[192:195], v[216:219], v[38:41]
	v_mfma_f32_16x16x32_bf16 v[34:37], v[200:203], v[216:219], v[34:37]
	v_mfma_f32_16x16x32_bf16 v[22:25], v[192:195], v[224:227], v[22:25]
	v_mfma_f32_16x16x32_bf16 v[18:21], v[200:203], v[224:227], v[18:21]
	v_mfma_f32_16x16x32_bf16 v[6:9], v[192:195], v[232:235], v[6:9]
	v_mfma_f32_16x16x32_bf16 v[2:5], v[200:203], v[232:235], v[2:5]
	s_barrier
	s_add_i32 s60, s60, 2
	s_add_u32 s28, s28, 0x100
	s_addc_u32 s29, s29, 0
	s_add_u32 s58, s58, 0x10000
	s_addc_u32 s59, s59, 0
	s_cmp_gt_u32 s60, 29
	s_cbranch_scc0 .LBB0_475
	s_and_b64 vcc, exec, s[8:9]
	s_cbranch_vccz .LBB0_478
	s_barrier

; #define PG8_STAGE(bufoff, gbase, voff) do { _Pragma("unroll") for (int _i = 0; _i < 2; ++_i) \
;         __builtin_amdgcn_global_load_lds((const unsigned*)((const char*)(gbase) + (voff)[_i]), (LAS unsigned*)(lds + (bufoff) + ldsw + _i * 8192), 16, 0, 0); } while (0)
; #define PG8_LDA(dst, b, h) do { _Pragma("unroll") for (int m = 0; m < 4; ++m) _Pragma("unroll") for (int k = 0; k < 2; ++k) dst[m][k] = *(const LAS bf16x8*)(lds + PG8_SA(b, h) + aoff + m * 2048 + k * 1024); } while (0)
; #define PG8_LDB(dst, b, h) do { _Pragma("unroll") for (int n = 0; n < 2; ++n) _Pragma("unroll") for (int k = 0; k < 2; ++k) dst[n][k] = *(const LAS bf16x8*)(lds + PG8_SB(b, h) + boff + n * 2048 + k * 1024); } while (0)
; #define PG8_MMA(ai, bj, At, Bt) do { __builtin_amdgcn_s_setprio(1); _Pragma("unroll") for (int m = 0; m < 4; ++m) _Pragma("unroll") for (int n = 0; n < 2; ++n) _Pragma("unroll") for (int k = 0; k < 2; ++k) \
;         acc[ai][bj][m][n] = __builtin_amdgcn_mfma_f32_16x16x32_bf16(Bt[n][k], At[m][k], acc[ai][bj][m][n], 0, 0, 0); __builtin_amdgcn_s_setprio(0); } while (0)
; #define PG8_WAIT_V(n) asm volatile("s_waitcnt vmcnt(" #n ")" ::: "memory")
; template <class Epi, class Sched, bool ABLK = false, bool ALIGN_EPI = true, bool SP2 = true, bool BBLK = true>
; __device__ __forceinline__ void gemm_phase(LAS unsigned char* lds, const Gemm g, const Sched& S, const Epi& E) {
;     ...
;         for (int t = 0; t < nt; t += 2) {
;             const bool last = (t == nt - 2);
;             const char* a1 = a_tile(uA, tbA + t + 1);
;             const char* a2 = last ? a_tile(nuA, ntbA) : a_tile(uA, tbA + t + 2); const char* b2 = last ? nB : cB + (size_t)(t + 2) * kstepB;
;             const char* a3 = last ? a_tile(nuA, ntbA + 1) : a_tile(uA, tbA + t + 3); const char* b3 = b2 + kstepB;
;             if (last && has_next) S.a_ready(nxt);
;             if constexpr (SP2) {
;             PG8_LDB(B0, 0, 0); PG8_LDB(B1, 0, 1); PG8_SCHED; PG8_LDA(At, 0, 0); PG8_STAGE(PG8_SA(1, 1), a1 + hstepA, voffA);
;             PG8_WAIT_V(8); PG8_WAIT_L(0); PG8_BAR; PG8_MMA(0, 0, At, B0); PG8_MMA(0, 1, At, B1); PG8_BAR; PG8_SCHED;
;             PG8_LDA(At, 0, 1); PG8_STAGE(PG8_SB(0, 0), b2, voffB); PG8_STAGE(PG8_SB(0, 1), b2 + hstepB, voffB); PG8_STAGE(PG8_SA(0, 0), a2, voffA);
;             PG8_WAIT_V(8); PG8_WAIT_L(0); PG8_BAR; PG8_MMA(1, 0, At, B0); PG8_MMA(1, 1, At, B1); PG8_BAR; PG8_SCHED;
.LBB0_540:
	ds_read_b128 v[152:155], v148
	ds_read_b128 v[156:159], v148 offset:1024
	ds_read_b128 v[160:163], v148 offset:2048
	ds_read_b128 v[164:167], v148 offset:3072
	ds_read_b128 v[168:171], v149
	ds_read_b128 v[172:175], v149 offset:1024
	ds_read_b128 v[176:179], v149 offset:2048
	ds_read_b128 v[180:183], v149 offset:3072
	s_add_u32 s42, s75, s40
	s_addc_u32 s43, s76, s41
	s_add_u32 s48, s42, 0x10000
	s_addc_u32 s49, s43, 0
	s_add_i32 s79, s79, 2
	s_add_u32 s46, s66, s40
	s_addc_u32 s47, s67, s41
	s_add_u32 s42, s42, 0x18000
	s_addc_u32 s43, s43, 0
	s_cmp_eq_u32 s77, s40
	s_cselect_b32 s43, s65, s43
	s_cselect_b32 s42, s64, s42
	s_cselect_b32 s47, s4, s47
	s_cselect_b32 s46, s5, s46
	s_cselect_b32 s49, s63, s49
	s_cselect_b32 s48, s35, s48
	v_lshl_add_u64 v[216:217], v[142:143], 0, s[40:41]
	s_add_i32 m0, s52, 0xc000
	ds_read_b128 v[184:187], v150
	ds_read_b128 v[188:191], v150 offset:1024
	ds_read_b128 v[192:195], v150 offset:2048
	ds_read_b128 v[196:199], v150 offset:3072
	ds_read_b128 v[200:203], v150 offset:4096
	ds_read_b128 v[204:207], v150 offset:5120
	ds_read_b128 v[208:211], v150 offset:6144
	ds_read_b128 v[212:215], v150 offset:7168
	global_load_lds_dwordx4 v[216:217], off
	v_lshl_add_u64 v[216:217], v[144:145], 0, s[40:41]
	s_add_i32 m0, s52, 0xe000
	s_nop 0
	global_load_lds_dwordx4 v[216:217], off
	s_waitcnt vmcnt(8) lgkmcnt(0)
	s_barrier
	v_mfma_f32_16x16x32_bf16 v[126:129], v[152:155], v[184:187], v[126:129]
	v_mfma_f32_16x16x32_bf16 v[122:125], v[160:163], v[184:187], v[122:125]
	v_mfma_f32_16x16x32_bf16 v[110:113], v[152:155], v[192:195], v[110:113]
	v_mfma_f32_16x16x32_bf16 v[106:109], v[160:163], v[192:195], v[106:109]
	v_mfma_f32_16x16x32_bf16 v[94:97], v[152:155], v[200:203], v[94:97]
	v_mfma_f32_16x16x32_bf16 v[90:93], v[160:163], v[200:203], v[90:93]
	v_mfma_f32_16x16x32_bf16 v[78:81], v[152:155], v[208:211], v[78:81]
	v_mfma_f32_16x16x32_bf16 v[74:77], v[160:163], v[208:211], v[74:77]
	v_mfma_f32_16x16x32_bf16 v[126:129], v[156:159], v[188:191], v[126:129]
	v_mfma_f32_16x16x32_bf16 v[122:125], v[164:167], v[188:191], v[122:125]
	v_mfma_f32_16x16x32_bf16 v[110:113], v[156:159], v[196:199], v[110:113]
	v_mfma_f32_16x16x32_bf16 v[106:109], v[164:167], v[196:199], v[106:109]
	v_mfma_f32_16x16x32_bf16 v[94:97], v[156:159], v[204:207], v[94:97]
	v_mfma_f32_16x16x32_bf16 v[90:93], v[164:167], v[204:207], v[90:93]
	v_mfma_f32_16x16x32_bf16 v[78:81], v[156:159], v[212:215], v[78:81]
	v_mfma_f32_16x16x32_bf16 v[74:77], v[164:167], v[212:215], v[74:77]
	v_mfma_f32_16x16x32_bf16 v[118:121], v[168:171], v[184:187], v[118:121]
	v_mfma_f32_16x16x32_bf16 v[114:117], v[176:179], v[184:187], v[114:117]
	v_mfma_f32_16x16x32_bf16 v[102:105], v[168:171], v[192:195], v[102:105]
	v_mfma_f32_16x16x32_bf16 v[98:101], v[176:179], v[192:195], v[98:101]
	v_mfma_f32_16x16x32_bf16 v[86:89], v[168:171], v[200:203], v[86:89]
	v_mfma_f32_16x16x32_bf16 v[82:85], v[176:179], v[200:203], v[82:85]
	v_mfma_f32_16x16x32_bf16 v[70:73], v[168:171], v[208:211], v[70:73]
	v_mfma_f32_16x16x32_bf16 v[66:69], v[176:179], v[208:211], v[66:69]
	v_mfma_f32_16x16x32_bf16 v[118:121], v[172:175], v[188:191], v[118:121]
	v_mfma_f32_16x16x32_bf16 v[114:117], v[180:183], v[188:191], v[114:117]
	v_mfma_f32_16x16x32_bf16 v[102:105], v[172:175], v[196:199], v[102:105]
	v_mfma_f32_16x16x32_bf16 v[98:101], v[180:183], v[196:199], v[98:101]
	v_mfma_f32_16x16x32_bf16 v[86:89], v[172:175], v[204:207], v[86:89]
	v_mfma_f32_16x16x32_bf16 v[82:85], v[180:183], v[204:207], v[82:85]
	v_mfma_f32_16x16x32_bf16 v[70:73], v[172:175], v[212:215], v[70:73]
	v_mfma_f32_16x16x32_bf16 v[66:69], v[180:183], v[212:215], v[66:69]
	s_barrier
	s_add_i32 s60, s72, s51
	s_mov_b32 m0, s60
	ds_read_b128 v[184:187], v150 offset:16384
	ds_read_b128 v[188:191], v150 offset:17408
	ds_read_b128 v[192:195], v150 offset:18432
	ds_read_b128 v[196:199], v150 offset:19456
	ds_read_b128 v[200:203], v150 offset:20480
	ds_read_b128 v[204:207], v150 offset:21504
	ds_read_b128 v[208:211], v150 offset:22528
	ds_read_b128 v[212:215], v150 offset:23552
	global_load_lds_dwordx4 v130, s[46:47]
	s_add_i32 m0, s60, 0x2000
	s_add_u32 s60, s46, 0x4000
	s_addc_u32 s61, s47, 0
	s_add_i32 s81, s73, s51
	global_load_lds_dwordx4 v132, s[46:47]
	s_mov_b32 m0, s81
	s_nop 0
	global_load_lds_dwordx4 v130, s[60:61]
	s_add_i32 m0, s81, 0x2000
	s_nop 0
	global_load_lds_dwordx4 v132, s[60:61]
	s_mov_b32 m0, s52
	s_nop 0
	global_load_lds_dwordx4 v130, s[48:49]
	s_mov_b32 m0, s53
	s_nop 0
	global_load_lds_dwordx4 v132, s[48:49]
	s_waitcnt vmcnt(8) lgkmcnt(0)
	s_barrier
; #define PG8_STAGE(bufoff, gbase, voff) do { _Pragma("unroll") for (int _i = 0; _i < 2; ++_i) \
;         __builtin_amdgcn_global_load_lds((const unsigned*)((const char*)(gbase) + (voff)[_i]), (LAS unsigned*)(lds + (bufoff) + ldsw + _i * 8192), 16, 0, 0); } while (0)
; #define PG8_LDA(dst, b, h) do { _Pragma("unroll") for (int m = 0; m < 4; ++m) _Pragma("unroll") for (int k = 0; k < 2; ++k) dst[m][k] = *(const LAS bf16x8*)(lds + PG8_SA(b, h) + aoff + m * 2048 + k * 1024); } while (0)
; #define PG8_LDB(dst, b, h) do { _Pragma("unroll") for (int n = 0; n < 2; ++n) _Pragma("unroll") for (int k = 0; k < 2; ++k) dst[n][k] = *(const LAS bf16x8*)(lds + PG8_SB(b, h) + boff + n * 2048 + k * 1024); } while (0)
; #define PG8_MMA(ai, bj, At, Bt) do { __builtin_amdgcn_s_setprio(1); _Pragma("unroll") for (int m = 0; m < 4; ++m) _Pragma("unroll") for (int n = 0; n < 2; ++n) _Pragma("unroll") for (int k = 0; k < 2; ++k) \
;         acc[ai][bj][m][n] = __builtin_amdgcn_mfma_f32_16x16x32_bf16(Bt[n][k], At[m][k], acc[ai][bj][m][n], 0, 0, 0); __builtin_amdgcn_s_setprio(0); } while (0)
; #define PG8_WAIT_V(n) asm volatile("s_waitcnt vmcnt(" #n ")" ::: "memory")
; #define PG8_WAIT_L(n) asm volatile("s_waitcnt lgkmcnt(" #n ")" ::: "memory")
; #define PG8_BAR __builtin_amdgcn_s_barrier()
; #define PG8_SCHED __builtin_amdgcn_sched_barrier(0)
; template <class Epi, class Sched, bool ABLK = false, bool ALIGN_EPI = true, bool SP2 = true, bool BBLK = true>
; __device__ __forceinline__ void gemm_phase(LAS unsigned char* lds, const Gemm g, const Sched& S, const Epi& E) {
;     ...
;             PG8_LDB(B0, 1, 0); PG8_LDB(B1, 1, 1); PG8_SCHED; PG8_LDA(At, 1, 0); PG8_STAGE(PG8_SA(0, 1), a2 + hstepA, voffA);
;             PG8_WAIT_V(8); PG8_WAIT_L(0); PG8_BAR; PG8_MMA(0, 0, At, B0); PG8_MMA(0, 1, At, B1); PG8_BAR; PG8_SCHED;
	v_mfma_f32_16x16x32_bf16 v[62:65], v[152:155], v[184:187], v[62:65]
	v_mfma_f32_16x16x32_bf16 v[58:61], v[160:163], v[184:187], v[58:61]
	v_mfma_f32_16x16x32_bf16 v[46:49], v[152:155], v[192:195], v[46:49]
	v_mfma_f32_16x16x32_bf16 v[42:45], v[160:163], v[192:195], v[42:45]
	v_mfma_f32_16x16x32_bf16 v[30:33], v[152:155], v[200:203], v[30:33]
	v_mfma_f32_16x16x32_bf16 v[26:29], v[160:163], v[200:203], v[26:29]
	v_mfma_f32_16x16x32_bf16 v[14:17], v[152:155], v[208:211], v[14:17]
	v_mfma_f32_16x16x32_bf16 v[10:13], v[160:163], v[208:211], v[10:13]
	v_mfma_f32_16x16x32_bf16 v[62:65], v[156:159], v[188:191], v[62:65]
	v_mfma_f32_16x16x32_bf16 v[58:61], v[164:167], v[188:191], v[58:61]
	v_mfma_f32_16x16x32_bf16 v[46:49], v[156:159], v[196:199], v[46:49]
	v_mfma_f32_16x16x32_bf16 v[42:45], v[164:167], v[196:199], v[42:45]
	v_mfma_f32_16x16x32_bf16 v[30:33], v[156:159], v[204:207], v[30:33]
	v_mfma_f32_16x16x32_bf16 v[26:29], v[164:167], v[204:207], v[26:29]
	v_mfma_f32_16x16x32_bf16 v[14:17], v[156:159], v[212:215], v[14:17]
	v_mfma_f32_16x16x32_bf16 v[10:13], v[164:167], v[212:215], v[10:13]
	v_mfma_f32_16x16x32_bf16 v[54:57], v[168:171], v[184:187], v[54:57]
	v_mfma_f32_16x16x32_bf16 v[50:53], v[176:179], v[184:187], v[50:53]
	v_mfma_f32_16x16x32_bf16 v[38:41], v[168:171], v[192:195], v[38:41]
	v_mfma_f32_16x16x32_bf16 v[34:37], v[176:179], v[192:195], v[34:37]
	v_mfma_f32_16x16x32_bf16 v[22:25], v[168:171], v[200:203], v[22:25]
	v_mfma_f32_16x16x32_bf16 v[18:21], v[176:179], v[200:203], v[18:21]
	v_mfma_f32_16x16x32_bf16 v[6:9], v[168:171], v[208:211], v[6:9]
	v_mfma_f32_16x16x32_bf16 v[2:5], v[176:179], v[208:211], v[2:5]
	v_mfma_f32_16x16x32_bf16 v[54:57], v[172:175], v[188:191], v[54:57]
	v_mfma_f32_16x16x32_bf16 v[50:53], v[180:183], v[188:191], v[50:53]
	v_mfma_f32_16x16x32_bf16 v[38:41], v[172:175], v[196:199], v[38:41]
	v_mfma_f32_16x16x32_bf16 v[34:37], v[180:183], v[196:199], v[34:37]
	v_mfma_f32_16x16x32_bf16 v[22:25], v[172:175], v[204:207], v[22:25]
	v_mfma_f32_16x16x32_bf16 v[18:21], v[180:183], v[204:207], v[18:21]
	v_mfma_f32_16x16x32_bf16 v[6:9], v[172:175], v[212:215], v[6:9]
	v_mfma_f32_16x16x32_bf16 v[2:5], v[180:183], v[212:215], v[2:5]
	s_barrier
	s_add_i32 s60, 0, 0x18000
	v_add_u32_e32 v151, s60, v146
	s_add_i32 s61, 0, 0x1c000
	ds_read_b128 v[152:155], v151
	ds_read_b128 v[156:159], v151 offset:1024
	ds_read_b128 v[160:163], v151 offset:2048
	ds_read_b128 v[164:167], v151 offset:3072
	v_add_u32_e32 v151, s61, v146
	ds_read_b128 v[168:171], v151
	ds_read_b128 v[172:175], v151 offset:1024
	ds_read_b128 v[176:179], v151 offset:2048
	ds_read_b128 v[180:183], v151 offset:3072
	s_add_u32 s48, s48, 0x4000
	s_addc_u32 s49, s49, 0
	s_mov_b32 m0, s54
	ds_read_b128 v[184:187], v150 offset:32768
	ds_read_b128 v[188:191], v150 offset:33792
	ds_read_b128 v[192:195], v150 offset:34816
	ds_read_b128 v[196:199], v150 offset:35840
	ds_read_b128 v[200:203], v150 offset:36864
	ds_read_b128 v[204:207], v150 offset:37888
	ds_read_b128 v[208:211], v150 offset:38912
	ds_read_b128 v[212:215], v150 offset:39936
	global_load_lds_dwordx4 v130, s[48:49]
	s_mov_b32 m0, s55
	s_nop 0
	global_load_lds_dwordx4 v132, s[48:49]
	s_waitcnt vmcnt(8) lgkmcnt(0)
	s_barrier
	v_mfma_f32_16x16x32_bf16 v[126:129], v[152:155], v[184:187], v[126:129]
	v_mfma_f32_16x16x32_bf16 v[122:125], v[160:163], v[184:187], v[122:125]
	v_mfma_f32_16x16x32_bf16 v[110:113], v[152:155], v[192:195], v[110:113]
	v_mfma_f32_16x16x32_bf16 v[106:109], v[160:163], v[192:195], v[106:109]
	v_mfma_f32_16x16x32_bf16 v[94:97], v[152:155], v[200:203], v[94:97]
	v_mfma_f32_16x16x32_bf16 v[90:93], v[160:163], v[200:203], v[90:93]
	v_mfma_f32_16x16x32_bf16 v[78:81], v[152:155], v[208:211], v[78:81]
	v_mfma_f32_16x16x32_bf16 v[74:77], v[160:163], v[208:211], v[74:77]
	v_mfma_f32_16x16x32_bf16 v[126:129], v[156:159], v[188:191], v[126:129]
	v_mfma_f32_16x16x32_bf16 v[122:125], v[164:167], v[188:191], v[122:125]
	v_mfma_f32_16x16x32_bf16 v[110:113], v[156:159], v[196:199], v[110:113]
	v_mfma_f32_16x16x32_bf16 v[106:109], v[164:167], v[196:199], v[106:109]
	v_mfma_f32_16x16x32_bf16 v[94:97], v[156:159], v[204:207], v[94:97]
	v_mfma_f32_16x16x32_bf16 v[90:93], v[164:167], v[204:207], v[90:93]
	v_mfma_f32_16x16x32_bf16 v[78:81], v[156:159], v[212:215], v[78:81]
	v_mfma_f32_16x16x32_bf16 v[74:77], v[164:167], v[212:215], v[74:77]
	v_mfma_f32_16x16x32_bf16 v[118:121], v[168:171], v[184:187], v[118:121]
	v_mfma_f32_16x16x32_bf16 v[114:117], v[176:179], v[184:187], v[114:117]
	v_mfma_f32_16x16x32_bf16 v[102:105], v[168:171], v[192:195], v[102:105]
	v_mfma_f32_16x16x32_bf16 v[98:101], v[176:179], v[192:195], v[98:101]
	v_mfma_f32_16x16x32_bf16 v[86:89], v[168:171], v[200:203], v[86:89]
	v_mfma_f32_16x16x32_bf16 v[82:85], v[176:179], v[200:203], v[82:85]
	v_mfma_f32_16x16x32_bf16 v[70:73], v[168:171], v[208:211], v[70:73]
	v_mfma_f32_16x16x32_bf16 v[66:69], v[176:179], v[208:211], v[66:69]
	v_mfma_f32_16x16x32_bf16 v[118:121], v[172:175], v[188:191], v[118:121]
	v_mfma_f32_16x16x32_bf16 v[114:117], v[180:183], v[188:191], v[114:117]
	v_mfma_f32_16x16x32_bf16 v[102:105], v[172:175], v[196:199], v[102:105]
	v_mfma_f32_16x16x32_bf16 v[98:101], v[180:183], v[196:199], v[98:101]
	v_mfma_f32_16x16x32_bf16 v[86:89], v[172:175], v[204:207], v[86:89]
	v_mfma_f32_16x16x32_bf16 v[82:85], v[180:183], v[204:207], v[82:85]
	v_mfma_f32_16x16x32_bf16 v[70:73], v[172:175], v[212:215], v[70:73]
	v_mfma_f32_16x16x32_bf16 v[66:69], v[180:183], v[212:215], v[66:69]
	s_barrier
; #define PG8_STAGE(bufoff, gbase, voff) do { _Pragma("unroll") for (int _i = 0; _i < 2; ++_i) \
;         __builtin_amdgcn_global_load_lds((const unsigned*)((const char*)(gbase) + (voff)[_i]), (LAS unsigned*)(lds + (bufoff) + ldsw + _i * 8192), 16, 0, 0); } while (0)
; #define PG8_LDA(dst, b, h) do { _Pragma("unroll") for (int m = 0; m < 4; ++m) _Pragma("unroll") for (int k = 0; k < 2; ++k) dst[m][k] = *(const LAS bf16x8*)(lds + PG8_SA(b, h) + aoff + m * 2048 + k * 1024); } while (0)
; #define PG8_MMA(ai, bj, At, Bt) do { __builtin_amdgcn_s_setprio(1); _Pragma("unroll") for (int m = 0; m < 4; ++m) _Pragma("unroll") for (int n = 0; n < 2; ++n) _Pragma("unroll") for (int k = 0; k < 2; ++k) \
;         acc[ai][bj][m][n] = __builtin_amdgcn_mfma_f32_16x16x32_bf16(Bt[n][k], At[m][k], acc[ai][bj][m][n], 0, 0, 0); __builtin_amdgcn_s_setprio(0); } while (0)
; #define PG8_WAIT_V(n) asm volatile("s_waitcnt vmcnt(" #n ")" ::: "memory")
; #define PG8_WAIT_L(n) asm volatile("s_waitcnt lgkmcnt(" #n ")" ::: "memory")
; #define PG8_BAR __builtin_amdgcn_s_barrier()
; #define PG8_SCHED __builtin_amdgcn_sched_barrier(0)
; template <class Epi, class Sched, bool ABLK = false, bool ALIGN_EPI = true, bool SP2 = true, bool BBLK = true>
; __device__ __forceinline__ void gemm_phase(LAS unsigned char* lds, const Gemm g, const Sched& S, const Epi& E) {
;     ...
;         for (int t = 0; t < nt; t += 2) {
;             const bool last = (t == nt - 2);
;     ...
;             PG8_LDA(At, 1, 1); PG8_STAGE(PG8_SB(1, 0), b3, voffB); PG8_STAGE(PG8_SB(1, 1), b3 + hstepB, voffB); PG8_STAGE(PG8_SA(1, 0), a3, voffA);
;             PG8_WAIT_V(8); PG8_WAIT_L(0); PG8_BAR; PG8_MMA(1, 0, At, B0); PG8_MMA(1, 1, At, B1); PG8_BAR; PG8_SCHED;
	s_add_u32 s48, s46, 0x8000
	s_addc_u32 s49, s47, 0
	s_add_i32 s81, s60, s51
	s_mov_b32 m0, s81
	ds_read_b128 v[184:187], v150 offset:49152
	ds_read_b128 v[188:191], v150 offset:50176
	ds_read_b128 v[192:195], v150 offset:51200
	ds_read_b128 v[196:199], v150 offset:52224
	ds_read_b128 v[200:203], v150 offset:53248
	ds_read_b128 v[204:207], v150 offset:54272
	ds_read_b128 v[208:211], v150 offset:55296
	ds_read_b128 v[212:215], v150 offset:56320
	global_load_lds_dwordx4 v130, s[48:49]
	s_add_i32 m0, s81, 0x2000
	s_add_u32 s46, s46, 0xc000
	v_lshl_add_u64 v[216:217], s[48:49], 0, v[132:133]
	s_addc_u32 s47, s47, 0
	s_add_i32 s48, s61, s51
	global_load_lds_dwordx4 v[216:217], off
	s_mov_b32 m0, s48
	s_nop 0
	global_load_lds_dwordx4 v130, s[46:47]
	s_add_i32 m0, s48, 0x2000
	s_nop 0
	global_load_lds_dwordx4 v132, s[46:47]
	s_mov_b32 m0, s56
	s_nop 0
	global_load_lds_dwordx4 v130, s[42:43]
	s_mov_b32 m0, s57
	s_nop 0
	global_load_lds_dwordx4 v132, s[42:43]
	s_waitcnt vmcnt(8) lgkmcnt(0)
	s_barrier
	v_mfma_f32_16x16x32_bf16 v[62:65], v[152:155], v[184:187], v[62:65]
	v_mfma_f32_16x16x32_bf16 v[58:61], v[160:163], v[184:187], v[58:61]
	v_mfma_f32_16x16x32_bf16 v[46:49], v[152:155], v[192:195], v[46:49]
	v_mfma_f32_16x16x32_bf16 v[42:45], v[160:163], v[192:195], v[42:45]
	v_mfma_f32_16x16x32_bf16 v[30:33], v[152:155], v[200:203], v[30:33]
	v_mfma_f32_16x16x32_bf16 v[26:29], v[160:163], v[200:203], v[26:29]
	v_mfma_f32_16x16x32_bf16 v[14:17], v[152:155], v[208:211], v[14:17]
	v_mfma_f32_16x16x32_bf16 v[10:13], v[160:163], v[208:211], v[10:13]
	v_mfma_f32_16x16x32_bf16 v[62:65], v[156:159], v[188:191], v[62:65]
	v_mfma_f32_16x16x32_bf16 v[58:61], v[164:167], v[188:191], v[58:61]
	v_mfma_f32_16x16x32_bf16 v[46:49], v[156:159], v[196:199], v[46:49]
	v_mfma_f32_16x16x32_bf16 v[42:45], v[164:167], v[196:199], v[42:45]
	v_mfma_f32_16x16x32_bf16 v[30:33], v[156:159], v[204:207], v[30:33]
	v_mfma_f32_16x16x32_bf16 v[26:29], v[164:167], v[204:207], v[26:29]
	v_mfma_f32_16x16x32_bf16 v[14:17], v[156:159], v[212:215], v[14:17]
	v_mfma_f32_16x16x32_bf16 v[10:13], v[164:167], v[212:215], v[10:13]
	v_mfma_f32_16x16x32_bf16 v[54:57], v[168:171], v[184:187], v[54:57]
	v_mfma_f32_16x16x32_bf16 v[50:53], v[176:179], v[184:187], v[50:53]
	v_mfma_f32_16x16x32_bf16 v[38:41], v[168:171], v[192:195], v[38:41]
	v_mfma_f32_16x16x32_bf16 v[34:37], v[176:179], v[192:195], v[34:37]
	v_mfma_f32_16x16x32_bf16 v[22:25], v[168:171], v[200:203], v[22:25]
	v_mfma_f32_16x16x32_bf16 v[18:21], v[176:179], v[200:203], v[18:21]
	v_mfma_f32_16x16x32_bf16 v[6:9], v[168:171], v[208:211], v[6:9]
	v_mfma_f32_16x16x32_bf16 v[2:5], v[176:179], v[208:211], v[2:5]
	v_mfma_f32_16x16x32_bf16 v[54:57], v[172:175], v[188:191], v[54:57]
	v_mfma_f32_16x16x32_bf16 v[50:53], v[180:183], v[188:191], v[50:53]
	v_mfma_f32_16x16x32_bf16 v[38:41], v[172:175], v[196:199], v[38:41]
	v_mfma_f32_16x16x32_bf16 v[34:37], v[180:183], v[196:199], v[34:37]
	v_mfma_f32_16x16x32_bf16 v[22:25], v[172:175], v[204:207], v[22:25]
	v_mfma_f32_16x16x32_bf16 v[18:21], v[180:183], v[204:207], v[18:21]
	v_mfma_f32_16x16x32_bf16 v[6:9], v[172:175], v[212:215], v[6:9]
	v_mfma_f32_16x16x32_bf16 v[2:5], v[180:183], v[212:215], v[2:5]
	s_barrier
	s_add_u32 s40, s40, 0x10000
	s_addc_u32 s41, s41, 0
	s_cmp_ge_u32 s79, s59
	s_cbranch_scc0 .LBB0_540
	s_and_b64 vcc, exec, s[12:13]
	s_cbranch_vccz .LBB0_543
	s_barrier

; #define PG8_STAGE(bufoff, gbase, voff) do { _Pragma("unroll") for (int _i = 0; _i < 2; ++_i) \
;         __builtin_amdgcn_global_load_lds((const unsigned*)((const char*)(gbase) + (voff)[_i]), (LAS unsigned*)(lds + (bufoff) + ldsw + _i * 8192), 16, 0, 0); } while (0)
; #define PG8_LDA(dst, b, h) do { _Pragma("unroll") for (int m = 0; m < 4; ++m) _Pragma("unroll") for (int k = 0; k < 2; ++k) dst[m][k] = *(const LAS bf16x8*)(lds + PG8_SA(b, h) + aoff + m * 2048 + k * 1024); } while (0)
; #define PG8_LDB(dst, b, h) do { _Pragma("unroll") for (int n = 0; n < 2; ++n) _Pragma("unroll") for (int k = 0; k < 2; ++k) dst[n][k] = *(const LAS bf16x8*)(lds + PG8_SB(b, h) + boff + n * 2048 + k * 1024); } while (0)
; #define PG8_MMA(ai, bj, At, Bt) do { __builtin_amdgcn_s_setprio(1); _Pragma("unroll") for (int m = 0; m < 4; ++m) _Pragma("unroll") for (int n = 0; n < 2; ++n) _Pragma("unroll") for (int k = 0; k < 2; ++k) \
;         acc[ai][bj][m][n] = __builtin_amdgcn_mfma_f32_16x16x32_bf16(Bt[n][k], At[m][k], acc[ai][bj][m][n], 0, 0, 0); __builtin_amdgcn_s_setprio(0); } while (0)
; #define PG8_WAIT_V(n) asm volatile("s_waitcnt vmcnt(" #n ")" ::: "memory")
; template <class Epi, class Sched, bool ABLK = false, bool ALIGN_EPI = true, bool SP2 = true, bool BBLK = true>
; __device__ __forceinline__ void gemm_phase(LAS unsigned char* lds, const Gemm g, const Sched& S, const Epi& E) {
;     ...
;         for (int t = 0; t < nt; t += 2) {
;             const bool last = (t == nt - 2);
;             const char* a1 = a_tile(uA, tbA + t + 1);
;             const char* a2 = last ? a_tile(nuA, ntbA) : a_tile(uA, tbA + t + 2); const char* b2 = last ? nB : cB + (size_t)(t + 2) * kstepB;
;             const char* a3 = last ? a_tile(nuA, ntbA + 1) : a_tile(uA, tbA + t + 3); const char* b3 = b2 + kstepB;
;             if (last && has_next) S.a_ready(nxt);
;             if constexpr (SP2) {
;             PG8_LDB(B0, 0, 0); PG8_LDB(B1, 0, 1); PG8_SCHED; PG8_LDA(At, 0, 0); PG8_STAGE(PG8_SA(1, 1), a1 + hstepA, voffA);
;             PG8_WAIT_V(8); PG8_WAIT_L(0); PG8_BAR; PG8_MMA(0, 0, At, B0); PG8_MMA(0, 1, At, B1); PG8_BAR; PG8_SCHED;
;             PG8_LDA(At, 0, 1); PG8_STAGE(PG8_SB(0, 0), b2, voffB); PG8_STAGE(PG8_SB(0, 1), b2 + hstepB, voffB); PG8_STAGE(PG8_SA(0, 0), a2, voffA);
;             PG8_WAIT_V(8); PG8_WAIT_L(0); PG8_BAR; PG8_MMA(1, 0, At, B0); PG8_MMA(1, 1, At, B1); PG8_BAR; PG8_SCHED;
.LBB0_668:
	ds_read_b128 v[184:187], v153
	ds_read_b128 v[188:191], v153 offset:1024
	ds_read_b128 v[192:195], v153 offset:2048
	ds_read_b128 v[196:199], v153 offset:3072
	ds_read_b128 v[200:203], v157
	ds_read_b128 v[204:207], v157 offset:1024
	ds_read_b128 v[208:211], v157 offset:2048
	ds_read_b128 v[212:215], v157 offset:3072
	s_add_u32 s30, s26, s28
	s_addc_u32 s31, s27, s29
	s_add_u32 s36, s30, 0x100
	s_addc_u32 s37, s31, 0
	s_add_u32 s30, s30, 0x180
	s_addc_u32 s31, s31, 0
	s_cmpk_eq_i32 s28, 0xf00
	s_cselect_b32 s31, s17, s31
	s_cselect_b32 s30, s15, s30
	s_cselect_b32 s35, s5, s53
	s_cselect_b32 s34, s9, s52
	s_cselect_b32 s37, s2, s37
	s_cselect_b32 s36, s4, s36
	v_lshl_add_u64 v[248:249], v[180:181], 0, s[28:29]
	s_add_i32 m0, s25, 0xc000
	ds_read_b128 v[216:219], v149
	ds_read_b128 v[220:223], v149 offset:1024
	ds_read_b128 v[224:227], v149 offset:2048
	ds_read_b128 v[228:231], v149 offset:3072
	ds_read_b128 v[232:235], v149 offset:4096
	ds_read_b128 v[236:239], v149 offset:5120
	ds_read_b128 v[240:243], v149 offset:6144
	ds_read_b128 v[244:247], v149 offset:7168
	global_load_lds_dwordx4 v[248:249], off
	v_lshl_add_u64 v[248:249], v[182:183], 0, s[28:29]
	s_add_i32 m0, s25, 0xe000
	s_nop 0
	global_load_lds_dwordx4 v[248:249], off
	s_waitcnt vmcnt(8) lgkmcnt(0)
	s_barrier
	v_mfma_f32_16x16x32_bf16 v[126:129], v[184:187], v[216:219], v[126:129]
	v_mfma_f32_16x16x32_bf16 v[122:125], v[192:195], v[216:219], v[122:125]
	v_mfma_f32_16x16x32_bf16 v[110:113], v[184:187], v[224:227], v[110:113]
	v_mfma_f32_16x16x32_bf16 v[106:109], v[192:195], v[224:227], v[106:109]
	v_mfma_f32_16x16x32_bf16 v[94:97], v[184:187], v[232:235], v[94:97]
	v_mfma_f32_16x16x32_bf16 v[90:93], v[192:195], v[232:235], v[90:93]
	v_mfma_f32_16x16x32_bf16 v[78:81], v[184:187], v[240:243], v[78:81]
	v_mfma_f32_16x16x32_bf16 v[74:77], v[192:195], v[240:243], v[74:77]
	v_mfma_f32_16x16x32_bf16 v[126:129], v[188:191], v[220:223], v[126:129]
	v_mfma_f32_16x16x32_bf16 v[122:125], v[196:199], v[220:223], v[122:125]
	v_mfma_f32_16x16x32_bf16 v[110:113], v[188:191], v[228:231], v[110:113]
	v_mfma_f32_16x16x32_bf16 v[106:109], v[196:199], v[228:231], v[106:109]
	v_mfma_f32_16x16x32_bf16 v[94:97], v[188:191], v[236:239], v[94:97]
	v_mfma_f32_16x16x32_bf16 v[90:93], v[196:199], v[236:239], v[90:93]
	v_mfma_f32_16x16x32_bf16 v[78:81], v[188:191], v[244:247], v[78:81]
	v_mfma_f32_16x16x32_bf16 v[74:77], v[196:199], v[244:247], v[74:77]
	v_mfma_f32_16x16x32_bf16 v[118:121], v[200:203], v[216:219], v[118:121]
	v_mfma_f32_16x16x32_bf16 v[114:117], v[208:211], v[216:219], v[114:117]
	v_mfma_f32_16x16x32_bf16 v[102:105], v[200:203], v[224:227], v[102:105]
	v_mfma_f32_16x16x32_bf16 v[98:101], v[208:211], v[224:227], v[98:101]
	v_mfma_f32_16x16x32_bf16 v[86:89], v[200:203], v[232:235], v[86:89]
	v_mfma_f32_16x16x32_bf16 v[82:85], v[208:211], v[232:235], v[82:85]
	v_mfma_f32_16x16x32_bf16 v[70:73], v[200:203], v[240:243], v[70:73]
	v_mfma_f32_16x16x32_bf16 v[66:69], v[208:211], v[240:243], v[66:69]
	v_mfma_f32_16x16x32_bf16 v[118:121], v[204:207], v[220:223], v[118:121]
	v_mfma_f32_16x16x32_bf16 v[114:117], v[212:215], v[220:223], v[114:117]
	v_mfma_f32_16x16x32_bf16 v[102:105], v[204:207], v[228:231], v[102:105]
	v_mfma_f32_16x16x32_bf16 v[98:101], v[212:215], v[228:231], v[98:101]
	v_mfma_f32_16x16x32_bf16 v[86:89], v[204:207], v[236:239], v[86:89]
	v_mfma_f32_16x16x32_bf16 v[82:85], v[212:215], v[236:239], v[82:85]
	v_mfma_f32_16x16x32_bf16 v[70:73], v[204:207], v[244:247], v[70:73]
	v_mfma_f32_16x16x32_bf16 v[66:69], v[212:215], v[244:247], v[66:69]
	s_barrier
	s_add_i32 s55, s72, s41
	s_mov_b32 m0, s55
	ds_read_b128 v[216:219], v149 offset:16384
	ds_read_b128 v[220:223], v149 offset:17408
	ds_read_b128 v[224:227], v149 offset:18432
	ds_read_b128 v[228:231], v149 offset:19456
	ds_read_b128 v[232:235], v149 offset:20480
	ds_read_b128 v[236:239], v149 offset:21504
	ds_read_b128 v[240:243], v149 offset:22528
	ds_read_b128 v[244:247], v149 offset:23552
	global_load_lds_dwordx4 v132, s[34:35]
	s_add_i32 m0, s55, 0x2000
	s_add_u32 s56, s34, 0x4000
	s_addc_u32 s57, s35, 0
	s_add_i32 s55, s73, s41
	global_load_lds_dwordx4 v136, s[34:35]
	s_mov_b32 m0, s55
	s_nop 0
	global_load_lds_dwordx4 v132, s[56:57]
	s_add_i32 m0, s55, 0x2000
	s_nop 0
	global_load_lds_dwordx4 v136, s[56:57]
	s_mov_b32 m0, s25
	s_nop 0
	global_load_lds_dwordx4 v130, s[36:37]
	s_mov_b32 m0, s42
	s_nop 0
	global_load_lds_dwordx4 v134, s[36:37]
	s_waitcnt vmcnt(8) lgkmcnt(0)
	s_barrier
	v_mfma_f32_16x16x32_bf16 v[62:65], v[184:187], v[216:219], v[62:65]
	v_mfma_f32_16x16x32_bf16 v[58:61], v[192:195], v[216:219], v[58:61]
	v_mfma_f32_16x16x32_bf16 v[46:49], v[184:187], v[224:227], v[46:49]
	v_mfma_f32_16x16x32_bf16 v[42:45], v[192:195], v[224:227], v[42:45]
	v_mfma_f32_16x16x32_bf16 v[30:33], v[184:187], v[232:235], v[30:33]
	v_mfma_f32_16x16x32_bf16 v[26:29], v[192:195], v[232:235], v[26:29]
	v_mfma_f32_16x16x32_bf16 v[14:17], v[184:187], v[240:243], v[14:17]
	v_mfma_f32_16x16x32_bf16 v[10:13], v[192:195], v[240:243], v[10:13]
	v_mfma_f32_16x16x32_bf16 v[62:65], v[188:191], v[220:223], v[62:65]
	v_mfma_f32_16x16x32_bf16 v[58:61], v[196:199], v[220:223], v[58:61]
	v_mfma_f32_16x16x32_bf16 v[46:49], v[188:191], v[228:231], v[46:49]
	v_mfma_f32_16x16x32_bf16 v[42:45], v[196:199], v[228:231], v[42:45]
	v_mfma_f32_16x16x32_bf16 v[30:33], v[188:191], v[236:239], v[30:33]
	v_mfma_f32_16x16x32_bf16 v[26:29], v[196:199], v[236:239], v[26:29]
	v_mfma_f32_16x16x32_bf16 v[14:17], v[188:191], v[244:247], v[14:17]
	v_mfma_f32_16x16x32_bf16 v[10:13], v[196:199], v[244:247], v[10:13]
	v_mfma_f32_16x16x32_bf16 v[54:57], v[200:203], v[216:219], v[54:57]
	v_mfma_f32_16x16x32_bf16 v[50:53], v[208:211], v[216:219], v[50:53]
	v_mfma_f32_16x16x32_bf16 v[38:41], v[200:203], v[224:227], v[38:41]
	v_mfma_f32_16x16x32_bf16 v[34:37], v[208:211], v[224:227], v[34:37]
	v_mfma_f32_16x16x32_bf16 v[22:25], v[200:203], v[232:235], v[22:25]
	v_mfma_f32_16x16x32_bf16 v[18:21], v[208:211], v[232:235], v[18:21]
	v_mfma_f32_16x16x32_bf16 v[6:9], v[200:203], v[240:243], v[6:9]
	v_mfma_f32_16x16x32_bf16 v[2:5], v[208:211], v[240:243], v[2:5]
	v_mfma_f32_16x16x32_bf16 v[54:57], v[204:207], v[220:223], v[54:57]
	v_mfma_f32_16x16x32_bf16 v[50:53], v[212:215], v[220:223], v[50:53]
	v_mfma_f32_16x16x32_bf16 v[38:41], v[204:207], v[228:231], v[38:41]
	v_mfma_f32_16x16x32_bf16 v[34:37], v[212:215], v[228:231], v[34:37]
	v_mfma_f32_16x16x32_bf16 v[22:25], v[204:207], v[236:239], v[22:25]
	v_mfma_f32_16x16x32_bf16 v[18:21], v[212:215], v[236:239], v[18:21]
	v_mfma_f32_16x16x32_bf16 v[6:9], v[204:207], v[244:247], v[6:9]
	v_mfma_f32_16x16x32_bf16 v[2:5], v[212:215], v[244:247], v[2:5]
	s_barrier
; #define PG8_STAGE(bufoff, gbase, voff) do { _Pragma("unroll") for (int _i = 0; _i < 2; ++_i) \
;         __builtin_amdgcn_global_load_lds((const unsigned*)((const char*)(gbase) + (voff)[_i]), (LAS unsigned*)(lds + (bufoff) + ldsw + _i * 8192), 16, 0, 0); } while (0)
; #define PG8_LDA(dst, b, h) do { _Pragma("unroll") for (int m = 0; m < 4; ++m) _Pragma("unroll") for (int k = 0; k < 2; ++k) dst[m][k] = *(const LAS bf16x8*)(lds + PG8_SA(b, h) + aoff + m * 2048 + k * 1024); } while (0)
; #define PG8_LDB(dst, b, h) do { _Pragma("unroll") for (int n = 0; n < 2; ++n) _Pragma("unroll") for (int k = 0; k < 2; ++k) dst[n][k] = *(const LAS bf16x8*)(lds + PG8_SB(b, h) + boff + n * 2048 + k * 1024); } while (0)
; #define PG8_MMA(ai, bj, At, Bt) do { __builtin_amdgcn_s_setprio(1); _Pragma("unroll") for (int m = 0; m < 4; ++m) _Pragma("unroll") for (int n = 0; n < 2; ++n) _Pragma("unroll") for (int k = 0; k < 2; ++k) \
;         acc[ai][bj][m][n] = __builtin_amdgcn_mfma_f32_16x16x32_bf16(Bt[n][k], At[m][k], acc[ai][bj][m][n], 0, 0, 0); __builtin_amdgcn_s_setprio(0); } while (0)
; #define PG8_WAIT_V(n) asm volatile("s_waitcnt vmcnt(" #n ")" ::: "memory")
; #define PG8_WAIT_L(n) asm volatile("s_waitcnt lgkmcnt(" #n ")" ::: "memory")
; #define PG8_BAR __builtin_amdgcn_s_barrier()
; #define PG8_SCHED __builtin_amdgcn_sched_barrier(0)
; template <class Epi, class Sched, bool ABLK = false, bool ALIGN_EPI = true, bool SP2 = true, bool BBLK = true>
; __device__ __forceinline__ void gemm_phase(LAS unsigned char* lds, const Gemm g, const Sched& S, const Epi& E) {
;     ...
;         for (int t = 0; t < nt; t += 2) {
;             const bool last = (t == nt - 2);
;     ...
;             PG8_LDB(B0, 1, 0); PG8_LDB(B1, 1, 1); PG8_SCHED; PG8_LDA(At, 1, 0); PG8_STAGE(PG8_SA(0, 1), a2 + hstepA, voffA);
;             PG8_WAIT_V(8); PG8_WAIT_L(0); PG8_BAR; PG8_MMA(0, 0, At, B0); PG8_MMA(0, 1, At, B1); PG8_BAR; PG8_SCHED;
;             PG8_LDA(At, 1, 1); PG8_STAGE(PG8_SB(1, 0), b3, voffB); PG8_STAGE(PG8_SB(1, 1), b3 + hstepB, voffB); PG8_STAGE(PG8_SA(1, 0), a3, voffA);
;             PG8_WAIT_V(8); PG8_WAIT_L(0); PG8_BAR; PG8_MMA(1, 0, At, B0); PG8_MMA(1, 1, At, B1); PG8_BAR; PG8_SCHED;
	v_add_u32_e32 v138, s60, v1
	ds_read_b128 v[184:187], v138
	ds_read_b128 v[188:191], v138 offset:1024
	ds_read_b128 v[192:195], v138 offset:2048
	ds_read_b128 v[196:199], v138 offset:3072
	v_add_u32_e32 v138, s61, v1
	ds_read_b128 v[200:203], v138
	ds_read_b128 v[204:207], v138 offset:1024
	ds_read_b128 v[208:211], v138 offset:2048
	ds_read_b128 v[212:215], v138 offset:3072
	s_add_u32 s36, s36, 0x80000
	s_addc_u32 s37, s37, 0
	s_mov_b32 m0, s43
	ds_read_b128 v[216:219], v149 offset:32768
	ds_read_b128 v[220:223], v149 offset:33792
	ds_read_b128 v[224:227], v149 offset:34816
	ds_read_b128 v[228:231], v149 offset:35840
	ds_read_b128 v[232:235], v149 offset:36864
	ds_read_b128 v[236:239], v149 offset:37888
	ds_read_b128 v[240:243], v149 offset:38912
	ds_read_b128 v[244:247], v149 offset:39936
	global_load_lds_dwordx4 v130, s[36:37]
	s_mov_b32 m0, s46
	s_nop 0
	global_load_lds_dwordx4 v134, s[36:37]
	s_waitcnt vmcnt(8) lgkmcnt(0)
	s_barrier
	v_mfma_f32_16x16x32_bf16 v[126:129], v[184:187], v[216:219], v[126:129]
	v_mfma_f32_16x16x32_bf16 v[122:125], v[192:195], v[216:219], v[122:125]
	v_mfma_f32_16x16x32_bf16 v[110:113], v[184:187], v[224:227], v[110:113]
	v_mfma_f32_16x16x32_bf16 v[106:109], v[192:195], v[224:227], v[106:109]
	v_mfma_f32_16x16x32_bf16 v[94:97], v[184:187], v[232:235], v[94:97]
	v_mfma_f32_16x16x32_bf16 v[90:93], v[192:195], v[232:235], v[90:93]
	v_mfma_f32_16x16x32_bf16 v[78:81], v[184:187], v[240:243], v[78:81]
	v_mfma_f32_16x16x32_bf16 v[74:77], v[192:195], v[240:243], v[74:77]
	v_mfma_f32_16x16x32_bf16 v[126:129], v[188:191], v[220:223], v[126:129]
	v_mfma_f32_16x16x32_bf16 v[122:125], v[196:199], v[220:223], v[122:125]
	v_mfma_f32_16x16x32_bf16 v[110:113], v[188:191], v[228:231], v[110:113]
	v_mfma_f32_16x16x32_bf16 v[106:109], v[196:199], v[228:231], v[106:109]
	v_mfma_f32_16x16x32_bf16 v[94:97], v[188:191], v[236:239], v[94:97]
	v_mfma_f32_16x16x32_bf16 v[90:93], v[196:199], v[236:239], v[90:93]
	v_mfma_f32_16x16x32_bf16 v[78:81], v[188:191], v[244:247], v[78:81]
	v_mfma_f32_16x16x32_bf16 v[74:77], v[196:199], v[244:247], v[74:77]
	v_mfma_f32_16x16x32_bf16 v[118:121], v[200:203], v[216:219], v[118:121]
	v_mfma_f32_16x16x32_bf16 v[114:117], v[208:211], v[216:219], v[114:117]
	v_mfma_f32_16x16x32_bf16 v[102:105], v[200:203], v[224:227], v[102:105]
	v_mfma_f32_16x16x32_bf16 v[98:101], v[208:211], v[224:227], v[98:101]
	v_mfma_f32_16x16x32_bf16 v[86:89], v[200:203], v[232:235], v[86:89]
	v_mfma_f32_16x16x32_bf16 v[82:85], v[208:211], v[232:235], v[82:85]
	v_mfma_f32_16x16x32_bf16 v[70:73], v[200:203], v[240:243], v[70:73]
	v_mfma_f32_16x16x32_bf16 v[66:69], v[208:211], v[240:243], v[66:69]
	v_mfma_f32_16x16x32_bf16 v[118:121], v[204:207], v[220:223], v[118:121]
	v_mfma_f32_16x16x32_bf16 v[114:117], v[212:215], v[220:223], v[114:117]
	v_mfma_f32_16x16x32_bf16 v[102:105], v[204:207], v[228:231], v[102:105]
	v_mfma_f32_16x16x32_bf16 v[98:101], v[212:215], v[228:231], v[98:101]
	v_mfma_f32_16x16x32_bf16 v[86:89], v[204:207], v[236:239], v[86:89]
	v_mfma_f32_16x16x32_bf16 v[82:85], v[212:215], v[236:239], v[82:85]
	v_mfma_f32_16x16x32_bf16 v[70:73], v[204:207], v[244:247], v[70:73]
	v_mfma_f32_16x16x32_bf16 v[66:69], v[212:215], v[244:247], v[66:69]
	s_barrier
	s_add_u32 s36, s34, 0x8000
	s_addc_u32 s37, s35, 0
	s_add_i32 s55, s60, s41
	s_mov_b32 m0, s55
	ds_read_b128 v[216:219], v149 offset:49152
	ds_read_b128 v[220:223], v149 offset:50176
	ds_read_b128 v[224:227], v149 offset:51200
	ds_read_b128 v[228:231], v149 offset:52224
	ds_read_b128 v[232:235], v149 offset:53248
	ds_read_b128 v[236:239], v149 offset:54272
	ds_read_b128 v[240:243], v149 offset:55296
	ds_read_b128 v[244:247], v149 offset:56320
	global_load_lds_dwordx4 v132, s[36:37]
	s_add_i32 m0, s55, 0x2000
	s_add_u32 s34, s34, 0xc000
	v_lshl_add_u64 v[248:249], s[36:37], 0, v[136:137]
	s_addc_u32 s35, s35, 0
	s_add_i32 s36, s61, s41
	global_load_lds_dwordx4 v[248:249], off
	s_mov_b32 m0, s36
	s_nop 0
	global_load_lds_dwordx4 v132, s[34:35]
	s_add_i32 m0, s36, 0x2000
	s_nop 0
	global_load_lds_dwordx4 v136, s[34:35]
	s_mov_b32 m0, s47
	s_nop 0
	global_load_lds_dwordx4 v130, s[30:31]
	s_mov_b32 m0, s48
	s_nop 0
	global_load_lds_dwordx4 v134, s[30:31]
	s_waitcnt vmcnt(8) lgkmcnt(0)
	s_barrier
	v_mfma_f32_16x16x32_bf16 v[62:65], v[184:187], v[216:219], v[62:65]
	v_mfma_f32_16x16x32_bf16 v[58:61], v[192:195], v[216:219], v[58:61]
	v_mfma_f32_16x16x32_bf16 v[46:49], v[184:187], v[224:227], v[46:49]
	v_mfma_f32_16x16x32_bf16 v[42:45], v[192:195], v[224:227], v[42:45]
	v_mfma_f32_16x16x32_bf16 v[30:33], v[184:187], v[232:235], v[30:33]
	v_mfma_f32_16x16x32_bf16 v[26:29], v[192:195], v[232:235], v[26:29]
	v_mfma_f32_16x16x32_bf16 v[14:17], v[184:187], v[240:243], v[14:17]
	v_mfma_f32_16x16x32_bf16 v[10:13], v[192:195], v[240:243], v[10:13]
	v_mfma_f32_16x16x32_bf16 v[62:65], v[188:191], v[220:223], v[62:65]
	v_mfma_f32_16x16x32_bf16 v[58:61], v[196:199], v[220:223], v[58:61]
	v_mfma_f32_16x16x32_bf16 v[46:49], v[188:191], v[228:231], v[46:49]
	v_mfma_f32_16x16x32_bf16 v[42:45], v[196:199], v[228:231], v[42:45]
	v_mfma_f32_16x16x32_bf16 v[30:33], v[188:191], v[236:239], v[30:33]
	v_mfma_f32_16x16x32_bf16 v[26:29], v[196:199], v[236:239], v[26:29]
	v_mfma_f32_16x16x32_bf16 v[14:17], v[188:191], v[244:247], v[14:17]
	v_mfma_f32_16x16x32_bf16 v[10:13], v[196:199], v[244:247], v[10:13]
	v_mfma_f32_16x16x32_bf16 v[54:57], v[200:203], v[216:219], v[54:57]
	v_mfma_f32_16x16x32_bf16 v[50:53], v[208:211], v[216:219], v[50:53]
	v_mfma_f32_16x16x32_bf16 v[38:41], v[200:203], v[224:227], v[38:41]
	v_mfma_f32_16x16x32_bf16 v[34:37], v[208:211], v[224:227], v[34:37]
	v_mfma_f32_16x16x32_bf16 v[22:25], v[200:203], v[232:235], v[22:25]
	v_mfma_f32_16x16x32_bf16 v[18:21], v[208:211], v[232:235], v[18:21]
	v_mfma_f32_16x16x32_bf16 v[6:9], v[200:203], v[240:243], v[6:9]
	v_mfma_f32_16x16x32_bf16 v[2:5], v[208:211], v[240:243], v[2:5]
	v_mfma_f32_16x16x32_bf16 v[54:57], v[204:207], v[220:223], v[54:57]
	v_mfma_f32_16x16x32_bf16 v[50:53], v[212:215], v[220:223], v[50:53]
	v_mfma_f32_16x16x32_bf16 v[38:41], v[204:207], v[228:231], v[38:41]
	v_mfma_f32_16x16x32_bf16 v[34:37], v[212:215], v[228:231], v[34:37]
	v_mfma_f32_16x16x32_bf16 v[22:25], v[204:207], v[236:239], v[22:25]
	v_mfma_f32_16x16x32_bf16 v[18:21], v[212:215], v[236:239], v[18:21]
	v_mfma_f32_16x16x32_bf16 v[6:9], v[204:207], v[244:247], v[6:9]
	v_mfma_f32_16x16x32_bf16 v[2:5], v[212:215], v[244:247], v[2:5]
	s_barrier
	s_add_i32 s54, s54, 2
	s_add_u32 s28, s28, 0x100
	s_addc_u32 s29, s29, 0
	s_add_u32 s52, s52, 0x10000
	s_addc_u32 s53, s53, 0
	s_cmp_gt_u32 s54, 29
	s_cbranch_scc0 .LBB0_668
	s_and_b64 vcc, exec, s[12:13]
	s_cbranch_vccz .LBB0_671
	s_barrier

; #define PG8_STAGE(bufoff, gbase, voff) do { _Pragma("unroll") for (int _i = 0; _i < 2; ++_i) \
;         __builtin_amdgcn_global_load_lds((const unsigned*)((const char*)(gbase) + (voff)[_i]), (LAS unsigned*)(lds + (bufoff) + ldsw + _i * 8192), 16, 0, 0); } while (0)
; #define PG8_LDA(dst, b, h) do { _Pragma("unroll") for (int m = 0; m < 4; ++m) _Pragma("unroll") for (int k = 0; k < 2; ++k) dst[m][k] = *(const LAS bf16x8*)(lds + PG8_SA(b, h) + aoff + m * 2048 + k * 1024); } while (0)
; #define PG8_LDB(dst, b, h) do { _Pragma("unroll") for (int n = 0; n < 2; ++n) _Pragma("unroll") for (int k = 0; k < 2; ++k) dst[n][k] = *(const LAS bf16x8*)(lds + PG8_SB(b, h) + boff + n * 2048 + k * 1024); } while (0)
; #define PG8_MMA(ai, bj, At, Bt) do { __builtin_amdgcn_s_setprio(1); _Pragma("unroll") for (int m = 0; m < 4; ++m) _Pragma("unroll") for (int n = 0; n < 2; ++n) _Pragma("unroll") for (int k = 0; k < 2; ++k) \
;         acc[ai][bj][m][n] = __builtin_amdgcn_mfma_f32_16x16x32_bf16(Bt[n][k], At[m][k], acc[ai][bj][m][n], 0, 0, 0); __builtin_amdgcn_s_setprio(0); } while (0)
; #define PG8_WAIT_V(n) asm volatile("s_waitcnt vmcnt(" #n ")" ::: "memory")
; template <class Epi, class Sched, bool ABLK = false, bool ALIGN_EPI = true, bool SP2 = true, bool BBLK = true>
; __device__ __forceinline__ void gemm_phase(LAS unsigned char* lds, const Gemm g, const Sched& S, const Epi& E) {
;     ...
;         for (int t = 0; t < nt; t += 2) {
;             const bool last = (t == nt - 2);
;             const char* a1 = a_tile(uA, tbA + t + 1);
;             const char* a2 = last ? a_tile(nuA, ntbA) : a_tile(uA, tbA + t + 2); const char* b2 = last ? nB : cB + (size_t)(t + 2) * kstepB;
;             const char* a3 = last ? a_tile(nuA, ntbA + 1) : a_tile(uA, tbA + t + 3); const char* b3 = b2 + kstepB;
;             if (last && has_next) S.a_ready(nxt);
;             if constexpr (SP2) {
;             PG8_LDB(B0, 0, 0); PG8_LDB(B1, 0, 1); PG8_SCHED; PG8_LDA(At, 0, 0); PG8_STAGE(PG8_SA(1, 1), a1 + hstepA, voffA);
;             PG8_WAIT_V(8); PG8_WAIT_L(0); PG8_BAR; PG8_MMA(0, 0, At, B0); PG8_MMA(0, 1, At, B1); PG8_BAR; PG8_SCHED;
;             PG8_LDA(At, 0, 1); PG8_STAGE(PG8_SB(0, 0), b2, voffB); PG8_STAGE(PG8_SB(0, 1), b2 + hstepB, voffB); PG8_STAGE(PG8_SA(0, 0), a2, voffA);
;             PG8_WAIT_V(8); PG8_WAIT_L(0); PG8_BAR; PG8_MMA(1, 0, At, B0); PG8_MMA(1, 1, At, B1); PG8_BAR; PG8_SCHED;
.LBB0_1038:
	ds_read_b128 v[156:159], v153
	ds_read_b128 v[160:163], v153 offset:1024
	ds_read_b128 v[164:167], v153 offset:2048
	ds_read_b128 v[168:171], v153 offset:3072
	ds_read_b128 v[172:175], v154
	ds_read_b128 v[176:179], v154 offset:1024
	ds_read_b128 v[180:183], v154 offset:2048
	ds_read_b128 v[184:187], v154 offset:3072
	s_add_u32 s22, s56, s20
	s_addc_u32 s23, s57, s21
	s_add_u32 s26, s22, 0x100
	s_addc_u32 s27, s23, 0
	s_add_i32 s65, s65, 2
	s_add_u32 s22, s22, 0x180
	s_addc_u32 s23, s23, 0
	s_cmp_eq_u32 s64, s20
	s_cselect_b32 s23, s50, s23
	s_cselect_b32 s22, s49, s22
	s_cselect_b32 s25, s4, s55
	s_cselect_b32 s24, s5, s51
	s_cselect_b32 s27, s48, s27
	s_cselect_b32 s26, s17, s26
	v_lshl_add_u64 v[220:221], v[146:147], 0, s[20:21]
	s_add_i32 m0, s35, 0xc000
	ds_read_b128 v[188:191], v155
	ds_read_b128 v[192:195], v155 offset:1024
	ds_read_b128 v[196:199], v155 offset:2048
	ds_read_b128 v[200:203], v155 offset:3072
	ds_read_b128 v[204:207], v155 offset:4096
	ds_read_b128 v[208:211], v155 offset:5120
	ds_read_b128 v[212:215], v155 offset:6144
	ds_read_b128 v[216:219], v155 offset:7168
	global_load_lds_dwordx4 v[220:221], off
	v_lshl_add_u64 v[220:221], v[148:149], 0, s[20:21]
	s_add_i32 m0, s35, 0xe000
	s_nop 0
	global_load_lds_dwordx4 v[220:221], off
	s_waitcnt vmcnt(8) lgkmcnt(0)
	s_barrier
	v_mfma_f32_16x16x32_bf16 v[126:129], v[156:159], v[188:191], v[126:129]
	v_mfma_f32_16x16x32_bf16 v[122:125], v[164:167], v[188:191], v[122:125]
	v_mfma_f32_16x16x32_bf16 v[110:113], v[156:159], v[196:199], v[110:113]
	v_mfma_f32_16x16x32_bf16 v[106:109], v[164:167], v[196:199], v[106:109]
	v_mfma_f32_16x16x32_bf16 v[94:97], v[156:159], v[204:207], v[94:97]
	v_mfma_f32_16x16x32_bf16 v[90:93], v[164:167], v[204:207], v[90:93]
	v_mfma_f32_16x16x32_bf16 v[78:81], v[156:159], v[212:215], v[78:81]
	v_mfma_f32_16x16x32_bf16 v[74:77], v[164:167], v[212:215], v[74:77]
	v_mfma_f32_16x16x32_bf16 v[126:129], v[160:163], v[192:195], v[126:129]
	v_mfma_f32_16x16x32_bf16 v[122:125], v[168:171], v[192:195], v[122:125]
	v_mfma_f32_16x16x32_bf16 v[110:113], v[160:163], v[200:203], v[110:113]
	v_mfma_f32_16x16x32_bf16 v[106:109], v[168:171], v[200:203], v[106:109]
	v_mfma_f32_16x16x32_bf16 v[94:97], v[160:163], v[208:211], v[94:97]
	v_mfma_f32_16x16x32_bf16 v[90:93], v[168:171], v[208:211], v[90:93]
	v_mfma_f32_16x16x32_bf16 v[78:81], v[160:163], v[216:219], v[78:81]
	v_mfma_f32_16x16x32_bf16 v[74:77], v[168:171], v[216:219], v[74:77]
	v_mfma_f32_16x16x32_bf16 v[118:121], v[172:175], v[188:191], v[118:121]
	v_mfma_f32_16x16x32_bf16 v[114:117], v[180:183], v[188:191], v[114:117]
	v_mfma_f32_16x16x32_bf16 v[102:105], v[172:175], v[196:199], v[102:105]
	v_mfma_f32_16x16x32_bf16 v[98:101], v[180:183], v[196:199], v[98:101]
	v_mfma_f32_16x16x32_bf16 v[86:89], v[172:175], v[204:207], v[86:89]
	v_mfma_f32_16x16x32_bf16 v[82:85], v[180:183], v[204:207], v[82:85]
	v_mfma_f32_16x16x32_bf16 v[70:73], v[172:175], v[212:215], v[70:73]
	v_mfma_f32_16x16x32_bf16 v[66:69], v[180:183], v[212:215], v[66:69]
	v_mfma_f32_16x16x32_bf16 v[118:121], v[176:179], v[192:195], v[118:121]
	v_mfma_f32_16x16x32_bf16 v[114:117], v[184:187], v[192:195], v[114:117]
	v_mfma_f32_16x16x32_bf16 v[102:105], v[176:179], v[200:203], v[102:105]
	v_mfma_f32_16x16x32_bf16 v[98:101], v[184:187], v[200:203], v[98:101]
	v_mfma_f32_16x16x32_bf16 v[86:89], v[176:179], v[208:211], v[86:89]
	v_mfma_f32_16x16x32_bf16 v[82:85], v[184:187], v[208:211], v[82:85]
	v_mfma_f32_16x16x32_bf16 v[70:73], v[176:179], v[216:219], v[70:73]
	v_mfma_f32_16x16x32_bf16 v[66:69], v[184:187], v[216:219], v[66:69]
	s_barrier
	s_add_i32 s66, s72, s34
	s_mov_b32 m0, s66
	ds_read_b128 v[188:191], v155 offset:16384
	ds_read_b128 v[192:195], v155 offset:17408
	ds_read_b128 v[196:199], v155 offset:18432
	ds_read_b128 v[200:203], v155 offset:19456
	ds_read_b128 v[204:207], v155 offset:20480
	ds_read_b128 v[208:211], v155 offset:21504
	ds_read_b128 v[212:215], v155 offset:22528
	ds_read_b128 v[216:219], v155 offset:23552
	global_load_lds_dwordx4 v132, s[24:25]
	s_add_i32 m0, s66, 0x2000
	s_add_u32 s66, s24, 0x4000
	s_addc_u32 s67, s25, 0
	s_add_i32 s75, s73, s34
	global_load_lds_dwordx4 v136, s[24:25]
	s_mov_b32 m0, s75
	s_nop 0
	global_load_lds_dwordx4 v132, s[66:67]
	s_add_i32 m0, s75, 0x2000
	s_nop 0
	global_load_lds_dwordx4 v136, s[66:67]
	s_mov_b32 m0, s35
	s_nop 0
	global_load_lds_dwordx4 v130, s[26:27]
	s_mov_b32 m0, s36
	s_nop 0
	global_load_lds_dwordx4 v134, s[26:27]
	s_waitcnt vmcnt(8) lgkmcnt(0)
	s_barrier
	v_mfma_f32_16x16x32_bf16 v[62:65], v[156:159], v[188:191], v[62:65]
	v_mfma_f32_16x16x32_bf16 v[58:61], v[164:167], v[188:191], v[58:61]
	v_mfma_f32_16x16x32_bf16 v[46:49], v[156:159], v[196:199], v[46:49]
	v_mfma_f32_16x16x32_bf16 v[42:45], v[164:167], v[196:199], v[42:45]
	v_mfma_f32_16x16x32_bf16 v[30:33], v[156:159], v[204:207], v[30:33]
	v_mfma_f32_16x16x32_bf16 v[26:29], v[164:167], v[204:207], v[26:29]
	v_mfma_f32_16x16x32_bf16 v[14:17], v[156:159], v[212:215], v[14:17]
	v_mfma_f32_16x16x32_bf16 v[10:13], v[164:167], v[212:215], v[10:13]
	v_mfma_f32_16x16x32_bf16 v[62:65], v[160:163], v[192:195], v[62:65]
	v_mfma_f32_16x16x32_bf16 v[58:61], v[168:171], v[192:195], v[58:61]
	v_mfma_f32_16x16x32_bf16 v[46:49], v[160:163], v[200:203], v[46:49]
	v_mfma_f32_16x16x32_bf16 v[42:45], v[168:171], v[200:203], v[42:45]
	v_mfma_f32_16x16x32_bf16 v[30:33], v[160:163], v[208:211], v[30:33]
	v_mfma_f32_16x16x32_bf16 v[26:29], v[168:171], v[208:211], v[26:29]
	v_mfma_f32_16x16x32_bf16 v[14:17], v[160:163], v[216:219], v[14:17]
	v_mfma_f32_16x16x32_bf16 v[10:13], v[168:171], v[216:219], v[10:13]
	v_mfma_f32_16x16x32_bf16 v[54:57], v[172:175], v[188:191], v[54:57]
	v_mfma_f32_16x16x32_bf16 v[50:53], v[180:183], v[188:191], v[50:53]
	v_mfma_f32_16x16x32_bf16 v[38:41], v[172:175], v[196:199], v[38:41]
	v_mfma_f32_16x16x32_bf16 v[34:37], v[180:183], v[196:199], v[34:37]
	v_mfma_f32_16x16x32_bf16 v[22:25], v[172:175], v[204:207], v[22:25]
	v_mfma_f32_16x16x32_bf16 v[18:21], v[180:183], v[204:207], v[18:21]
	v_mfma_f32_16x16x32_bf16 v[6:9], v[172:175], v[212:215], v[6:9]
	v_mfma_f32_16x16x32_bf16 v[2:5], v[180:183], v[212:215], v[2:5]
	v_mfma_f32_16x16x32_bf16 v[54:57], v[176:179], v[192:195], v[54:57]
	v_mfma_f32_16x16x32_bf16 v[50:53], v[184:187], v[192:195], v[50:53]
	v_mfma_f32_16x16x32_bf16 v[38:41], v[176:179], v[200:203], v[38:41]
	v_mfma_f32_16x16x32_bf16 v[34:37], v[184:187], v[200:203], v[34:37]
	v_mfma_f32_16x16x32_bf16 v[22:25], v[176:179], v[208:211], v[22:25]
	v_mfma_f32_16x16x32_bf16 v[18:21], v[184:187], v[208:211], v[18:21]
	v_mfma_f32_16x16x32_bf16 v[6:9], v[176:179], v[216:219], v[6:9]
	v_mfma_f32_16x16x32_bf16 v[2:5], v[184:187], v[216:219], v[2:5]
	s_barrier
; #define PG8_STAGE(bufoff, gbase, voff) do { _Pragma("unroll") for (int _i = 0; _i < 2; ++_i) \
;         __builtin_amdgcn_global_load_lds((const unsigned*)((const char*)(gbase) + (voff)[_i]), (LAS unsigned*)(lds + (bufoff) + ldsw + _i * 8192), 16, 0, 0); } while (0)
; #define PG8_LDA(dst, b, h) do { _Pragma("unroll") for (int m = 0; m < 4; ++m) _Pragma("unroll") for (int k = 0; k < 2; ++k) dst[m][k] = *(const LAS bf16x8*)(lds + PG8_SA(b, h) + aoff + m * 2048 + k * 1024); } while (0)
; #define PG8_LDB(dst, b, h) do { _Pragma("unroll") for (int n = 0; n < 2; ++n) _Pragma("unroll") for (int k = 0; k < 2; ++k) dst[n][k] = *(const LAS bf16x8*)(lds + PG8_SB(b, h) + boff + n * 2048 + k * 1024); } while (0)
; #define PG8_MMA(ai, bj, At, Bt) do { __builtin_amdgcn_s_setprio(1); _Pragma("unroll") for (int m = 0; m < 4; ++m) _Pragma("unroll") for (int n = 0; n < 2; ++n) _Pragma("unroll") for (int k = 0; k < 2; ++k) \
;         acc[ai][bj][m][n] = __builtin_amdgcn_mfma_f32_16x16x32_bf16(Bt[n][k], At[m][k], acc[ai][bj][m][n], 0, 0, 0); __builtin_amdgcn_s_setprio(0); } while (0)
; #define PG8_WAIT_V(n) asm volatile("s_waitcnt vmcnt(" #n ")" ::: "memory")
; #define PG8_WAIT_L(n) asm volatile("s_waitcnt lgkmcnt(" #n ")" ::: "memory")
; #define PG8_BAR __builtin_amdgcn_s_barrier()
; #define PG8_SCHED __builtin_amdgcn_sched_barrier(0)
; template <class Epi, class Sched, bool ABLK = false, bool ALIGN_EPI = true, bool SP2 = true, bool BBLK = true>
; __device__ __forceinline__ void gemm_phase(LAS unsigned char* lds, const Gemm g, const Sched& S, const Epi& E) {
;     ...
;         for (int t = 0; t < nt; t += 2) {
;             const bool last = (t == nt - 2);
;     ...
;             PG8_LDB(B0, 1, 0); PG8_LDB(B1, 1, 1); PG8_SCHED; PG8_LDA(At, 1, 0); PG8_STAGE(PG8_SA(0, 1), a2 + hstepA, voffA);
;             PG8_WAIT_V(8); PG8_WAIT_L(0); PG8_BAR; PG8_MMA(0, 0, At, B0); PG8_MMA(0, 1, At, B1); PG8_BAR; PG8_SCHED;
;             PG8_LDA(At, 1, 1); PG8_STAGE(PG8_SB(1, 0), b3, voffB); PG8_STAGE(PG8_SB(1, 1), b3 + hstepB, voffB); PG8_STAGE(PG8_SA(1, 0), a3, voffA);
;             PG8_WAIT_V(8); PG8_WAIT_L(0); PG8_BAR; PG8_MMA(1, 0, At, B0); PG8_MMA(1, 1, At, B1); PG8_BAR; PG8_SCHED;
	v_add_u32_e32 v168, s60, v151
	v_add_u32_e32 v184, s61, v151
	ds_read_b128 v[156:159], v168
	ds_read_b128 v[160:163], v168 offset:1024
	ds_read_b128 v[164:167], v168 offset:2048
	ds_read_b128 v[168:171], v168 offset:3072
	ds_read_b128 v[172:175], v184
	ds_read_b128 v[176:179], v184 offset:1024
	ds_read_b128 v[180:183], v184 offset:2048
	ds_read_b128 v[184:187], v184 offset:3072
	s_add_u32 s26, s26, 0x80000
	s_addc_u32 s27, s27, 0
	s_mov_b32 m0, s37
	ds_read_b128 v[188:191], v155 offset:32768
	ds_read_b128 v[192:195], v155 offset:33792
	ds_read_b128 v[196:199], v155 offset:34816
	ds_read_b128 v[200:203], v155 offset:35840
	ds_read_b128 v[204:207], v155 offset:36864
	ds_read_b128 v[208:211], v155 offset:37888
	ds_read_b128 v[212:215], v155 offset:38912
	ds_read_b128 v[216:219], v155 offset:39936
	global_load_lds_dwordx4 v130, s[26:27]
	s_mov_b32 m0, s40
	s_nop 0
	global_load_lds_dwordx4 v134, s[26:27]
	s_waitcnt vmcnt(8) lgkmcnt(0)
	s_barrier
	v_mfma_f32_16x16x32_bf16 v[126:129], v[156:159], v[188:191], v[126:129]
	v_mfma_f32_16x16x32_bf16 v[122:125], v[164:167], v[188:191], v[122:125]
	v_mfma_f32_16x16x32_bf16 v[110:113], v[156:159], v[196:199], v[110:113]
	v_mfma_f32_16x16x32_bf16 v[106:109], v[164:167], v[196:199], v[106:109]
	v_mfma_f32_16x16x32_bf16 v[94:97], v[156:159], v[204:207], v[94:97]
	v_mfma_f32_16x16x32_bf16 v[90:93], v[164:167], v[204:207], v[90:93]
	v_mfma_f32_16x16x32_bf16 v[78:81], v[156:159], v[212:215], v[78:81]
	v_mfma_f32_16x16x32_bf16 v[74:77], v[164:167], v[212:215], v[74:77]
	v_mfma_f32_16x16x32_bf16 v[126:129], v[160:163], v[192:195], v[126:129]
	v_mfma_f32_16x16x32_bf16 v[122:125], v[168:171], v[192:195], v[122:125]
	v_mfma_f32_16x16x32_bf16 v[110:113], v[160:163], v[200:203], v[110:113]
	v_mfma_f32_16x16x32_bf16 v[106:109], v[168:171], v[200:203], v[106:109]
	v_mfma_f32_16x16x32_bf16 v[94:97], v[160:163], v[208:211], v[94:97]
	v_mfma_f32_16x16x32_bf16 v[90:93], v[168:171], v[208:211], v[90:93]
	v_mfma_f32_16x16x32_bf16 v[78:81], v[160:163], v[216:219], v[78:81]
	v_mfma_f32_16x16x32_bf16 v[74:77], v[168:171], v[216:219], v[74:77]
	v_mfma_f32_16x16x32_bf16 v[118:121], v[172:175], v[188:191], v[118:121]
	v_mfma_f32_16x16x32_bf16 v[114:117], v[180:183], v[188:191], v[114:117]
	v_mfma_f32_16x16x32_bf16 v[102:105], v[172:175], v[196:199], v[102:105]
	v_mfma_f32_16x16x32_bf16 v[98:101], v[180:183], v[196:199], v[98:101]
	v_mfma_f32_16x16x32_bf16 v[86:89], v[172:175], v[204:207], v[86:89]
	v_mfma_f32_16x16x32_bf16 v[82:85], v[180:183], v[204:207], v[82:85]
	v_mfma_f32_16x16x32_bf16 v[70:73], v[172:175], v[212:215], v[70:73]
	v_mfma_f32_16x16x32_bf16 v[66:69], v[180:183], v[212:215], v[66:69]
	v_mfma_f32_16x16x32_bf16 v[118:121], v[176:179], v[192:195], v[118:121]
	v_mfma_f32_16x16x32_bf16 v[114:117], v[184:187], v[192:195], v[114:117]
	v_mfma_f32_16x16x32_bf16 v[102:105], v[176:179], v[200:203], v[102:105]
	v_mfma_f32_16x16x32_bf16 v[98:101], v[184:187], v[200:203], v[98:101]
	v_mfma_f32_16x16x32_bf16 v[86:89], v[176:179], v[208:211], v[86:89]
	v_mfma_f32_16x16x32_bf16 v[82:85], v[184:187], v[208:211], v[82:85]
	v_mfma_f32_16x16x32_bf16 v[70:73], v[176:179], v[216:219], v[70:73]
	v_mfma_f32_16x16x32_bf16 v[66:69], v[184:187], v[216:219], v[66:69]
	s_barrier
	s_add_u32 s26, s24, 0x8000
	s_addc_u32 s27, s25, 0
	s_add_i32 s66, s60, s34
	s_mov_b32 m0, s66
	ds_read_b128 v[188:191], v155 offset:49152
	ds_read_b128 v[192:195], v155 offset:50176
	ds_read_b128 v[196:199], v155 offset:51200
	ds_read_b128 v[200:203], v155 offset:52224
	ds_read_b128 v[204:207], v155 offset:53248
	ds_read_b128 v[208:211], v155 offset:54272
	ds_read_b128 v[212:215], v155 offset:55296
	ds_read_b128 v[216:219], v155 offset:56320
	global_load_lds_dwordx4 v132, s[26:27]
	s_add_i32 m0, s66, 0x2000
	s_add_u32 s24, s24, 0xc000
	v_lshl_add_u64 v[220:221], s[26:27], 0, v[136:137]
	s_addc_u32 s25, s25, 0
	s_add_i32 s26, s61, s34
	global_load_lds_dwordx4 v[220:221], off
	s_mov_b32 m0, s26
	s_nop 0
	global_load_lds_dwordx4 v132, s[24:25]
	s_add_i32 m0, s26, 0x2000
	s_nop 0
	global_load_lds_dwordx4 v136, s[24:25]
	s_mov_b32 m0, s41
	s_nop 0
	global_load_lds_dwordx4 v130, s[22:23]
	s_mov_b32 m0, s42
	s_nop 0
	global_load_lds_dwordx4 v134, s[22:23]
	s_waitcnt vmcnt(8) lgkmcnt(0)
	s_barrier
	v_mfma_f32_16x16x32_bf16 v[62:65], v[156:159], v[188:191], v[62:65]
	v_mfma_f32_16x16x32_bf16 v[58:61], v[164:167], v[188:191], v[58:61]
	v_mfma_f32_16x16x32_bf16 v[46:49], v[156:159], v[196:199], v[46:49]
	v_mfma_f32_16x16x32_bf16 v[42:45], v[164:167], v[196:199], v[42:45]
	v_mfma_f32_16x16x32_bf16 v[30:33], v[156:159], v[204:207], v[30:33]
	v_mfma_f32_16x16x32_bf16 v[26:29], v[164:167], v[204:207], v[26:29]
	v_mfma_f32_16x16x32_bf16 v[14:17], v[156:159], v[212:215], v[14:17]
	v_mfma_f32_16x16x32_bf16 v[10:13], v[164:167], v[212:215], v[10:13]
	v_mfma_f32_16x16x32_bf16 v[62:65], v[160:163], v[192:195], v[62:65]
	v_mfma_f32_16x16x32_bf16 v[58:61], v[168:171], v[192:195], v[58:61]
	v_mfma_f32_16x16x32_bf16 v[46:49], v[160:163], v[200:203], v[46:49]
	v_mfma_f32_16x16x32_bf16 v[42:45], v[168:171], v[200:203], v[42:45]
	v_mfma_f32_16x16x32_bf16 v[30:33], v[160:163], v[208:211], v[30:33]
	v_mfma_f32_16x16x32_bf16 v[26:29], v[168:171], v[208:211], v[26:29]
	v_mfma_f32_16x16x32_bf16 v[14:17], v[160:163], v[216:219], v[14:17]
	v_mfma_f32_16x16x32_bf16 v[10:13], v[168:171], v[216:219], v[10:13]
	v_mfma_f32_16x16x32_bf16 v[54:57], v[172:175], v[188:191], v[54:57]
	v_mfma_f32_16x16x32_bf16 v[50:53], v[180:183], v[188:191], v[50:53]
	v_mfma_f32_16x16x32_bf16 v[38:41], v[172:175], v[196:199], v[38:41]
	v_mfma_f32_16x16x32_bf16 v[34:37], v[180:183], v[196:199], v[34:37]
	v_mfma_f32_16x16x32_bf16 v[22:25], v[172:175], v[204:207], v[22:25]
	v_mfma_f32_16x16x32_bf16 v[18:21], v[180:183], v[204:207], v[18:21]
	v_mfma_f32_16x16x32_bf16 v[6:9], v[172:175], v[212:215], v[6:9]
	v_mfma_f32_16x16x32_bf16 v[2:5], v[180:183], v[212:215], v[2:5]
	v_mfma_f32_16x16x32_bf16 v[54:57], v[176:179], v[192:195], v[54:57]
	v_mfma_f32_16x16x32_bf16 v[50:53], v[184:187], v[192:195], v[50:53]
	v_mfma_f32_16x16x32_bf16 v[38:41], v[176:179], v[200:203], v[38:41]
	v_mfma_f32_16x16x32_bf16 v[34:37], v[184:187], v[200:203], v[34:37]
	v_mfma_f32_16x16x32_bf16 v[22:25], v[176:179], v[208:211], v[22:25]
	v_mfma_f32_16x16x32_bf16 v[18:21], v[184:187], v[208:211], v[18:21]
	v_mfma_f32_16x16x32_bf16 v[6:9], v[176:179], v[216:219], v[6:9]
	v_mfma_f32_16x16x32_bf16 v[2:5], v[184:187], v[216:219], v[2:5]
	s_barrier
	s_add_u32 s51, s51, 0x10000
	s_addc_u32 s55, s55, 0
	s_add_u32 s20, s20, 0x100
	s_addc_u32 s21, s21, 0
	s_cmp_ge_u32 s65, s46
	s_cbranch_scc0 .LBB0_1038
	s_and_b64 vcc, exec, s[10:11]
	s_cbranch_vccz .LBB0_1041
	s_barrier

; #define PG8_STAGE(bufoff, gbase, voff) do { _Pragma("unroll") for (int _i = 0; _i < 2; ++_i) \
;         __builtin_amdgcn_global_load_lds((const unsigned*)((const char*)(gbase) + (voff)[_i]), (LAS unsigned*)(lds + (bufoff) + ldsw + _i * 8192), 16, 0, 0); } while (0)
; #define PG8_LDA(dst, b, h) do { _Pragma("unroll") for (int m = 0; m < 4; ++m) _Pragma("unroll") for (int k = 0; k < 2; ++k) dst[m][k] = *(const LAS bf16x8*)(lds + PG8_SA(b, h) + aoff + m * 2048 + k * 1024); } while (0)
; #define PG8_LDB(dst, b, h) do { _Pragma("unroll") for (int n = 0; n < 2; ++n) _Pragma("unroll") for (int k = 0; k < 2; ++k) dst[n][k] = *(const LAS bf16x8*)(lds + PG8_SB(b, h) + boff + n * 2048 + k * 1024); } while (0)
; #define PG8_MMA(ai, bj, At, Bt) do { __builtin_amdgcn_s_setprio(1); _Pragma("unroll") for (int m = 0; m < 4; ++m) _Pragma("unroll") for (int n = 0; n < 2; ++n) _Pragma("unroll") for (int k = 0; k < 2; ++k) \
;         acc[ai][bj][m][n] = __builtin_amdgcn_mfma_f32_16x16x32_bf16(Bt[n][k], At[m][k], acc[ai][bj][m][n], 0, 0, 0); __builtin_amdgcn_s_setprio(0); } while (0)
; #define PG8_WAIT_V(n) asm volatile("s_waitcnt vmcnt(" #n ")" ::: "memory")
; template <class Epi, class Sched, bool ABLK = false, bool ALIGN_EPI = true, bool SP2 = true, bool BBLK = true>
; __device__ __forceinline__ void gemm_phase(LAS unsigned char* lds, const Gemm g, const Sched& S, const Epi& E) {
;     ...
;         for (int t = 0; t < nt; t += 2) {
;             const bool last = (t == nt - 2);
;             const char* a1 = a_tile(uA, tbA + t + 1);
;             const char* a2 = last ? a_tile(nuA, ntbA) : a_tile(uA, tbA + t + 2); const char* b2 = last ? nB : cB + (size_t)(t + 2) * kstepB;
;             const char* a3 = last ? a_tile(nuA, ntbA + 1) : a_tile(uA, tbA + t + 3); const char* b3 = b2 + kstepB;
;             if (last && has_next) S.a_ready(nxt);
;             if constexpr (SP2) {
;             PG8_LDB(B0, 0, 0); PG8_LDB(B1, 0, 1); PG8_SCHED; PG8_LDA(At, 0, 0); PG8_STAGE(PG8_SA(1, 1), a1 + hstepA, voffA);
;             PG8_WAIT_V(8); PG8_WAIT_L(0); PG8_BAR; PG8_MMA(0, 0, At, B0); PG8_MMA(0, 1, At, B1); PG8_BAR; PG8_SCHED;
;             PG8_LDA(At, 0, 1); PG8_STAGE(PG8_SB(0, 0), b2, voffB); PG8_STAGE(PG8_SB(0, 1), b2 + hstepB, voffB); PG8_STAGE(PG8_SA(0, 0), a2, voffA);
;             PG8_WAIT_V(8); PG8_WAIT_L(0); PG8_BAR; PG8_MMA(1, 0, At, B0); PG8_MMA(1, 1, At, B1); PG8_BAR; PG8_SCHED;
.LBB0_1164:
	ds_read_b128 v[172:175], v169
	ds_read_b128 v[176:179], v169 offset:1024
	ds_read_b128 v[180:183], v169 offset:2048
	ds_read_b128 v[184:187], v169 offset:3072
	ds_read_b128 v[188:191], v170
	ds_read_b128 v[192:195], v170 offset:1024
	ds_read_b128 v[196:199], v170 offset:2048
	ds_read_b128 v[200:203], v170 offset:3072
	s_add_u32 s30, s26, s28
	s_addc_u32 s31, s27, s29
	s_add_u32 s36, s30, 0x100
	s_addc_u32 s37, s31, 0
	s_add_u32 s30, s30, 0x180
	s_addc_u32 s31, s31, 0
	s_cmpk_eq_i32 s28, 0xf00
	s_cselect_b32 s31, s57, s31
	s_cselect_b32 s30, s23, s30
	s_cselect_b32 s35, s11, s65
	s_cselect_b32 s34, s15, s64
	s_cselect_b32 s37, s4, s37
	s_cselect_b32 s36, s5, s36
	s_mov_b32 m0, s50
	v_lshl_add_u64 v[236:237], v[164:165], 0, s[28:29]
	ds_read_b128 v[204:207], v171
	ds_read_b128 v[208:211], v171 offset:1024
	ds_read_b128 v[212:215], v171 offset:2048
	ds_read_b128 v[216:219], v171 offset:3072
	ds_read_b128 v[220:223], v171 offset:4096
	ds_read_b128 v[224:227], v171 offset:5120
	ds_read_b128 v[228:231], v171 offset:6144
	ds_read_b128 v[232:235], v171 offset:7168
	global_load_lds_dwordx4 v[236:237], off
	v_lshl_add_u64 v[236:237], v[166:167], 0, s[28:29]
	s_mov_b32 m0, s51
	s_nop 0
	global_load_lds_dwordx4 v[236:237], off
	s_waitcnt vmcnt(8) lgkmcnt(0)
	s_barrier
	v_mfma_f32_16x16x32_bf16 v[126:129], v[172:175], v[204:207], v[126:129]
	v_mfma_f32_16x16x32_bf16 v[122:125], v[180:183], v[204:207], v[122:125]
	v_mfma_f32_16x16x32_bf16 v[110:113], v[172:175], v[212:215], v[110:113]
	v_mfma_f32_16x16x32_bf16 v[106:109], v[180:183], v[212:215], v[106:109]
	v_mfma_f32_16x16x32_bf16 v[94:97], v[172:175], v[220:223], v[94:97]
	v_mfma_f32_16x16x32_bf16 v[90:93], v[180:183], v[220:223], v[90:93]
	v_mfma_f32_16x16x32_bf16 v[78:81], v[172:175], v[228:231], v[78:81]
	v_mfma_f32_16x16x32_bf16 v[74:77], v[180:183], v[228:231], v[74:77]
	v_mfma_f32_16x16x32_bf16 v[126:129], v[176:179], v[208:211], v[126:129]
	v_mfma_f32_16x16x32_bf16 v[122:125], v[184:187], v[208:211], v[122:125]
	v_mfma_f32_16x16x32_bf16 v[110:113], v[176:179], v[216:219], v[110:113]
	v_mfma_f32_16x16x32_bf16 v[106:109], v[184:187], v[216:219], v[106:109]
	v_mfma_f32_16x16x32_bf16 v[94:97], v[176:179], v[224:227], v[94:97]
	v_mfma_f32_16x16x32_bf16 v[90:93], v[184:187], v[224:227], v[90:93]
	v_mfma_f32_16x16x32_bf16 v[78:81], v[176:179], v[232:235], v[78:81]
	v_mfma_f32_16x16x32_bf16 v[74:77], v[184:187], v[232:235], v[74:77]
	v_mfma_f32_16x16x32_bf16 v[118:121], v[188:191], v[204:207], v[118:121]
	v_mfma_f32_16x16x32_bf16 v[114:117], v[196:199], v[204:207], v[114:117]
	v_mfma_f32_16x16x32_bf16 v[102:105], v[188:191], v[212:215], v[102:105]
	v_mfma_f32_16x16x32_bf16 v[98:101], v[196:199], v[212:215], v[98:101]
	v_mfma_f32_16x16x32_bf16 v[86:89], v[188:191], v[220:223], v[86:89]
	v_mfma_f32_16x16x32_bf16 v[82:85], v[196:199], v[220:223], v[82:85]
	v_mfma_f32_16x16x32_bf16 v[70:73], v[188:191], v[228:231], v[70:73]
	v_mfma_f32_16x16x32_bf16 v[66:69], v[196:199], v[228:231], v[66:69]
	v_mfma_f32_16x16x32_bf16 v[118:121], v[192:195], v[208:211], v[118:121]
	v_mfma_f32_16x16x32_bf16 v[114:117], v[200:203], v[208:211], v[114:117]
	v_mfma_f32_16x16x32_bf16 v[102:105], v[192:195], v[216:219], v[102:105]
	v_mfma_f32_16x16x32_bf16 v[98:101], v[200:203], v[216:219], v[98:101]
	v_mfma_f32_16x16x32_bf16 v[86:89], v[192:195], v[224:227], v[86:89]
	v_mfma_f32_16x16x32_bf16 v[82:85], v[200:203], v[224:227], v[82:85]
	v_mfma_f32_16x16x32_bf16 v[70:73], v[192:195], v[232:235], v[70:73]
	v_mfma_f32_16x16x32_bf16 v[66:69], v[200:203], v[232:235], v[66:69]
	s_barrier
	s_mov_b32 m0, s55
	s_add_u32 s76, s34, 0x4000
	ds_read_b128 v[204:207], v171 offset:16384
	ds_read_b128 v[208:211], v171 offset:17408
	ds_read_b128 v[212:215], v171 offset:18432
	ds_read_b128 v[216:219], v171 offset:19456
	ds_read_b128 v[220:223], v171 offset:20480
	ds_read_b128 v[224:227], v171 offset:21504
	ds_read_b128 v[228:231], v171 offset:22528
	ds_read_b128 v[232:235], v171 offset:23552
	global_load_lds_dwordx4 v134, s[34:35]
	s_mov_b32 m0, s56
	s_addc_u32 s77, s35, 0
	s_add_i32 s67, s73, s42
	global_load_lds_dwordx4 v130, s[34:35]
	s_mov_b32 m0, s67
	s_nop 0
	global_load_lds_dwordx4 v134, s[76:77]
	s_add_i32 m0, s67, 0x2000
	s_nop 0
	global_load_lds_dwordx4 v130, s[76:77]
	s_mov_b32 m0, s25
	s_nop 0
	global_load_lds_dwordx4 v136, s[36:37]
	s_mov_b32 m0, s43
	s_nop 0
	global_load_lds_dwordx4 v132, s[36:37]
	s_waitcnt vmcnt(8) lgkmcnt(0)
	s_barrier
	v_mfma_f32_16x16x32_bf16 v[62:65], v[172:175], v[204:207], v[62:65]
	v_mfma_f32_16x16x32_bf16 v[58:61], v[180:183], v[204:207], v[58:61]
	v_mfma_f32_16x16x32_bf16 v[46:49], v[172:175], v[212:215], v[46:49]
	v_mfma_f32_16x16x32_bf16 v[42:45], v[180:183], v[212:215], v[42:45]
	v_mfma_f32_16x16x32_bf16 v[30:33], v[172:175], v[220:223], v[30:33]
	v_mfma_f32_16x16x32_bf16 v[26:29], v[180:183], v[220:223], v[26:29]
	v_mfma_f32_16x16x32_bf16 v[14:17], v[172:175], v[228:231], v[14:17]
	v_mfma_f32_16x16x32_bf16 v[10:13], v[180:183], v[228:231], v[10:13]
	v_mfma_f32_16x16x32_bf16 v[62:65], v[176:179], v[208:211], v[62:65]
	v_mfma_f32_16x16x32_bf16 v[58:61], v[184:187], v[208:211], v[58:61]
	v_mfma_f32_16x16x32_bf16 v[46:49], v[176:179], v[216:219], v[46:49]
	v_mfma_f32_16x16x32_bf16 v[42:45], v[184:187], v[216:219], v[42:45]
	v_mfma_f32_16x16x32_bf16 v[30:33], v[176:179], v[224:227], v[30:33]
	v_mfma_f32_16x16x32_bf16 v[26:29], v[184:187], v[224:227], v[26:29]
	v_mfma_f32_16x16x32_bf16 v[14:17], v[176:179], v[232:235], v[14:17]
	v_mfma_f32_16x16x32_bf16 v[10:13], v[184:187], v[232:235], v[10:13]
	v_mfma_f32_16x16x32_bf16 v[54:57], v[188:191], v[204:207], v[54:57]
	v_mfma_f32_16x16x32_bf16 v[50:53], v[196:199], v[204:207], v[50:53]
	v_mfma_f32_16x16x32_bf16 v[38:41], v[188:191], v[212:215], v[38:41]
	v_mfma_f32_16x16x32_bf16 v[34:37], v[196:199], v[212:215], v[34:37]
	v_mfma_f32_16x16x32_bf16 v[22:25], v[188:191], v[220:223], v[22:25]
	v_mfma_f32_16x16x32_bf16 v[18:21], v[196:199], v[220:223], v[18:21]
	v_mfma_f32_16x16x32_bf16 v[6:9], v[188:191], v[228:231], v[6:9]
	v_mfma_f32_16x16x32_bf16 v[2:5], v[196:199], v[228:231], v[2:5]
	v_mfma_f32_16x16x32_bf16 v[54:57], v[192:195], v[208:211], v[54:57]
	v_mfma_f32_16x16x32_bf16 v[50:53], v[200:203], v[208:211], v[50:53]
	v_mfma_f32_16x16x32_bf16 v[38:41], v[192:195], v[216:219], v[38:41]
	v_mfma_f32_16x16x32_bf16 v[34:37], v[200:203], v[216:219], v[34:37]
	v_mfma_f32_16x16x32_bf16 v[22:25], v[192:195], v[224:227], v[22:25]
	v_mfma_f32_16x16x32_bf16 v[18:21], v[200:203], v[224:227], v[18:21]
	v_mfma_f32_16x16x32_bf16 v[6:9], v[192:195], v[232:235], v[6:9]
	v_mfma_f32_16x16x32_bf16 v[2:5], v[200:203], v[232:235], v[2:5]
	s_barrier
; #define PG8_STAGE(bufoff, gbase, voff) do { _Pragma("unroll") for (int _i = 0; _i < 2; ++_i) \
;         __builtin_amdgcn_global_load_lds((const unsigned*)((const char*)(gbase) + (voff)[_i]), (LAS unsigned*)(lds + (bufoff) + ldsw + _i * 8192), 16, 0, 0); } while (0)
; #define PG8_LDA(dst, b, h) do { _Pragma("unroll") for (int m = 0; m < 4; ++m) _Pragma("unroll") for (int k = 0; k < 2; ++k) dst[m][k] = *(const LAS bf16x8*)(lds + PG8_SA(b, h) + aoff + m * 2048 + k * 1024); } while (0)
; #define PG8_LDB(dst, b, h) do { _Pragma("unroll") for (int n = 0; n < 2; ++n) _Pragma("unroll") for (int k = 0; k < 2; ++k) dst[n][k] = *(const LAS bf16x8*)(lds + PG8_SB(b, h) + boff + n * 2048 + k * 1024); } while (0)
; #define PG8_MMA(ai, bj, At, Bt) do { __builtin_amdgcn_s_setprio(1); _Pragma("unroll") for (int m = 0; m < 4; ++m) _Pragma("unroll") for (int n = 0; n < 2; ++n) _Pragma("unroll") for (int k = 0; k < 2; ++k) \
;         acc[ai][bj][m][n] = __builtin_amdgcn_mfma_f32_16x16x32_bf16(Bt[n][k], At[m][k], acc[ai][bj][m][n], 0, 0, 0); __builtin_amdgcn_s_setprio(0); } while (0)
; #define PG8_WAIT_V(n) asm volatile("s_waitcnt vmcnt(" #n ")" ::: "memory")
; #define PG8_WAIT_L(n) asm volatile("s_waitcnt lgkmcnt(" #n ")" ::: "memory")
; #define PG8_BAR __builtin_amdgcn_s_barrier()
; #define PG8_SCHED __builtin_amdgcn_sched_barrier(0)
; template <class Epi, class Sched, bool ABLK = false, bool ALIGN_EPI = true, bool SP2 = true, bool BBLK = true>
; __device__ __forceinline__ void gemm_phase(LAS unsigned char* lds, const Gemm g, const Sched& S, const Epi& E) {
;     ...
;         for (int t = 0; t < nt; t += 2) {
;             const bool last = (t == nt - 2);
;     ...
;             PG8_LDB(B0, 1, 0); PG8_LDB(B1, 1, 1); PG8_SCHED; PG8_LDA(At, 1, 0); PG8_STAGE(PG8_SA(0, 1), a2 + hstepA, voffA);
;             PG8_WAIT_V(8); PG8_WAIT_L(0); PG8_BAR; PG8_MMA(0, 0, At, B0); PG8_MMA(0, 1, At, B1); PG8_BAR; PG8_SCHED;
;             PG8_LDA(At, 1, 1); PG8_STAGE(PG8_SB(1, 0), b3, voffB); PG8_STAGE(PG8_SB(1, 1), b3 + hstepB, voffB); PG8_STAGE(PG8_SA(1, 0), a3, voffA);
;             PG8_WAIT_V(8); PG8_WAIT_L(0); PG8_BAR; PG8_MMA(1, 0, At, B0); PG8_MMA(1, 1, At, B1); PG8_BAR; PG8_SCHED;
	v_add_u32_e32 v184, s60, v168
	v_add_u32_e32 v200, s61, v168
	ds_read_b128 v[172:175], v184
	ds_read_b128 v[176:179], v184 offset:1024
	ds_read_b128 v[180:183], v184 offset:2048
	ds_read_b128 v[184:187], v184 offset:3072
	ds_read_b128 v[188:191], v200
	ds_read_b128 v[192:195], v200 offset:1024
	ds_read_b128 v[196:199], v200 offset:2048
	ds_read_b128 v[200:203], v200 offset:3072
	s_add_u32 s36, s36, 0x80000
	s_addc_u32 s37, s37, 0
	s_mov_b32 m0, s44
	ds_read_b128 v[204:207], v171 offset:32768
	ds_read_b128 v[208:211], v171 offset:33792
	ds_read_b128 v[212:215], v171 offset:34816
	ds_read_b128 v[216:219], v171 offset:35840
	ds_read_b128 v[220:223], v171 offset:36864
	ds_read_b128 v[224:227], v171 offset:37888
	ds_read_b128 v[228:231], v171 offset:38912
	ds_read_b128 v[232:235], v171 offset:39936
	global_load_lds_dwordx4 v136, s[36:37]
	s_mov_b32 m0, s45
	s_nop 0
	global_load_lds_dwordx4 v132, s[36:37]
	s_waitcnt vmcnt(8) lgkmcnt(0)
	s_barrier
	v_mfma_f32_16x16x32_bf16 v[126:129], v[172:175], v[204:207], v[126:129]
	v_mfma_f32_16x16x32_bf16 v[122:125], v[180:183], v[204:207], v[122:125]
	v_mfma_f32_16x16x32_bf16 v[110:113], v[172:175], v[212:215], v[110:113]
	v_mfma_f32_16x16x32_bf16 v[106:109], v[180:183], v[212:215], v[106:109]
	v_mfma_f32_16x16x32_bf16 v[94:97], v[172:175], v[220:223], v[94:97]
	v_mfma_f32_16x16x32_bf16 v[90:93], v[180:183], v[220:223], v[90:93]
	v_mfma_f32_16x16x32_bf16 v[78:81], v[172:175], v[228:231], v[78:81]
	v_mfma_f32_16x16x32_bf16 v[74:77], v[180:183], v[228:231], v[74:77]
	v_mfma_f32_16x16x32_bf16 v[126:129], v[176:179], v[208:211], v[126:129]
	v_mfma_f32_16x16x32_bf16 v[122:125], v[184:187], v[208:211], v[122:125]
	v_mfma_f32_16x16x32_bf16 v[110:113], v[176:179], v[216:219], v[110:113]
	v_mfma_f32_16x16x32_bf16 v[106:109], v[184:187], v[216:219], v[106:109]
	v_mfma_f32_16x16x32_bf16 v[94:97], v[176:179], v[224:227], v[94:97]
	v_mfma_f32_16x16x32_bf16 v[90:93], v[184:187], v[224:227], v[90:93]
	v_mfma_f32_16x16x32_bf16 v[78:81], v[176:179], v[232:235], v[78:81]
	v_mfma_f32_16x16x32_bf16 v[74:77], v[184:187], v[232:235], v[74:77]
	v_mfma_f32_16x16x32_bf16 v[118:121], v[188:191], v[204:207], v[118:121]
	v_mfma_f32_16x16x32_bf16 v[114:117], v[196:199], v[204:207], v[114:117]
	v_mfma_f32_16x16x32_bf16 v[102:105], v[188:191], v[212:215], v[102:105]
	v_mfma_f32_16x16x32_bf16 v[98:101], v[196:199], v[212:215], v[98:101]
	v_mfma_f32_16x16x32_bf16 v[86:89], v[188:191], v[220:223], v[86:89]
	v_mfma_f32_16x16x32_bf16 v[82:85], v[196:199], v[220:223], v[82:85]
	v_mfma_f32_16x16x32_bf16 v[70:73], v[188:191], v[228:231], v[70:73]
	v_mfma_f32_16x16x32_bf16 v[66:69], v[196:199], v[228:231], v[66:69]
	v_mfma_f32_16x16x32_bf16 v[118:121], v[192:195], v[208:211], v[118:121]
	v_mfma_f32_16x16x32_bf16 v[114:117], v[200:203], v[208:211], v[114:117]
	v_mfma_f32_16x16x32_bf16 v[102:105], v[192:195], v[216:219], v[102:105]
	v_mfma_f32_16x16x32_bf16 v[98:101], v[200:203], v[216:219], v[98:101]
	v_mfma_f32_16x16x32_bf16 v[86:89], v[192:195], v[224:227], v[86:89]
	v_mfma_f32_16x16x32_bf16 v[82:85], v[200:203], v[224:227], v[82:85]
	v_mfma_f32_16x16x32_bf16 v[70:73], v[192:195], v[232:235], v[70:73]
	v_mfma_f32_16x16x32_bf16 v[66:69], v[200:203], v[232:235], v[66:69]
	s_barrier
	s_add_u32 s36, s34, 0x8000
	s_addc_u32 s37, s35, 0
	s_add_i32 s67, s60, s42
	s_mov_b32 m0, s67
	ds_read_b128 v[204:207], v171 offset:49152
	ds_read_b128 v[208:211], v171 offset:50176
	ds_read_b128 v[212:215], v171 offset:51200
	ds_read_b128 v[216:219], v171 offset:52224
	ds_read_b128 v[220:223], v171 offset:53248
	ds_read_b128 v[224:227], v171 offset:54272
	ds_read_b128 v[228:231], v171 offset:55296
	ds_read_b128 v[232:235], v171 offset:56320
	global_load_lds_dwordx4 v134, s[36:37]
	s_add_i32 m0, s67, 0x2000
	s_add_u32 s34, s34, 0xc000
	v_lshl_add_u64 v[236:237], s[36:37], 0, v[130:131]
	s_addc_u32 s35, s35, 0
	s_add_i32 s36, s61, s42
	global_load_lds_dwordx4 v[236:237], off
	s_mov_b32 m0, s36
	s_nop 0
	global_load_lds_dwordx4 v134, s[34:35]
	s_add_i32 m0, s36, 0x2000
	s_nop 0
	global_load_lds_dwordx4 v130, s[34:35]
	s_mov_b32 m0, s48
	s_nop 0
	global_load_lds_dwordx4 v136, s[30:31]
	s_mov_b32 m0, s49
	s_nop 0
	global_load_lds_dwordx4 v132, s[30:31]
	s_waitcnt vmcnt(8) lgkmcnt(0)
	s_barrier
	v_mfma_f32_16x16x32_bf16 v[62:65], v[172:175], v[204:207], v[62:65]
	v_mfma_f32_16x16x32_bf16 v[58:61], v[180:183], v[204:207], v[58:61]
	v_mfma_f32_16x16x32_bf16 v[46:49], v[172:175], v[212:215], v[46:49]
	v_mfma_f32_16x16x32_bf16 v[42:45], v[180:183], v[212:215], v[42:45]
	v_mfma_f32_16x16x32_bf16 v[30:33], v[172:175], v[220:223], v[30:33]
	v_mfma_f32_16x16x32_bf16 v[26:29], v[180:183], v[220:223], v[26:29]
	v_mfma_f32_16x16x32_bf16 v[14:17], v[172:175], v[228:231], v[14:17]
	v_mfma_f32_16x16x32_bf16 v[10:13], v[180:183], v[228:231], v[10:13]
	v_mfma_f32_16x16x32_bf16 v[62:65], v[176:179], v[208:211], v[62:65]
	v_mfma_f32_16x16x32_bf16 v[58:61], v[184:187], v[208:211], v[58:61]
	v_mfma_f32_16x16x32_bf16 v[46:49], v[176:179], v[216:219], v[46:49]
	v_mfma_f32_16x16x32_bf16 v[42:45], v[184:187], v[216:219], v[42:45]
	v_mfma_f32_16x16x32_bf16 v[30:33], v[176:179], v[224:227], v[30:33]
	v_mfma_f32_16x16x32_bf16 v[26:29], v[184:187], v[224:227], v[26:29]
	v_mfma_f32_16x16x32_bf16 v[14:17], v[176:179], v[232:235], v[14:17]
	v_mfma_f32_16x16x32_bf16 v[10:13], v[184:187], v[232:235], v[10:13]
	v_mfma_f32_16x16x32_bf16 v[54:57], v[188:191], v[204:207], v[54:57]
	v_mfma_f32_16x16x32_bf16 v[50:53], v[196:199], v[204:207], v[50:53]
	v_mfma_f32_16x16x32_bf16 v[38:41], v[188:191], v[212:215], v[38:41]
	v_mfma_f32_16x16x32_bf16 v[34:37], v[196:199], v[212:215], v[34:37]
	v_mfma_f32_16x16x32_bf16 v[22:25], v[188:191], v[220:223], v[22:25]
	v_mfma_f32_16x16x32_bf16 v[18:21], v[196:199], v[220:223], v[18:21]
	v_mfma_f32_16x16x32_bf16 v[6:9], v[188:191], v[228:231], v[6:9]
	v_mfma_f32_16x16x32_bf16 v[2:5], v[196:199], v[228:231], v[2:5]
	v_mfma_f32_16x16x32_bf16 v[54:57], v[192:195], v[208:211], v[54:57]
	v_mfma_f32_16x16x32_bf16 v[50:53], v[200:203], v[208:211], v[50:53]
	v_mfma_f32_16x16x32_bf16 v[38:41], v[192:195], v[216:219], v[38:41]
	v_mfma_f32_16x16x32_bf16 v[34:37], v[200:203], v[216:219], v[34:37]
	v_mfma_f32_16x16x32_bf16 v[22:25], v[192:195], v[224:227], v[22:25]
	v_mfma_f32_16x16x32_bf16 v[18:21], v[200:203], v[224:227], v[18:21]
	v_mfma_f32_16x16x32_bf16 v[6:9], v[192:195], v[232:235], v[6:9]
	v_mfma_f32_16x16x32_bf16 v[2:5], v[200:203], v[232:235], v[2:5]
	s_barrier
	s_add_i32 s66, s66, 2
	s_add_u32 s28, s28, 0x100
	s_addc_u32 s29, s29, 0
	s_add_u32 s64, s64, 0x10000
	s_addc_u32 s65, s65, 0
	s_cmp_gt_u32 s66, 29
	s_cbranch_scc0 .LBB0_1164
	s_and_b64 vcc, exec, s[6:7]
	s_cbranch_vccz .LBB0_1167
	s_barrier

; #define PG8_STAGE(bufoff, gbase, voff) do { _Pragma("unroll") for (int _i = 0; _i < 2; ++_i) \
;         __builtin_amdgcn_global_load_lds((const unsigned*)((const char*)(gbase) + (voff)[_i]), (LAS unsigned*)(lds + (bufoff) + ldsw + _i * 8192), 16, 0, 0); } while (0)
; #define PG8_LDA(dst, b, h) do { _Pragma("unroll") for (int m = 0; m < 4; ++m) _Pragma("unroll") for (int k = 0; k < 2; ++k) dst[m][k] = *(const LAS bf16x8*)(lds + PG8_SA(b, h) + aoff + m * 2048 + k * 1024); } while (0)
; #define PG8_LDB(dst, b, h) do { _Pragma("unroll") for (int n = 0; n < 2; ++n) _Pragma("unroll") for (int k = 0; k < 2; ++k) dst[n][k] = *(const LAS bf16x8*)(lds + PG8_SB(b, h) + boff + n * 2048 + k * 1024); } while (0)
; #define PG8_MMA(ai, bj, At, Bt) do { __builtin_amdgcn_s_setprio(1); _Pragma("unroll") for (int m = 0; m < 4; ++m) _Pragma("unroll") for (int n = 0; n < 2; ++n) _Pragma("unroll") for (int k = 0; k < 2; ++k) \
;         acc[ai][bj][m][n] = __builtin_amdgcn_mfma_f32_16x16x32_bf16(Bt[n][k], At[m][k], acc[ai][bj][m][n], 0, 0, 0); __builtin_amdgcn_s_setprio(0); } while (0)
; #define PG8_WAIT_V(n) asm volatile("s_waitcnt vmcnt(" #n ")" ::: "memory")
; template <class Epi, class Sched, bool ABLK = false, bool ALIGN_EPI = true, bool SP2 = true, bool BBLK = true>
; __device__ __forceinline__ void gemm_phase(LAS unsigned char* lds, const Gemm g, const Sched& S, const Epi& E) {
;     ...
;         for (int t = 0; t < nt; t += 2) {
;             const bool last = (t == nt - 2);
;             const char* a1 = a_tile(uA, tbA + t + 1);
;             const char* a2 = last ? a_tile(nuA, ntbA) : a_tile(uA, tbA + t + 2); const char* b2 = last ? nB : cB + (size_t)(t + 2) * kstepB;
;             const char* a3 = last ? a_tile(nuA, ntbA + 1) : a_tile(uA, tbA + t + 3); const char* b3 = b2 + kstepB;
;             if (last && has_next) S.a_ready(nxt);
;             if constexpr (SP2) {
;             PG8_LDB(B0, 0, 0); PG8_LDB(B1, 0, 1); PG8_SCHED; PG8_LDA(At, 0, 0); PG8_STAGE(PG8_SA(1, 1), a1 + hstepA, voffA);
;             PG8_WAIT_V(8); PG8_WAIT_L(0); PG8_BAR; PG8_MMA(0, 0, At, B0); PG8_MMA(0, 1, At, B1); PG8_BAR; PG8_SCHED;
;             PG8_LDA(At, 0, 1); PG8_STAGE(PG8_SB(0, 0), b2, voffB); PG8_STAGE(PG8_SB(0, 1), b2 + hstepB, voffB); PG8_STAGE(PG8_SA(0, 0), a2, voffA);
;             PG8_WAIT_V(8); PG8_WAIT_L(0); PG8_BAR; PG8_MMA(1, 0, At, B0); PG8_MMA(1, 1, At, B1); PG8_BAR; PG8_SCHED;
.LBB0_1229:
	ds_read_b128 v[152:155], v149
	ds_read_b128 v[156:159], v149 offset:1024
	ds_read_b128 v[160:163], v149 offset:2048
	ds_read_b128 v[164:167], v149 offset:3072
	ds_read_b128 v[168:171], v150
	ds_read_b128 v[172:175], v150 offset:1024
	ds_read_b128 v[176:179], v150 offset:2048
	ds_read_b128 v[180:183], v150 offset:3072
	s_add_u32 s24, s51, s22
	s_addc_u32 s25, s55, s23
	s_add_u32 s28, s24, 0x10000
	s_addc_u32 s29, s25, 0
	s_add_i32 s57, s57, 2
	s_add_u32 s26, s49, s22
	s_addc_u32 s27, s50, s23
	s_add_u32 s24, s24, 0x18000
	s_addc_u32 s25, s25, 0
	s_cmp_eq_u32 s56, s22
	s_cselect_b32 s25, s48, s25
	s_cselect_b32 s24, s47, s24
	s_cselect_b32 s27, s4, s27
	s_cselect_b32 s26, s5, s26
	s_cselect_b32 s29, s46, s29
	s_cselect_b32 s28, s19, s28
	v_lshl_add_u64 v[216:217], v[142:143], 0, s[22:23]
	s_add_i32 m0, s35, 0xc000
	ds_read_b128 v[184:187], v151
	ds_read_b128 v[188:191], v151 offset:1024
	ds_read_b128 v[192:195], v151 offset:2048
	ds_read_b128 v[196:199], v151 offset:3072
	ds_read_b128 v[200:203], v151 offset:4096
	ds_read_b128 v[204:207], v151 offset:5120
	ds_read_b128 v[208:211], v151 offset:6144
	ds_read_b128 v[212:215], v151 offset:7168
	global_load_lds_dwordx4 v[216:217], off
	v_lshl_add_u64 v[216:217], v[144:145], 0, s[22:23]
	s_add_i32 m0, s35, 0xe000
	s_nop 0
	global_load_lds_dwordx4 v[216:217], off
	s_waitcnt vmcnt(8) lgkmcnt(0)
	s_barrier
	v_mfma_f32_16x16x32_bf16 v[126:129], v[152:155], v[184:187], v[126:129]
	v_mfma_f32_16x16x32_bf16 v[122:125], v[160:163], v[184:187], v[122:125]
	v_mfma_f32_16x16x32_bf16 v[110:113], v[152:155], v[192:195], v[110:113]
	v_mfma_f32_16x16x32_bf16 v[106:109], v[160:163], v[192:195], v[106:109]
	v_mfma_f32_16x16x32_bf16 v[94:97], v[152:155], v[200:203], v[94:97]
	v_mfma_f32_16x16x32_bf16 v[90:93], v[160:163], v[200:203], v[90:93]
	v_mfma_f32_16x16x32_bf16 v[78:81], v[152:155], v[208:211], v[78:81]
	v_mfma_f32_16x16x32_bf16 v[74:77], v[160:163], v[208:211], v[74:77]
	v_mfma_f32_16x16x32_bf16 v[126:129], v[156:159], v[188:191], v[126:129]
	v_mfma_f32_16x16x32_bf16 v[122:125], v[164:167], v[188:191], v[122:125]
	v_mfma_f32_16x16x32_bf16 v[110:113], v[156:159], v[196:199], v[110:113]
	v_mfma_f32_16x16x32_bf16 v[106:109], v[164:167], v[196:199], v[106:109]
	v_mfma_f32_16x16x32_bf16 v[94:97], v[156:159], v[204:207], v[94:97]
	v_mfma_f32_16x16x32_bf16 v[90:93], v[164:167], v[204:207], v[90:93]
	v_mfma_f32_16x16x32_bf16 v[78:81], v[156:159], v[212:215], v[78:81]
	v_mfma_f32_16x16x32_bf16 v[74:77], v[164:167], v[212:215], v[74:77]
	v_mfma_f32_16x16x32_bf16 v[118:121], v[168:171], v[184:187], v[118:121]
	v_mfma_f32_16x16x32_bf16 v[114:117], v[176:179], v[184:187], v[114:117]
	v_mfma_f32_16x16x32_bf16 v[102:105], v[168:171], v[192:195], v[102:105]
	v_mfma_f32_16x16x32_bf16 v[98:101], v[176:179], v[192:195], v[98:101]
	v_mfma_f32_16x16x32_bf16 v[86:89], v[168:171], v[200:203], v[86:89]
	v_mfma_f32_16x16x32_bf16 v[82:85], v[176:179], v[200:203], v[82:85]
	v_mfma_f32_16x16x32_bf16 v[70:73], v[168:171], v[208:211], v[70:73]
	v_mfma_f32_16x16x32_bf16 v[66:69], v[176:179], v[208:211], v[66:69]
	v_mfma_f32_16x16x32_bf16 v[118:121], v[172:175], v[188:191], v[118:121]
	v_mfma_f32_16x16x32_bf16 v[114:117], v[180:183], v[188:191], v[114:117]
	v_mfma_f32_16x16x32_bf16 v[102:105], v[172:175], v[196:199], v[102:105]
	v_mfma_f32_16x16x32_bf16 v[98:101], v[180:183], v[196:199], v[98:101]
	v_mfma_f32_16x16x32_bf16 v[86:89], v[172:175], v[204:207], v[86:89]
	v_mfma_f32_16x16x32_bf16 v[82:85], v[180:183], v[204:207], v[82:85]
	v_mfma_f32_16x16x32_bf16 v[70:73], v[172:175], v[212:215], v[70:73]
	v_mfma_f32_16x16x32_bf16 v[66:69], v[180:183], v[212:215], v[66:69]
	s_barrier
	s_add_i32 s59, s72, s34
	s_mov_b32 m0, s59
	ds_read_b128 v[184:187], v151 offset:16384
	ds_read_b128 v[188:191], v151 offset:17408
	ds_read_b128 v[192:195], v151 offset:18432
	ds_read_b128 v[196:199], v151 offset:19456
	ds_read_b128 v[200:203], v151 offset:20480
	ds_read_b128 v[204:207], v151 offset:21504
	ds_read_b128 v[208:211], v151 offset:22528
	ds_read_b128 v[212:215], v151 offset:23552
	global_load_lds_dwordx4 v130, s[26:27]
	s_add_i32 m0, s59, 0x2000
	s_add_u32 s64, s26, 0x4000
	s_addc_u32 s65, s27, 0
	s_add_i32 s59, s73, s34
	global_load_lds_dwordx4 v132, s[26:27]
	s_mov_b32 m0, s59
	s_nop 0
	global_load_lds_dwordx4 v130, s[64:65]
	s_add_i32 m0, s59, 0x2000
	s_nop 0
	global_load_lds_dwordx4 v132, s[64:65]
	s_mov_b32 m0, s35
	s_nop 0
	global_load_lds_dwordx4 v130, s[28:29]
	s_mov_b32 m0, s36
	s_nop 0
	global_load_lds_dwordx4 v132, s[28:29]
	s_waitcnt vmcnt(8) lgkmcnt(0)
	s_barrier
; #define PG8_STAGE(bufoff, gbase, voff) do { _Pragma("unroll") for (int _i = 0; _i < 2; ++_i) \
;         __builtin_amdgcn_global_load_lds((const unsigned*)((const char*)(gbase) + (voff)[_i]), (LAS unsigned*)(lds + (bufoff) + ldsw + _i * 8192), 16, 0, 0); } while (0)
; #define PG8_LDA(dst, b, h) do { _Pragma("unroll") for (int m = 0; m < 4; ++m) _Pragma("unroll") for (int k = 0; k < 2; ++k) dst[m][k] = *(const LAS bf16x8*)(lds + PG8_SA(b, h) + aoff + m * 2048 + k * 1024); } while (0)
; #define PG8_LDB(dst, b, h) do { _Pragma("unroll") for (int n = 0; n < 2; ++n) _Pragma("unroll") for (int k = 0; k < 2; ++k) dst[n][k] = *(const LAS bf16x8*)(lds + PG8_SB(b, h) + boff + n * 2048 + k * 1024); } while (0)
; #define PG8_MMA(ai, bj, At, Bt) do { __builtin_amdgcn_s_setprio(1); _Pragma("unroll") for (int m = 0; m < 4; ++m) _Pragma("unroll") for (int n = 0; n < 2; ++n) _Pragma("unroll") for (int k = 0; k < 2; ++k) \
;         acc[ai][bj][m][n] = __builtin_amdgcn_mfma_f32_16x16x32_bf16(Bt[n][k], At[m][k], acc[ai][bj][m][n], 0, 0, 0); __builtin_amdgcn_s_setprio(0); } while (0)
; #define PG8_WAIT_V(n) asm volatile("s_waitcnt vmcnt(" #n ")" ::: "memory")
; #define PG8_WAIT_L(n) asm volatile("s_waitcnt lgkmcnt(" #n ")" ::: "memory")
; #define PG8_BAR __builtin_amdgcn_s_barrier()
; #define PG8_SCHED __builtin_amdgcn_sched_barrier(0)
; template <class Epi, class Sched, bool ABLK = false, bool ALIGN_EPI = true, bool SP2 = true, bool BBLK = true>
; __device__ __forceinline__ void gemm_phase(LAS unsigned char* lds, const Gemm g, const Sched& S, const Epi& E) {
;     ...
;             PG8_LDB(B0, 1, 0); PG8_LDB(B1, 1, 1); PG8_SCHED; PG8_LDA(At, 1, 0); PG8_STAGE(PG8_SA(0, 1), a2 + hstepA, voffA);
;             PG8_WAIT_V(8); PG8_WAIT_L(0); PG8_BAR; PG8_MMA(0, 0, At, B0); PG8_MMA(0, 1, At, B1); PG8_BAR; PG8_SCHED;
	v_mfma_f32_16x16x32_bf16 v[62:65], v[152:155], v[184:187], v[62:65]
	v_mfma_f32_16x16x32_bf16 v[58:61], v[160:163], v[184:187], v[58:61]
	v_mfma_f32_16x16x32_bf16 v[46:49], v[152:155], v[192:195], v[46:49]
	v_mfma_f32_16x16x32_bf16 v[42:45], v[160:163], v[192:195], v[42:45]
	v_mfma_f32_16x16x32_bf16 v[30:33], v[152:155], v[200:203], v[30:33]
	v_mfma_f32_16x16x32_bf16 v[26:29], v[160:163], v[200:203], v[26:29]
	v_mfma_f32_16x16x32_bf16 v[14:17], v[152:155], v[208:211], v[14:17]
	v_mfma_f32_16x16x32_bf16 v[10:13], v[160:163], v[208:211], v[10:13]
	v_mfma_f32_16x16x32_bf16 v[62:65], v[156:159], v[188:191], v[62:65]
	v_mfma_f32_16x16x32_bf16 v[58:61], v[164:167], v[188:191], v[58:61]
	v_mfma_f32_16x16x32_bf16 v[46:49], v[156:159], v[196:199], v[46:49]
	v_mfma_f32_16x16x32_bf16 v[42:45], v[164:167], v[196:199], v[42:45]
	v_mfma_f32_16x16x32_bf16 v[30:33], v[156:159], v[204:207], v[30:33]
	v_mfma_f32_16x16x32_bf16 v[26:29], v[164:167], v[204:207], v[26:29]
	v_mfma_f32_16x16x32_bf16 v[14:17], v[156:159], v[212:215], v[14:17]
	v_mfma_f32_16x16x32_bf16 v[10:13], v[164:167], v[212:215], v[10:13]
	v_mfma_f32_16x16x32_bf16 v[54:57], v[168:171], v[184:187], v[54:57]
	v_mfma_f32_16x16x32_bf16 v[50:53], v[176:179], v[184:187], v[50:53]
	v_mfma_f32_16x16x32_bf16 v[38:41], v[168:171], v[192:195], v[38:41]
	v_mfma_f32_16x16x32_bf16 v[34:37], v[176:179], v[192:195], v[34:37]
	v_mfma_f32_16x16x32_bf16 v[22:25], v[168:171], v[200:203], v[22:25]
	v_mfma_f32_16x16x32_bf16 v[18:21], v[176:179], v[200:203], v[18:21]
	v_mfma_f32_16x16x32_bf16 v[6:9], v[168:171], v[208:211], v[6:9]
	v_mfma_f32_16x16x32_bf16 v[2:5], v[176:179], v[208:211], v[2:5]
	v_mfma_f32_16x16x32_bf16 v[54:57], v[172:175], v[188:191], v[54:57]
	v_mfma_f32_16x16x32_bf16 v[50:53], v[180:183], v[188:191], v[50:53]
	v_mfma_f32_16x16x32_bf16 v[38:41], v[172:175], v[196:199], v[38:41]
	v_mfma_f32_16x16x32_bf16 v[34:37], v[180:183], v[196:199], v[34:37]
	v_mfma_f32_16x16x32_bf16 v[22:25], v[172:175], v[204:207], v[22:25]
	v_mfma_f32_16x16x32_bf16 v[18:21], v[180:183], v[204:207], v[18:21]
	v_mfma_f32_16x16x32_bf16 v[6:9], v[172:175], v[212:215], v[6:9]
	v_mfma_f32_16x16x32_bf16 v[2:5], v[180:183], v[212:215], v[2:5]
	s_barrier
	v_add_u32_e32 v164, s60, v147
	v_add_u32_e32 v180, s61, v147
	ds_read_b128 v[152:155], v164
	ds_read_b128 v[156:159], v164 offset:1024
	ds_read_b128 v[160:163], v164 offset:2048
	ds_read_b128 v[164:167], v164 offset:3072
	ds_read_b128 v[168:171], v180
	ds_read_b128 v[172:175], v180 offset:1024
	ds_read_b128 v[176:179], v180 offset:2048
	ds_read_b128 v[180:183], v180 offset:3072
	s_add_u32 s28, s28, 0x4000
	s_addc_u32 s29, s29, 0
	s_mov_b32 m0, s37
	ds_read_b128 v[184:187], v151 offset:32768
	ds_read_b128 v[188:191], v151 offset:33792
	ds_read_b128 v[192:195], v151 offset:34816
	ds_read_b128 v[196:199], v151 offset:35840
	ds_read_b128 v[200:203], v151 offset:36864
	ds_read_b128 v[204:207], v151 offset:37888
	ds_read_b128 v[208:211], v151 offset:38912
	ds_read_b128 v[212:215], v151 offset:39936
	global_load_lds_dwordx4 v130, s[28:29]
	s_mov_b32 m0, s40
	s_nop 0
	global_load_lds_dwordx4 v132, s[28:29]
	s_waitcnt vmcnt(8) lgkmcnt(0)
	s_barrier
	v_mfma_f32_16x16x32_bf16 v[126:129], v[152:155], v[184:187], v[126:129]
	v_mfma_f32_16x16x32_bf16 v[122:125], v[160:163], v[184:187], v[122:125]
	v_mfma_f32_16x16x32_bf16 v[110:113], v[152:155], v[192:195], v[110:113]
	v_mfma_f32_16x16x32_bf16 v[106:109], v[160:163], v[192:195], v[106:109]
	v_mfma_f32_16x16x32_bf16 v[94:97], v[152:155], v[200:203], v[94:97]
	v_mfma_f32_16x16x32_bf16 v[90:93], v[160:163], v[200:203], v[90:93]
	v_mfma_f32_16x16x32_bf16 v[78:81], v[152:155], v[208:211], v[78:81]
	v_mfma_f32_16x16x32_bf16 v[74:77], v[160:163], v[208:211], v[74:77]
	v_mfma_f32_16x16x32_bf16 v[126:129], v[156:159], v[188:191], v[126:129]
	v_mfma_f32_16x16x32_bf16 v[122:125], v[164:167], v[188:191], v[122:125]
	v_mfma_f32_16x16x32_bf16 v[110:113], v[156:159], v[196:199], v[110:113]
	v_mfma_f32_16x16x32_bf16 v[106:109], v[164:167], v[196:199], v[106:109]
	v_mfma_f32_16x16x32_bf16 v[94:97], v[156:159], v[204:207], v[94:97]
	v_mfma_f32_16x16x32_bf16 v[90:93], v[164:167], v[204:207], v[90:93]
	v_mfma_f32_16x16x32_bf16 v[78:81], v[156:159], v[212:215], v[78:81]
	v_mfma_f32_16x16x32_bf16 v[74:77], v[164:167], v[212:215], v[74:77]
	v_mfma_f32_16x16x32_bf16 v[118:121], v[168:171], v[184:187], v[118:121]
	v_mfma_f32_16x16x32_bf16 v[114:117], v[176:179], v[184:187], v[114:117]
	v_mfma_f32_16x16x32_bf16 v[102:105], v[168:171], v[192:195], v[102:105]
	v_mfma_f32_16x16x32_bf16 v[98:101], v[176:179], v[192:195], v[98:101]
	v_mfma_f32_16x16x32_bf16 v[86:89], v[168:171], v[200:203], v[86:89]
	v_mfma_f32_16x16x32_bf16 v[82:85], v[176:179], v[200:203], v[82:85]
	v_mfma_f32_16x16x32_bf16 v[70:73], v[168:171], v[208:211], v[70:73]
	v_mfma_f32_16x16x32_bf16 v[66:69], v[176:179], v[208:211], v[66:69]
	v_mfma_f32_16x16x32_bf16 v[118:121], v[172:175], v[188:191], v[118:121]
	v_mfma_f32_16x16x32_bf16 v[114:117], v[180:183], v[188:191], v[114:117]
	v_mfma_f32_16x16x32_bf16 v[102:105], v[172:175], v[196:199], v[102:105]
	v_mfma_f32_16x16x32_bf16 v[98:101], v[180:183], v[196:199], v[98:101]
	v_mfma_f32_16x16x32_bf16 v[86:89], v[172:175], v[204:207], v[86:89]
	v_mfma_f32_16x16x32_bf16 v[82:85], v[180:183], v[204:207], v[82:85]
	v_mfma_f32_16x16x32_bf16 v[70:73], v[172:175], v[212:215], v[70:73]
	v_mfma_f32_16x16x32_bf16 v[66:69], v[180:183], v[212:215], v[66:69]
	s_barrier
; #define PG8_STAGE(bufoff, gbase, voff) do { _Pragma("unroll") for (int _i = 0; _i < 2; ++_i) \
;         __builtin_amdgcn_global_load_lds((const unsigned*)((const char*)(gbase) + (voff)[_i]), (LAS unsigned*)(lds + (bufoff) + ldsw + _i * 8192), 16, 0, 0); } while (0)
; #define PG8_LDA(dst, b, h) do { _Pragma("unroll") for (int m = 0; m < 4; ++m) _Pragma("unroll") for (int k = 0; k < 2; ++k) dst[m][k] = *(const LAS bf16x8*)(lds + PG8_SA(b, h) + aoff + m * 2048 + k * 1024); } while (0)
; #define PG8_MMA(ai, bj, At, Bt) do { __builtin_amdgcn_s_setprio(1); _Pragma("unroll") for (int m = 0; m < 4; ++m) _Pragma("unroll") for (int n = 0; n < 2; ++n) _Pragma("unroll") for (int k = 0; k < 2; ++k) \
;         acc[ai][bj][m][n] = __builtin_amdgcn_mfma_f32_16x16x32_bf16(Bt[n][k], At[m][k], acc[ai][bj][m][n], 0, 0, 0); __builtin_amdgcn_s_setprio(0); } while (0)
; #define PG8_WAIT_V(n) asm volatile("s_waitcnt vmcnt(" #n ")" ::: "memory")
; #define PG8_WAIT_L(n) asm volatile("s_waitcnt lgkmcnt(" #n ")" ::: "memory")
; #define PG8_BAR __builtin_amdgcn_s_barrier()
; #define PG8_SCHED __builtin_amdgcn_sched_barrier(0)
; template <class Epi, class Sched, bool ABLK = false, bool ALIGN_EPI = true, bool SP2 = true, bool BBLK = true>
; __device__ __forceinline__ void gemm_phase(LAS unsigned char* lds, const Gemm g, const Sched& S, const Epi& E) {
;     ...
;         for (int t = 0; t < nt; t += 2) {
;             const bool last = (t == nt - 2);
;     ...
;             PG8_LDA(At, 1, 1); PG8_STAGE(PG8_SB(1, 0), b3, voffB); PG8_STAGE(PG8_SB(1, 1), b3 + hstepB, voffB); PG8_STAGE(PG8_SA(1, 0), a3, voffA);
;             PG8_WAIT_V(8); PG8_WAIT_L(0); PG8_BAR; PG8_MMA(1, 0, At, B0); PG8_MMA(1, 1, At, B1); PG8_BAR; PG8_SCHED;
	s_add_u32 s28, s26, 0x8000
	s_addc_u32 s29, s27, 0
	s_add_i32 s59, s60, s34
	s_mov_b32 m0, s59
	ds_read_b128 v[184:187], v151 offset:49152
	ds_read_b128 v[188:191], v151 offset:50176
	ds_read_b128 v[192:195], v151 offset:51200
	ds_read_b128 v[196:199], v151 offset:52224
	ds_read_b128 v[200:203], v151 offset:53248
	ds_read_b128 v[204:207], v151 offset:54272
	ds_read_b128 v[208:211], v151 offset:55296
	ds_read_b128 v[212:215], v151 offset:56320
	global_load_lds_dwordx4 v130, s[28:29]
	s_add_i32 m0, s59, 0x2000
	s_add_u32 s26, s26, 0xc000
	v_lshl_add_u64 v[216:217], s[28:29], 0, v[132:133]
	s_addc_u32 s27, s27, 0
	s_add_i32 s28, s61, s34
	global_load_lds_dwordx4 v[216:217], off
	s_mov_b32 m0, s28
	s_nop 0
	global_load_lds_dwordx4 v130, s[26:27]
	s_add_i32 m0, s28, 0x2000
	s_nop 0
	global_load_lds_dwordx4 v132, s[26:27]
	s_mov_b32 m0, s41
	s_nop 0
	global_load_lds_dwordx4 v130, s[24:25]
	s_mov_b32 m0, s42
	s_nop 0
	global_load_lds_dwordx4 v132, s[24:25]
	s_waitcnt vmcnt(8) lgkmcnt(0)
	s_barrier
	v_mfma_f32_16x16x32_bf16 v[62:65], v[152:155], v[184:187], v[62:65]
	v_mfma_f32_16x16x32_bf16 v[58:61], v[160:163], v[184:187], v[58:61]
	v_mfma_f32_16x16x32_bf16 v[46:49], v[152:155], v[192:195], v[46:49]
	v_mfma_f32_16x16x32_bf16 v[42:45], v[160:163], v[192:195], v[42:45]
	v_mfma_f32_16x16x32_bf16 v[30:33], v[152:155], v[200:203], v[30:33]
	v_mfma_f32_16x16x32_bf16 v[26:29], v[160:163], v[200:203], v[26:29]
	v_mfma_f32_16x16x32_bf16 v[14:17], v[152:155], v[208:211], v[14:17]
	v_mfma_f32_16x16x32_bf16 v[10:13], v[160:163], v[208:211], v[10:13]
	v_mfma_f32_16x16x32_bf16 v[62:65], v[156:159], v[188:191], v[62:65]
	v_mfma_f32_16x16x32_bf16 v[58:61], v[164:167], v[188:191], v[58:61]
	v_mfma_f32_16x16x32_bf16 v[46:49], v[156:159], v[196:199], v[46:49]
	v_mfma_f32_16x16x32_bf16 v[42:45], v[164:167], v[196:199], v[42:45]
	v_mfma_f32_16x16x32_bf16 v[30:33], v[156:159], v[204:207], v[30:33]
	v_mfma_f32_16x16x32_bf16 v[26:29], v[164:167], v[204:207], v[26:29]
	v_mfma_f32_16x16x32_bf16 v[14:17], v[156:159], v[212:215], v[14:17]
	v_mfma_f32_16x16x32_bf16 v[10:13], v[164:167], v[212:215], v[10:13]
	v_mfma_f32_16x16x32_bf16 v[54:57], v[168:171], v[184:187], v[54:57]
	v_mfma_f32_16x16x32_bf16 v[50:53], v[176:179], v[184:187], v[50:53]
	v_mfma_f32_16x16x32_bf16 v[38:41], v[168:171], v[192:195], v[38:41]
	v_mfma_f32_16x16x32_bf16 v[34:37], v[176:179], v[192:195], v[34:37]
	v_mfma_f32_16x16x32_bf16 v[22:25], v[168:171], v[200:203], v[22:25]
	v_mfma_f32_16x16x32_bf16 v[18:21], v[176:179], v[200:203], v[18:21]
	v_mfma_f32_16x16x32_bf16 v[6:9], v[168:171], v[208:211], v[6:9]
	v_mfma_f32_16x16x32_bf16 v[2:5], v[176:179], v[208:211], v[2:5]
	v_mfma_f32_16x16x32_bf16 v[54:57], v[172:175], v[188:191], v[54:57]
	v_mfma_f32_16x16x32_bf16 v[50:53], v[180:183], v[188:191], v[50:53]
	v_mfma_f32_16x16x32_bf16 v[38:41], v[172:175], v[196:199], v[38:41]
	v_mfma_f32_16x16x32_bf16 v[34:37], v[180:183], v[196:199], v[34:37]
	v_mfma_f32_16x16x32_bf16 v[22:25], v[172:175], v[204:207], v[22:25]
	v_mfma_f32_16x16x32_bf16 v[18:21], v[180:183], v[204:207], v[18:21]
	v_mfma_f32_16x16x32_bf16 v[6:9], v[172:175], v[212:215], v[6:9]
	v_mfma_f32_16x16x32_bf16 v[2:5], v[180:183], v[212:215], v[2:5]
	s_barrier
	s_add_u32 s22, s22, 0x10000
	s_addc_u32 s23, s23, 0
	s_cmp_ge_u32 s57, s44
	s_cbranch_scc0 .LBB0_1229
	s_and_b64 vcc, exec, s[6:7]
	s_cbranch_vccz .LBB0_1232
	s_barrier

; #define PG8_STAGE(bufoff, gbase, voff) do { _Pragma("unroll") for (int _i = 0; _i < 2; ++_i) \
;         __builtin_amdgcn_global_load_lds((const unsigned*)((const char*)(gbase) + (voff)[_i]), (LAS unsigned*)(lds + (bufoff) + ldsw + _i * 8192), 16, 0, 0); } while (0)
; #define PG8_LDA(dst, b, h) do { _Pragma("unroll") for (int m = 0; m < 4; ++m) _Pragma("unroll") for (int k = 0; k < 2; ++k) dst[m][k] = *(const LAS bf16x8*)(lds + PG8_SA(b, h) + aoff + m * 2048 + k * 1024); } while (0)
; #define PG8_LDB(dst, b, h) do { _Pragma("unroll") for (int n = 0; n < 2; ++n) _Pragma("unroll") for (int k = 0; k < 2; ++k) dst[n][k] = *(const LAS bf16x8*)(lds + PG8_SB(b, h) + boff + n * 2048 + k * 1024); } while (0)
; #define PG8_MMA(ai, bj, At, Bt) do { __builtin_amdgcn_s_setprio(1); _Pragma("unroll") for (int m = 0; m < 4; ++m) _Pragma("unroll") for (int n = 0; n < 2; ++n) _Pragma("unroll") for (int k = 0; k < 2; ++k) \
;         acc[ai][bj][m][n] = __builtin_amdgcn_mfma_f32_16x16x32_bf16(Bt[n][k], At[m][k], acc[ai][bj][m][n], 0, 0, 0); __builtin_amdgcn_s_setprio(0); } while (0)
; #define PG8_WAIT_V(n) asm volatile("s_waitcnt vmcnt(" #n ")" ::: "memory")
; template <class Epi, class Sched, bool ABLK = false, bool ALIGN_EPI = true, bool SP2 = true, bool BBLK = true>
; __device__ __forceinline__ void gemm_phase(LAS unsigned char* lds, const Gemm g, const Sched& S, const Epi& E) {
;     ...
;         for (int t = 0; t < nt; t += 2) {
;             const bool last = (t == nt - 2);
;             const char* a1 = a_tile(uA, tbA + t + 1);
;             const char* a2 = last ? a_tile(nuA, ntbA) : a_tile(uA, tbA + t + 2); const char* b2 = last ? nB : cB + (size_t)(t + 2) * kstepB;
;             const char* a3 = last ? a_tile(nuA, ntbA + 1) : a_tile(uA, tbA + t + 3); const char* b3 = b2 + kstepB;
;             if (last && has_next) S.a_ready(nxt);
;             if constexpr (SP2) {
;             PG8_LDB(B0, 0, 0); PG8_LDB(B1, 0, 1); PG8_SCHED; PG8_LDA(At, 0, 0); PG8_STAGE(PG8_SA(1, 1), a1 + hstepA, voffA);
;             PG8_WAIT_V(8); PG8_WAIT_L(0); PG8_BAR; PG8_MMA(0, 0, At, B0); PG8_MMA(0, 1, At, B1); PG8_BAR; PG8_SCHED;
;             PG8_LDA(At, 0, 1); PG8_STAGE(PG8_SB(0, 0), b2, voffB); PG8_STAGE(PG8_SB(0, 1), b2 + hstepB, voffB); PG8_STAGE(PG8_SA(0, 0), a2, voffA);
;             PG8_WAIT_V(8); PG8_WAIT_L(0); PG8_BAR; PG8_MMA(1, 0, At, B0); PG8_MMA(1, 1, At, B1); PG8_BAR; PG8_SCHED;
.LBB0_1355:
	ds_read_b128 v[152:155], v163
	ds_read_b128 v[156:159], v163 offset:1024
	ds_read_b128 v[166:169], v163 offset:2048
	ds_read_b128 v[170:173], v163 offset:3072
	ds_read_b128 v[174:177], v164
	ds_read_b128 v[178:181], v164 offset:1024
	ds_read_b128 v[182:185], v164 offset:2048
	ds_read_b128 v[186:189], v164 offset:3072
	s_add_u32 s42, s36, s40
	s_addc_u32 s43, s37, s41
	s_add_u32 s46, s42, 0x100
	s_addc_u32 s47, s43, 0
	s_add_u32 s42, s42, 0x180
	s_addc_u32 s43, s43, 0
	s_cmpk_eq_i32 s40, 0xf00
	s_cselect_b32 s43, s57, s43
	s_cselect_b32 s42, s56, s42
	s_cselect_b32 s45, s21, s64
	s_cselect_b32 s44, s23, s59
	s_cselect_b32 s47, s4, s47
	s_cselect_b32 s46, s5, s46
	v_lshl_add_u64 v[222:223], v[148:149], 0, s[40:41]
	s_add_i32 m0, s31, 0xc000
	ds_read_b128 v[190:193], v165
	ds_read_b128 v[194:197], v165 offset:1024
	ds_read_b128 v[198:201], v165 offset:2048
	ds_read_b128 v[202:205], v165 offset:3072
	ds_read_b128 v[206:209], v165 offset:4096
	ds_read_b128 v[210:213], v165 offset:5120
	ds_read_b128 v[214:217], v165 offset:6144
	ds_read_b128 v[218:221], v165 offset:7168
	global_load_lds_dwordx4 v[222:223], off
	v_lshl_add_u64 v[222:223], v[150:151], 0, s[40:41]
	s_add_i32 m0, s31, 0xe000
	s_nop 0
	global_load_lds_dwordx4 v[222:223], off
	s_waitcnt vmcnt(8) lgkmcnt(0)
	s_barrier
	v_mfma_f32_16x16x32_bf16 v[126:129], v[152:155], v[190:193], v[126:129]
	v_mfma_f32_16x16x32_bf16 v[122:125], v[166:169], v[190:193], v[122:125]
	v_mfma_f32_16x16x32_bf16 v[110:113], v[152:155], v[198:201], v[110:113]
	v_mfma_f32_16x16x32_bf16 v[106:109], v[166:169], v[198:201], v[106:109]
	v_mfma_f32_16x16x32_bf16 v[94:97], v[152:155], v[206:209], v[94:97]
	v_mfma_f32_16x16x32_bf16 v[90:93], v[166:169], v[206:209], v[90:93]
	v_mfma_f32_16x16x32_bf16 v[78:81], v[152:155], v[214:217], v[78:81]
	v_mfma_f32_16x16x32_bf16 v[74:77], v[166:169], v[214:217], v[74:77]
	v_mfma_f32_16x16x32_bf16 v[126:129], v[156:159], v[194:197], v[126:129]
	v_mfma_f32_16x16x32_bf16 v[122:125], v[170:173], v[194:197], v[122:125]
	v_mfma_f32_16x16x32_bf16 v[110:113], v[156:159], v[202:205], v[110:113]
	v_mfma_f32_16x16x32_bf16 v[106:109], v[170:173], v[202:205], v[106:109]
	v_mfma_f32_16x16x32_bf16 v[94:97], v[156:159], v[210:213], v[94:97]
	v_mfma_f32_16x16x32_bf16 v[90:93], v[170:173], v[210:213], v[90:93]
	v_mfma_f32_16x16x32_bf16 v[78:81], v[156:159], v[218:221], v[78:81]
	v_mfma_f32_16x16x32_bf16 v[74:77], v[170:173], v[218:221], v[74:77]
	v_mfma_f32_16x16x32_bf16 v[118:121], v[174:177], v[190:193], v[118:121]
	v_mfma_f32_16x16x32_bf16 v[114:117], v[182:185], v[190:193], v[114:117]
	v_mfma_f32_16x16x32_bf16 v[102:105], v[174:177], v[198:201], v[102:105]
	v_mfma_f32_16x16x32_bf16 v[98:101], v[182:185], v[198:201], v[98:101]
	v_mfma_f32_16x16x32_bf16 v[86:89], v[174:177], v[206:209], v[86:89]
	v_mfma_f32_16x16x32_bf16 v[82:85], v[182:185], v[206:209], v[82:85]
	v_mfma_f32_16x16x32_bf16 v[70:73], v[174:177], v[214:217], v[70:73]
	v_mfma_f32_16x16x32_bf16 v[66:69], v[182:185], v[214:217], v[66:69]
	v_mfma_f32_16x16x32_bf16 v[118:121], v[178:181], v[194:197], v[118:121]
	v_mfma_f32_16x16x32_bf16 v[114:117], v[186:189], v[194:197], v[114:117]
	v_mfma_f32_16x16x32_bf16 v[102:105], v[178:181], v[202:205], v[102:105]
	v_mfma_f32_16x16x32_bf16 v[98:101], v[186:189], v[202:205], v[98:101]
	v_mfma_f32_16x16x32_bf16 v[86:89], v[178:181], v[210:213], v[86:89]
	v_mfma_f32_16x16x32_bf16 v[82:85], v[186:189], v[210:213], v[82:85]
	v_mfma_f32_16x16x32_bf16 v[70:73], v[178:181], v[218:221], v[70:73]
	v_mfma_f32_16x16x32_bf16 v[66:69], v[186:189], v[218:221], v[66:69]
	s_barrier
	s_add_i32 s66, s72, s49
	s_mov_b32 m0, s66
	ds_read_b128 v[190:193], v165 offset:16384
	ds_read_b128 v[194:197], v165 offset:17408
	ds_read_b128 v[198:201], v165 offset:18432
	ds_read_b128 v[202:205], v165 offset:19456
	ds_read_b128 v[206:209], v165 offset:20480
	ds_read_b128 v[210:213], v165 offset:21504
	ds_read_b128 v[214:217], v165 offset:22528
	ds_read_b128 v[218:221], v165 offset:23552
	global_load_lds_dwordx4 v134, s[44:45]
	s_add_i32 m0, s66, 0x2000
	s_add_u32 s66, s44, 0x4000
	s_addc_u32 s67, s45, 0
	s_add_i32 s75, s73, s49
	global_load_lds_dwordx4 v130, s[44:45]
	s_mov_b32 m0, s75
	s_nop 0
	global_load_lds_dwordx4 v134, s[66:67]
	s_add_i32 m0, s75, 0x2000
	s_nop 0
	global_load_lds_dwordx4 v130, s[66:67]
	s_mov_b32 m0, s31
	s_nop 0
	global_load_lds_dwordx4 v136, s[46:47]
	s_mov_b32 m0, s35
	s_nop 0
	global_load_lds_dwordx4 v132, s[46:47]
	s_waitcnt vmcnt(8) lgkmcnt(0)
	s_barrier
	v_mfma_f32_16x16x32_bf16 v[62:65], v[152:155], v[190:193], v[62:65]
	v_mfma_f32_16x16x32_bf16 v[58:61], v[166:169], v[190:193], v[58:61]
	v_mfma_f32_16x16x32_bf16 v[46:49], v[152:155], v[198:201], v[46:49]
	v_mfma_f32_16x16x32_bf16 v[42:45], v[166:169], v[198:201], v[42:45]
	v_mfma_f32_16x16x32_bf16 v[30:33], v[152:155], v[206:209], v[30:33]
	v_mfma_f32_16x16x32_bf16 v[26:29], v[166:169], v[206:209], v[26:29]
	v_mfma_f32_16x16x32_bf16 v[14:17], v[152:155], v[214:217], v[14:17]
	v_mfma_f32_16x16x32_bf16 v[10:13], v[166:169], v[214:217], v[10:13]
	v_mfma_f32_16x16x32_bf16 v[62:65], v[156:159], v[194:197], v[62:65]
	v_mfma_f32_16x16x32_bf16 v[58:61], v[170:173], v[194:197], v[58:61]
	v_mfma_f32_16x16x32_bf16 v[46:49], v[156:159], v[202:205], v[46:49]
	v_mfma_f32_16x16x32_bf16 v[42:45], v[170:173], v[202:205], v[42:45]
	v_mfma_f32_16x16x32_bf16 v[30:33], v[156:159], v[210:213], v[30:33]
	v_mfma_f32_16x16x32_bf16 v[26:29], v[170:173], v[210:213], v[26:29]
	v_mfma_f32_16x16x32_bf16 v[14:17], v[156:159], v[218:221], v[14:17]
	v_mfma_f32_16x16x32_bf16 v[10:13], v[170:173], v[218:221], v[10:13]
	v_mfma_f32_16x16x32_bf16 v[54:57], v[174:177], v[190:193], v[54:57]
	v_mfma_f32_16x16x32_bf16 v[50:53], v[182:185], v[190:193], v[50:53]
	v_mfma_f32_16x16x32_bf16 v[38:41], v[174:177], v[198:201], v[38:41]
	v_mfma_f32_16x16x32_bf16 v[34:37], v[182:185], v[198:201], v[34:37]
	v_mfma_f32_16x16x32_bf16 v[22:25], v[174:177], v[206:209], v[22:25]
	v_mfma_f32_16x16x32_bf16 v[18:21], v[182:185], v[206:209], v[18:21]
	v_mfma_f32_16x16x32_bf16 v[6:9], v[174:177], v[214:217], v[6:9]
	v_mfma_f32_16x16x32_bf16 v[2:5], v[182:185], v[214:217], v[2:5]
	v_mfma_f32_16x16x32_bf16 v[54:57], v[178:181], v[194:197], v[54:57]
	v_mfma_f32_16x16x32_bf16 v[50:53], v[186:189], v[194:197], v[50:53]
	v_mfma_f32_16x16x32_bf16 v[38:41], v[178:181], v[202:205], v[38:41]
	v_mfma_f32_16x16x32_bf16 v[34:37], v[186:189], v[202:205], v[34:37]
	v_mfma_f32_16x16x32_bf16 v[22:25], v[178:181], v[210:213], v[22:25]
	v_mfma_f32_16x16x32_bf16 v[18:21], v[186:189], v[210:213], v[18:21]
	v_mfma_f32_16x16x32_bf16 v[6:9], v[178:181], v[218:221], v[6:9]
	v_mfma_f32_16x16x32_bf16 v[2:5], v[186:189], v[218:221], v[2:5]
	s_barrier
; #define PG8_STAGE(bufoff, gbase, voff) do { _Pragma("unroll") for (int _i = 0; _i < 2; ++_i) \
;         __builtin_amdgcn_global_load_lds((const unsigned*)((const char*)(gbase) + (voff)[_i]), (LAS unsigned*)(lds + (bufoff) + ldsw + _i * 8192), 16, 0, 0); } while (0)
; #define PG8_LDA(dst, b, h) do { _Pragma("unroll") for (int m = 0; m < 4; ++m) _Pragma("unroll") for (int k = 0; k < 2; ++k) dst[m][k] = *(const LAS bf16x8*)(lds + PG8_SA(b, h) + aoff + m * 2048 + k * 1024); } while (0)
; #define PG8_LDB(dst, b, h) do { _Pragma("unroll") for (int n = 0; n < 2; ++n) _Pragma("unroll") for (int k = 0; k < 2; ++k) dst[n][k] = *(const LAS bf16x8*)(lds + PG8_SB(b, h) + boff + n * 2048 + k * 1024); } while (0)
; #define PG8_MMA(ai, bj, At, Bt) do { __builtin_amdgcn_s_setprio(1); _Pragma("unroll") for (int m = 0; m < 4; ++m) _Pragma("unroll") for (int n = 0; n < 2; ++n) _Pragma("unroll") for (int k = 0; k < 2; ++k) \
;         acc[ai][bj][m][n] = __builtin_amdgcn_mfma_f32_16x16x32_bf16(Bt[n][k], At[m][k], acc[ai][bj][m][n], 0, 0, 0); __builtin_amdgcn_s_setprio(0); } while (0)
; #define PG8_WAIT_V(n) asm volatile("s_waitcnt vmcnt(" #n ")" ::: "memory")
; #define PG8_WAIT_L(n) asm volatile("s_waitcnt lgkmcnt(" #n ")" ::: "memory")
; #define PG8_BAR __builtin_amdgcn_s_barrier()
; #define PG8_SCHED __builtin_amdgcn_sched_barrier(0)
; template <class Epi, class Sched, bool ABLK = false, bool ALIGN_EPI = true, bool SP2 = true, bool BBLK = true>
; __device__ __forceinline__ void gemm_phase(LAS unsigned char* lds, const Gemm g, const Sched& S, const Epi& E) {
;     ...
;         for (int t = 0; t < nt; t += 2) {
;             const bool last = (t == nt - 2);
;     ...
;             PG8_LDB(B0, 1, 0); PG8_LDB(B1, 1, 1); PG8_SCHED; PG8_LDA(At, 1, 0); PG8_STAGE(PG8_SA(0, 1), a2 + hstepA, voffA);
;             PG8_WAIT_V(8); PG8_WAIT_L(0); PG8_BAR; PG8_MMA(0, 0, At, B0); PG8_MMA(0, 1, At, B1); PG8_BAR; PG8_SCHED;
;             PG8_LDA(At, 1, 1); PG8_STAGE(PG8_SB(1, 0), b3, voffB); PG8_STAGE(PG8_SB(1, 1), b3 + hstepB, voffB); PG8_STAGE(PG8_SA(1, 0), a3, voffA);
;             PG8_WAIT_V(8); PG8_WAIT_L(0); PG8_BAR; PG8_MMA(1, 0, At, B0); PG8_MMA(1, 1, At, B1); PG8_BAR; PG8_SCHED;
	v_add_u32_e32 v138, s60, v161
	ds_read_b128 v[152:155], v138
	ds_read_b128 v[156:159], v138 offset:1024
	ds_read_b128 v[166:169], v138 offset:2048
	ds_read_b128 v[170:173], v138 offset:3072
	v_add_u32_e32 v138, s61, v161
	ds_read_b128 v[174:177], v138
	ds_read_b128 v[178:181], v138 offset:1024
	ds_read_b128 v[182:185], v138 offset:2048
	ds_read_b128 v[186:189], v138 offset:3072
	s_add_u32 s46, s46, 0x80000
	s_addc_u32 s47, s47, 0
	s_mov_b32 m0, s50
	ds_read_b128 v[190:193], v165 offset:32768
	ds_read_b128 v[194:197], v165 offset:33792
	ds_read_b128 v[198:201], v165 offset:34816
	ds_read_b128 v[202:205], v165 offset:35840
	ds_read_b128 v[206:209], v165 offset:36864
	ds_read_b128 v[210:213], v165 offset:37888
	ds_read_b128 v[214:217], v165 offset:38912
	ds_read_b128 v[218:221], v165 offset:39936
	global_load_lds_dwordx4 v136, s[46:47]
	s_mov_b32 m0, s51
	s_nop 0
	global_load_lds_dwordx4 v132, s[46:47]
	s_waitcnt vmcnt(8) lgkmcnt(0)
	s_barrier
	v_mfma_f32_16x16x32_bf16 v[126:129], v[152:155], v[190:193], v[126:129]
	v_mfma_f32_16x16x32_bf16 v[122:125], v[166:169], v[190:193], v[122:125]
	v_mfma_f32_16x16x32_bf16 v[110:113], v[152:155], v[198:201], v[110:113]
	v_mfma_f32_16x16x32_bf16 v[106:109], v[166:169], v[198:201], v[106:109]
	v_mfma_f32_16x16x32_bf16 v[94:97], v[152:155], v[206:209], v[94:97]
	v_mfma_f32_16x16x32_bf16 v[90:93], v[166:169], v[206:209], v[90:93]
	v_mfma_f32_16x16x32_bf16 v[78:81], v[152:155], v[214:217], v[78:81]
	v_mfma_f32_16x16x32_bf16 v[74:77], v[166:169], v[214:217], v[74:77]
	v_mfma_f32_16x16x32_bf16 v[126:129], v[156:159], v[194:197], v[126:129]
	v_mfma_f32_16x16x32_bf16 v[122:125], v[170:173], v[194:197], v[122:125]
	v_mfma_f32_16x16x32_bf16 v[110:113], v[156:159], v[202:205], v[110:113]
	v_mfma_f32_16x16x32_bf16 v[106:109], v[170:173], v[202:205], v[106:109]
	v_mfma_f32_16x16x32_bf16 v[94:97], v[156:159], v[210:213], v[94:97]
	v_mfma_f32_16x16x32_bf16 v[90:93], v[170:173], v[210:213], v[90:93]
	v_mfma_f32_16x16x32_bf16 v[78:81], v[156:159], v[218:221], v[78:81]
	v_mfma_f32_16x16x32_bf16 v[74:77], v[170:173], v[218:221], v[74:77]
	v_mfma_f32_16x16x32_bf16 v[118:121], v[174:177], v[190:193], v[118:121]
	v_mfma_f32_16x16x32_bf16 v[114:117], v[182:185], v[190:193], v[114:117]
	v_mfma_f32_16x16x32_bf16 v[102:105], v[174:177], v[198:201], v[102:105]
	v_mfma_f32_16x16x32_bf16 v[98:101], v[182:185], v[198:201], v[98:101]
	v_mfma_f32_16x16x32_bf16 v[86:89], v[174:177], v[206:209], v[86:89]
	v_mfma_f32_16x16x32_bf16 v[82:85], v[182:185], v[206:209], v[82:85]
	v_mfma_f32_16x16x32_bf16 v[70:73], v[174:177], v[214:217], v[70:73]
	v_mfma_f32_16x16x32_bf16 v[66:69], v[182:185], v[214:217], v[66:69]
	v_mfma_f32_16x16x32_bf16 v[118:121], v[178:181], v[194:197], v[118:121]
	v_mfma_f32_16x16x32_bf16 v[114:117], v[186:189], v[194:197], v[114:117]
	v_mfma_f32_16x16x32_bf16 v[102:105], v[178:181], v[202:205], v[102:105]
	v_mfma_f32_16x16x32_bf16 v[98:101], v[186:189], v[202:205], v[98:101]
	v_mfma_f32_16x16x32_bf16 v[86:89], v[178:181], v[210:213], v[86:89]
	v_mfma_f32_16x16x32_bf16 v[82:85], v[186:189], v[210:213], v[82:85]
	v_mfma_f32_16x16x32_bf16 v[70:73], v[178:181], v[218:221], v[70:73]
	v_mfma_f32_16x16x32_bf16 v[66:69], v[186:189], v[218:221], v[66:69]
	s_barrier
	s_add_u32 s46, s44, 0x8000
	s_addc_u32 s47, s45, 0
	s_add_i32 s66, s60, s49
	s_mov_b32 m0, s66
	ds_read_b128 v[190:193], v165 offset:49152
	ds_read_b128 v[194:197], v165 offset:50176
	ds_read_b128 v[198:201], v165 offset:51200
	ds_read_b128 v[202:205], v165 offset:52224
	ds_read_b128 v[206:209], v165 offset:53248
	ds_read_b128 v[210:213], v165 offset:54272
	ds_read_b128 v[214:217], v165 offset:55296
	ds_read_b128 v[218:221], v165 offset:56320
	global_load_lds_dwordx4 v134, s[46:47]
	s_add_i32 m0, s66, 0x2000
	s_add_u32 s44, s44, 0xc000
	v_lshl_add_u64 v[222:223], s[46:47], 0, v[130:131]
	s_addc_u32 s45, s45, 0
	s_add_i32 s46, s61, s49
	global_load_lds_dwordx4 v[222:223], off
	s_mov_b32 m0, s46
	s_nop 0
	global_load_lds_dwordx4 v134, s[44:45]
	s_add_i32 m0, s46, 0x2000
	s_nop 0
	global_load_lds_dwordx4 v130, s[44:45]
	s_mov_b32 m0, s54
	s_nop 0
	global_load_lds_dwordx4 v136, s[42:43]
	s_mov_b32 m0, s55
	s_nop 0
	global_load_lds_dwordx4 v132, s[42:43]
	s_waitcnt vmcnt(8) lgkmcnt(0)
	s_barrier
	v_mfma_f32_16x16x32_bf16 v[62:65], v[152:155], v[190:193], v[62:65]
	v_mfma_f32_16x16x32_bf16 v[58:61], v[166:169], v[190:193], v[58:61]
	v_mfma_f32_16x16x32_bf16 v[46:49], v[152:155], v[198:201], v[46:49]
	v_mfma_f32_16x16x32_bf16 v[42:45], v[166:169], v[198:201], v[42:45]
	v_mfma_f32_16x16x32_bf16 v[30:33], v[152:155], v[206:209], v[30:33]
	v_mfma_f32_16x16x32_bf16 v[26:29], v[166:169], v[206:209], v[26:29]
	v_mfma_f32_16x16x32_bf16 v[14:17], v[152:155], v[214:217], v[14:17]
	v_mfma_f32_16x16x32_bf16 v[10:13], v[166:169], v[214:217], v[10:13]
	v_mfma_f32_16x16x32_bf16 v[62:65], v[156:159], v[194:197], v[62:65]
	v_mfma_f32_16x16x32_bf16 v[58:61], v[170:173], v[194:197], v[58:61]
	v_mfma_f32_16x16x32_bf16 v[46:49], v[156:159], v[202:205], v[46:49]
	v_mfma_f32_16x16x32_bf16 v[42:45], v[170:173], v[202:205], v[42:45]
	v_mfma_f32_16x16x32_bf16 v[30:33], v[156:159], v[210:213], v[30:33]
	v_mfma_f32_16x16x32_bf16 v[26:29], v[170:173], v[210:213], v[26:29]
	v_mfma_f32_16x16x32_bf16 v[14:17], v[156:159], v[218:221], v[14:17]
	v_mfma_f32_16x16x32_bf16 v[10:13], v[170:173], v[218:221], v[10:13]
	v_mfma_f32_16x16x32_bf16 v[54:57], v[174:177], v[190:193], v[54:57]
	v_mfma_f32_16x16x32_bf16 v[50:53], v[182:185], v[190:193], v[50:53]
	v_mfma_f32_16x16x32_bf16 v[38:41], v[174:177], v[198:201], v[38:41]
	v_mfma_f32_16x16x32_bf16 v[34:37], v[182:185], v[198:201], v[34:37]
	v_mfma_f32_16x16x32_bf16 v[22:25], v[174:177], v[206:209], v[22:25]
	v_mfma_f32_16x16x32_bf16 v[18:21], v[182:185], v[206:209], v[18:21]
	v_mfma_f32_16x16x32_bf16 v[6:9], v[174:177], v[214:217], v[6:9]
	v_mfma_f32_16x16x32_bf16 v[2:5], v[182:185], v[214:217], v[2:5]
	v_mfma_f32_16x16x32_bf16 v[54:57], v[178:181], v[194:197], v[54:57]
	v_mfma_f32_16x16x32_bf16 v[50:53], v[186:189], v[194:197], v[50:53]
	v_mfma_f32_16x16x32_bf16 v[38:41], v[178:181], v[202:205], v[38:41]
	v_mfma_f32_16x16x32_bf16 v[34:37], v[186:189], v[202:205], v[34:37]
	v_mfma_f32_16x16x32_bf16 v[22:25], v[178:181], v[210:213], v[22:25]
	v_mfma_f32_16x16x32_bf16 v[18:21], v[186:189], v[210:213], v[18:21]
	v_mfma_f32_16x16x32_bf16 v[6:9], v[178:181], v[218:221], v[6:9]
	v_mfma_f32_16x16x32_bf16 v[2:5], v[186:189], v[218:221], v[2:5]
	s_barrier
	s_add_i32 s65, s65, 2
	s_add_u32 s40, s40, 0x100
	s_addc_u32 s41, s41, 0
	s_add_u32 s59, s59, 0x10000
	s_addc_u32 s64, s64, 0
	s_cmp_gt_u32 s65, 29
	s_cbranch_scc0 .LBB0_1355
	s_and_b64 vcc, exec, s[12:13]
	s_cbranch_vccz .LBB0_1358
	s_barrier

; #define PG8_STAGE(bufoff, gbase, voff) do { _Pragma("unroll") for (int _i = 0; _i < 2; ++_i) \
;         __builtin_amdgcn_global_load_lds((const unsigned*)((const char*)(gbase) + (voff)[_i]), (LAS unsigned*)(lds + (bufoff) + ldsw + _i * 8192), 16, 0, 0); } while (0)
; #define PG8_LDA(dst, b, h) do { _Pragma("unroll") for (int m = 0; m < 4; ++m) _Pragma("unroll") for (int k = 0; k < 2; ++k) dst[m][k] = *(const LAS bf16x8*)(lds + PG8_SA(b, h) + aoff + m * 2048 + k * 1024); } while (0)
; #define PG8_LDB(dst, b, h) do { _Pragma("unroll") for (int n = 0; n < 2; ++n) _Pragma("unroll") for (int k = 0; k < 2; ++k) dst[n][k] = *(const LAS bf16x8*)(lds + PG8_SB(b, h) + boff + n * 2048 + k * 1024); } while (0)
; #define PG8_MMA(ai, bj, At, Bt) do { __builtin_amdgcn_s_setprio(1); _Pragma("unroll") for (int m = 0; m < 4; ++m) _Pragma("unroll") for (int n = 0; n < 2; ++n) _Pragma("unroll") for (int k = 0; k < 2; ++k) \
;         acc[ai][bj][m][n] = __builtin_amdgcn_mfma_f32_16x16x32_bf16(Bt[n][k], At[m][k], acc[ai][bj][m][n], 0, 0, 0); __builtin_amdgcn_s_setprio(0); } while (0)
; #define PG8_WAIT_V(n) asm volatile("s_waitcnt vmcnt(" #n ")" ::: "memory")
; template <class Epi, class Sched, bool ABLK = false, bool ALIGN_EPI = true, bool SP2 = true, bool BBLK = true>
; __device__ __forceinline__ void gemm_phase(LAS unsigned char* lds, const Gemm g, const Sched& S, const Epi& E) {
;     ...
;         for (int t = 0; t < nt; t += 2) {
;             const bool last = (t == nt - 2);
;             const char* a1 = a_tile(uA, tbA + t + 1);
;             const char* a2 = last ? a_tile(nuA, ntbA) : a_tile(uA, tbA + t + 2); const char* b2 = last ? nB : cB + (size_t)(t + 2) * kstepB;
;             const char* a3 = last ? a_tile(nuA, ntbA + 1) : a_tile(uA, tbA + t + 3); const char* b3 = b2 + kstepB;
;             if (last && has_next) S.a_ready(nxt);
;             if constexpr (SP2) {
;             PG8_LDB(B0, 0, 0); PG8_LDB(B1, 0, 1); PG8_SCHED; PG8_LDA(At, 0, 0); PG8_STAGE(PG8_SA(1, 1), a1 + hstepA, voffA);
;             PG8_WAIT_V(8); PG8_WAIT_L(0); PG8_BAR; PG8_MMA(0, 0, At, B0); PG8_MMA(0, 1, At, B1); PG8_BAR; PG8_SCHED;
;             PG8_LDA(At, 0, 1); PG8_STAGE(PG8_SB(0, 0), b2, voffB); PG8_STAGE(PG8_SB(0, 1), b2 + hstepB, voffB); PG8_STAGE(PG8_SA(0, 0), a2, voffA);
;             PG8_WAIT_V(8); PG8_WAIT_L(0); PG8_BAR; PG8_MMA(1, 0, At, B0); PG8_MMA(1, 1, At, B1); PG8_BAR; PG8_SCHED;
.LBB0_1716:
	ds_read_b128 v[156:159], v152
	ds_read_b128 v[160:163], v152 offset:1024
	ds_read_b128 v[164:167], v152 offset:2048
	ds_read_b128 v[168:171], v152 offset:3072
	ds_read_b128 v[172:175], v153
	ds_read_b128 v[176:179], v153 offset:1024
	ds_read_b128 v[180:183], v153 offset:2048
	ds_read_b128 v[184:187], v153 offset:3072
	s_add_u32 s28, s54, s26
	s_addc_u32 s29, s55, s27
	s_add_u32 s34, s28, 0x100
	s_addc_u32 s35, s29, 0
	s_add_i32 s57, s57, 2
	s_add_u32 s28, s28, 0x180
	s_addc_u32 s29, s29, 0
	s_cmp_eq_u32 s56, s26
	s_cselect_b32 s29, s51, s29
	s_cselect_b32 s28, s50, s28
	s_cselect_b32 s31, s4, s53
	s_cselect_b32 s30, s5, s52
	s_cselect_b32 s35, s49, s35
	s_cselect_b32 s34, s23, s34
	v_lshl_add_u64 v[220:221], v[146:147], 0, s[26:27]
	s_add_i32 m0, s40, 0xc000
	ds_read_b128 v[188:191], v154
	ds_read_b128 v[192:195], v154 offset:1024
	ds_read_b128 v[196:199], v154 offset:2048
	ds_read_b128 v[200:203], v154 offset:3072
	ds_read_b128 v[204:207], v154 offset:4096
	ds_read_b128 v[208:211], v154 offset:5120
	ds_read_b128 v[212:215], v154 offset:6144
	ds_read_b128 v[216:219], v154 offset:7168
	global_load_lds_dwordx4 v[220:221], off
	v_lshl_add_u64 v[220:221], v[148:149], 0, s[26:27]
	s_add_i32 m0, s40, 0xe000
	s_nop 0
	global_load_lds_dwordx4 v[220:221], off
	s_waitcnt vmcnt(8) lgkmcnt(0)
	s_barrier
	v_mfma_f32_16x16x32_bf16 v[126:129], v[156:159], v[188:191], v[126:129]
	v_mfma_f32_16x16x32_bf16 v[122:125], v[164:167], v[188:191], v[122:125]
	v_mfma_f32_16x16x32_bf16 v[110:113], v[156:159], v[196:199], v[110:113]
	v_mfma_f32_16x16x32_bf16 v[106:109], v[164:167], v[196:199], v[106:109]
	v_mfma_f32_16x16x32_bf16 v[94:97], v[156:159], v[204:207], v[94:97]
	v_mfma_f32_16x16x32_bf16 v[90:93], v[164:167], v[204:207], v[90:93]
	v_mfma_f32_16x16x32_bf16 v[78:81], v[156:159], v[212:215], v[78:81]
	v_mfma_f32_16x16x32_bf16 v[74:77], v[164:167], v[212:215], v[74:77]
	v_mfma_f32_16x16x32_bf16 v[126:129], v[160:163], v[192:195], v[126:129]
	v_mfma_f32_16x16x32_bf16 v[122:125], v[168:171], v[192:195], v[122:125]
	v_mfma_f32_16x16x32_bf16 v[110:113], v[160:163], v[200:203], v[110:113]
	v_mfma_f32_16x16x32_bf16 v[106:109], v[168:171], v[200:203], v[106:109]
	v_mfma_f32_16x16x32_bf16 v[94:97], v[160:163], v[208:211], v[94:97]
	v_mfma_f32_16x16x32_bf16 v[90:93], v[168:171], v[208:211], v[90:93]
	v_mfma_f32_16x16x32_bf16 v[78:81], v[160:163], v[216:219], v[78:81]
	v_mfma_f32_16x16x32_bf16 v[74:77], v[168:171], v[216:219], v[74:77]
	v_mfma_f32_16x16x32_bf16 v[118:121], v[172:175], v[188:191], v[118:121]
	v_mfma_f32_16x16x32_bf16 v[114:117], v[180:183], v[188:191], v[114:117]
	v_mfma_f32_16x16x32_bf16 v[102:105], v[172:175], v[196:199], v[102:105]
	v_mfma_f32_16x16x32_bf16 v[98:101], v[180:183], v[196:199], v[98:101]
	v_mfma_f32_16x16x32_bf16 v[86:89], v[172:175], v[204:207], v[86:89]
	v_mfma_f32_16x16x32_bf16 v[82:85], v[180:183], v[204:207], v[82:85]
	v_mfma_f32_16x16x32_bf16 v[70:73], v[172:175], v[212:215], v[70:73]
	v_mfma_f32_16x16x32_bf16 v[66:69], v[180:183], v[212:215], v[66:69]
	v_mfma_f32_16x16x32_bf16 v[118:121], v[176:179], v[192:195], v[118:121]
	v_mfma_f32_16x16x32_bf16 v[114:117], v[184:187], v[192:195], v[114:117]
	v_mfma_f32_16x16x32_bf16 v[102:105], v[176:179], v[200:203], v[102:105]
	v_mfma_f32_16x16x32_bf16 v[98:101], v[184:187], v[200:203], v[98:101]
	v_mfma_f32_16x16x32_bf16 v[86:89], v[176:179], v[208:211], v[86:89]
	v_mfma_f32_16x16x32_bf16 v[82:85], v[184:187], v[208:211], v[82:85]
	v_mfma_f32_16x16x32_bf16 v[70:73], v[176:179], v[216:219], v[70:73]
	v_mfma_f32_16x16x32_bf16 v[66:69], v[184:187], v[216:219], v[66:69]
	s_barrier
	s_add_i32 s58, s72, s39
	s_mov_b32 m0, s58
	ds_read_b128 v[188:191], v154 offset:16384
	ds_read_b128 v[192:195], v154 offset:17408
	ds_read_b128 v[196:199], v154 offset:18432
	ds_read_b128 v[200:203], v154 offset:19456
	ds_read_b128 v[204:207], v154 offset:20480
	ds_read_b128 v[208:211], v154 offset:21504
	ds_read_b128 v[212:215], v154 offset:22528
	ds_read_b128 v[216:219], v154 offset:23552
	global_load_lds_dwordx4 v132, s[30:31]
	s_add_i32 m0, s58, 0x2000
	s_add_u32 s58, s30, 0x4000
	s_addc_u32 s59, s31, 0
	s_add_i32 s64, s73, s39
	global_load_lds_dwordx4 v136, s[30:31]
	s_mov_b32 m0, s64
	s_nop 0
	global_load_lds_dwordx4 v132, s[58:59]
	s_add_i32 m0, s64, 0x2000
	s_nop 0
	global_load_lds_dwordx4 v136, s[58:59]
	s_mov_b32 m0, s40
	s_nop 0
	global_load_lds_dwordx4 v130, s[34:35]
	s_mov_b32 m0, s41
	s_nop 0
	global_load_lds_dwordx4 v134, s[34:35]
	s_waitcnt vmcnt(8) lgkmcnt(0)
	s_barrier
	v_mfma_f32_16x16x32_bf16 v[62:65], v[156:159], v[188:191], v[62:65]
	v_mfma_f32_16x16x32_bf16 v[58:61], v[164:167], v[188:191], v[58:61]
	v_mfma_f32_16x16x32_bf16 v[46:49], v[156:159], v[196:199], v[46:49]
	v_mfma_f32_16x16x32_bf16 v[42:45], v[164:167], v[196:199], v[42:45]
	v_mfma_f32_16x16x32_bf16 v[30:33], v[156:159], v[204:207], v[30:33]
	v_mfma_f32_16x16x32_bf16 v[26:29], v[164:167], v[204:207], v[26:29]
	v_mfma_f32_16x16x32_bf16 v[14:17], v[156:159], v[212:215], v[14:17]
	v_mfma_f32_16x16x32_bf16 v[10:13], v[164:167], v[212:215], v[10:13]
	v_mfma_f32_16x16x32_bf16 v[62:65], v[160:163], v[192:195], v[62:65]
	v_mfma_f32_16x16x32_bf16 v[58:61], v[168:171], v[192:195], v[58:61]
	v_mfma_f32_16x16x32_bf16 v[46:49], v[160:163], v[200:203], v[46:49]
	v_mfma_f32_16x16x32_bf16 v[42:45], v[168:171], v[200:203], v[42:45]
	v_mfma_f32_16x16x32_bf16 v[30:33], v[160:163], v[208:211], v[30:33]
	v_mfma_f32_16x16x32_bf16 v[26:29], v[168:171], v[208:211], v[26:29]
	v_mfma_f32_16x16x32_bf16 v[14:17], v[160:163], v[216:219], v[14:17]
	v_mfma_f32_16x16x32_bf16 v[10:13], v[168:171], v[216:219], v[10:13]
	v_mfma_f32_16x16x32_bf16 v[54:57], v[172:175], v[188:191], v[54:57]
	v_mfma_f32_16x16x32_bf16 v[50:53], v[180:183], v[188:191], v[50:53]
	v_mfma_f32_16x16x32_bf16 v[38:41], v[172:175], v[196:199], v[38:41]
	v_mfma_f32_16x16x32_bf16 v[34:37], v[180:183], v[196:199], v[34:37]
	v_mfma_f32_16x16x32_bf16 v[22:25], v[172:175], v[204:207], v[22:25]
	v_mfma_f32_16x16x32_bf16 v[18:21], v[180:183], v[204:207], v[18:21]
	v_mfma_f32_16x16x32_bf16 v[6:9], v[172:175], v[212:215], v[6:9]
	v_mfma_f32_16x16x32_bf16 v[2:5], v[180:183], v[212:215], v[2:5]
	v_mfma_f32_16x16x32_bf16 v[54:57], v[176:179], v[192:195], v[54:57]
	v_mfma_f32_16x16x32_bf16 v[50:53], v[184:187], v[192:195], v[50:53]
	v_mfma_f32_16x16x32_bf16 v[38:41], v[176:179], v[200:203], v[38:41]
	v_mfma_f32_16x16x32_bf16 v[34:37], v[184:187], v[200:203], v[34:37]
	v_mfma_f32_16x16x32_bf16 v[22:25], v[176:179], v[208:211], v[22:25]
	v_mfma_f32_16x16x32_bf16 v[18:21], v[184:187], v[208:211], v[18:21]
	v_mfma_f32_16x16x32_bf16 v[6:9], v[176:179], v[216:219], v[6:9]
	v_mfma_f32_16x16x32_bf16 v[2:5], v[184:187], v[216:219], v[2:5]
	s_barrier
; #define PG8_STAGE(bufoff, gbase, voff) do { _Pragma("unroll") for (int _i = 0; _i < 2; ++_i) \
;         __builtin_amdgcn_global_load_lds((const unsigned*)((const char*)(gbase) + (voff)[_i]), (LAS unsigned*)(lds + (bufoff) + ldsw + _i * 8192), 16, 0, 0); } while (0)
; #define PG8_LDA(dst, b, h) do { _Pragma("unroll") for (int m = 0; m < 4; ++m) _Pragma("unroll") for (int k = 0; k < 2; ++k) dst[m][k] = *(const LAS bf16x8*)(lds + PG8_SA(b, h) + aoff + m * 2048 + k * 1024); } while (0)
; #define PG8_LDB(dst, b, h) do { _Pragma("unroll") for (int n = 0; n < 2; ++n) _Pragma("unroll") for (int k = 0; k < 2; ++k) dst[n][k] = *(const LAS bf16x8*)(lds + PG8_SB(b, h) + boff + n * 2048 + k * 1024); } while (0)
; #define PG8_MMA(ai, bj, At, Bt) do { __builtin_amdgcn_s_setprio(1); _Pragma("unroll") for (int m = 0; m < 4; ++m) _Pragma("unroll") for (int n = 0; n < 2; ++n) _Pragma("unroll") for (int k = 0; k < 2; ++k) \
;         acc[ai][bj][m][n] = __builtin_amdgcn_mfma_f32_16x16x32_bf16(Bt[n][k], At[m][k], acc[ai][bj][m][n], 0, 0, 0); __builtin_amdgcn_s_setprio(0); } while (0)
; #define PG8_WAIT_V(n) asm volatile("s_waitcnt vmcnt(" #n ")" ::: "memory")
; #define PG8_WAIT_L(n) asm volatile("s_waitcnt lgkmcnt(" #n ")" ::: "memory")
; #define PG8_BAR __builtin_amdgcn_s_barrier()
; #define PG8_SCHED __builtin_amdgcn_sched_barrier(0)
; template <class Epi, class Sched, bool ABLK = false, bool ALIGN_EPI = true, bool SP2 = true, bool BBLK = true>
; __device__ __forceinline__ void gemm_phase(LAS unsigned char* lds, const Gemm g, const Sched& S, const Epi& E) {
;     ...
;         for (int t = 0; t < nt; t += 2) {
;             const bool last = (t == nt - 2);
;     ...
;             PG8_LDB(B0, 1, 0); PG8_LDB(B1, 1, 1); PG8_SCHED; PG8_LDA(At, 1, 0); PG8_STAGE(PG8_SA(0, 1), a2 + hstepA, voffA);
;             PG8_WAIT_V(8); PG8_WAIT_L(0); PG8_BAR; PG8_MMA(0, 0, At, B0); PG8_MMA(0, 1, At, B1); PG8_BAR; PG8_SCHED;
;             PG8_LDA(At, 1, 1); PG8_STAGE(PG8_SB(1, 0), b3, voffB); PG8_STAGE(PG8_SB(1, 1), b3 + hstepB, voffB); PG8_STAGE(PG8_SA(1, 0), a3, voffA);
;             PG8_WAIT_V(8); PG8_WAIT_L(0); PG8_BAR; PG8_MMA(1, 0, At, B0); PG8_MMA(1, 1, At, B1); PG8_BAR; PG8_SCHED;
	v_add_u32_e32 v155, s60, v150
	ds_read_b128 v[156:159], v155
	ds_read_b128 v[160:163], v155 offset:1024
	ds_read_b128 v[164:167], v155 offset:2048
	ds_read_b128 v[168:171], v155 offset:3072
	v_add_u32_e32 v155, s61, v150
	ds_read_b128 v[172:175], v155
	ds_read_b128 v[176:179], v155 offset:1024
	ds_read_b128 v[180:183], v155 offset:2048
	ds_read_b128 v[184:187], v155 offset:3072
	s_add_u32 s34, s34, 0x80000
	s_addc_u32 s35, s35, 0
	s_mov_b32 m0, s42
	ds_read_b128 v[188:191], v154 offset:32768
	ds_read_b128 v[192:195], v154 offset:33792
	ds_read_b128 v[196:199], v154 offset:34816
	ds_read_b128 v[200:203], v154 offset:35840
	ds_read_b128 v[204:207], v154 offset:36864
	ds_read_b128 v[208:211], v154 offset:37888
	ds_read_b128 v[212:215], v154 offset:38912
	ds_read_b128 v[216:219], v154 offset:39936
	global_load_lds_dwordx4 v130, s[34:35]
	s_mov_b32 m0, s43
	s_nop 0
	global_load_lds_dwordx4 v134, s[34:35]
	s_waitcnt vmcnt(8) lgkmcnt(0)
	s_barrier
	v_mfma_f32_16x16x32_bf16 v[126:129], v[156:159], v[188:191], v[126:129]
	v_mfma_f32_16x16x32_bf16 v[122:125], v[164:167], v[188:191], v[122:125]
	v_mfma_f32_16x16x32_bf16 v[110:113], v[156:159], v[196:199], v[110:113]
	v_mfma_f32_16x16x32_bf16 v[106:109], v[164:167], v[196:199], v[106:109]
	v_mfma_f32_16x16x32_bf16 v[94:97], v[156:159], v[204:207], v[94:97]
	v_mfma_f32_16x16x32_bf16 v[90:93], v[164:167], v[204:207], v[90:93]
	v_mfma_f32_16x16x32_bf16 v[78:81], v[156:159], v[212:215], v[78:81]
	v_mfma_f32_16x16x32_bf16 v[74:77], v[164:167], v[212:215], v[74:77]
	v_mfma_f32_16x16x32_bf16 v[126:129], v[160:163], v[192:195], v[126:129]
	v_mfma_f32_16x16x32_bf16 v[122:125], v[168:171], v[192:195], v[122:125]
	v_mfma_f32_16x16x32_bf16 v[110:113], v[160:163], v[200:203], v[110:113]
	v_mfma_f32_16x16x32_bf16 v[106:109], v[168:171], v[200:203], v[106:109]
	v_mfma_f32_16x16x32_bf16 v[94:97], v[160:163], v[208:211], v[94:97]
	v_mfma_f32_16x16x32_bf16 v[90:93], v[168:171], v[208:211], v[90:93]
	v_mfma_f32_16x16x32_bf16 v[78:81], v[160:163], v[216:219], v[78:81]
	v_mfma_f32_16x16x32_bf16 v[74:77], v[168:171], v[216:219], v[74:77]
	v_mfma_f32_16x16x32_bf16 v[118:121], v[172:175], v[188:191], v[118:121]
	v_mfma_f32_16x16x32_bf16 v[114:117], v[180:183], v[188:191], v[114:117]
	v_mfma_f32_16x16x32_bf16 v[102:105], v[172:175], v[196:199], v[102:105]
	v_mfma_f32_16x16x32_bf16 v[98:101], v[180:183], v[196:199], v[98:101]
	v_mfma_f32_16x16x32_bf16 v[86:89], v[172:175], v[204:207], v[86:89]
	v_mfma_f32_16x16x32_bf16 v[82:85], v[180:183], v[204:207], v[82:85]
	v_mfma_f32_16x16x32_bf16 v[70:73], v[172:175], v[212:215], v[70:73]
	v_mfma_f32_16x16x32_bf16 v[66:69], v[180:183], v[212:215], v[66:69]
	v_mfma_f32_16x16x32_bf16 v[118:121], v[176:179], v[192:195], v[118:121]
	v_mfma_f32_16x16x32_bf16 v[114:117], v[184:187], v[192:195], v[114:117]
	v_mfma_f32_16x16x32_bf16 v[102:105], v[176:179], v[200:203], v[102:105]
	v_mfma_f32_16x16x32_bf16 v[98:101], v[184:187], v[200:203], v[98:101]
	v_mfma_f32_16x16x32_bf16 v[86:89], v[176:179], v[208:211], v[86:89]
	v_mfma_f32_16x16x32_bf16 v[82:85], v[184:187], v[208:211], v[82:85]
	v_mfma_f32_16x16x32_bf16 v[70:73], v[176:179], v[216:219], v[70:73]
	v_mfma_f32_16x16x32_bf16 v[66:69], v[184:187], v[216:219], v[66:69]
	s_barrier
	s_add_u32 s34, s30, 0x8000
	s_addc_u32 s35, s31, 0
	s_add_i32 s58, s60, s39
	s_mov_b32 m0, s58
	ds_read_b128 v[188:191], v154 offset:49152
	ds_read_b128 v[192:195], v154 offset:50176
	ds_read_b128 v[196:199], v154 offset:51200
	ds_read_b128 v[200:203], v154 offset:52224
	ds_read_b128 v[204:207], v154 offset:53248
	ds_read_b128 v[208:211], v154 offset:54272
	ds_read_b128 v[212:215], v154 offset:55296
	ds_read_b128 v[216:219], v154 offset:56320
	global_load_lds_dwordx4 v132, s[34:35]
	s_add_i32 m0, s58, 0x2000
	s_add_u32 s30, s30, 0xc000
	v_lshl_add_u64 v[220:221], s[34:35], 0, v[136:137]
	s_addc_u32 s31, s31, 0
	s_add_i32 s34, s61, s39
	global_load_lds_dwordx4 v[220:221], off
	s_mov_b32 m0, s34
	s_nop 0
	global_load_lds_dwordx4 v132, s[30:31]
	s_add_i32 m0, s34, 0x2000
	s_nop 0
	global_load_lds_dwordx4 v136, s[30:31]
	s_mov_b32 m0, s44
	s_nop 0
	global_load_lds_dwordx4 v130, s[28:29]
	s_mov_b32 m0, s45
	s_nop 0
	global_load_lds_dwordx4 v134, s[28:29]
	s_waitcnt vmcnt(8) lgkmcnt(0)
	s_barrier
	v_mfma_f32_16x16x32_bf16 v[62:65], v[156:159], v[188:191], v[62:65]
	v_mfma_f32_16x16x32_bf16 v[58:61], v[164:167], v[188:191], v[58:61]
	v_mfma_f32_16x16x32_bf16 v[46:49], v[156:159], v[196:199], v[46:49]
	v_mfma_f32_16x16x32_bf16 v[42:45], v[164:167], v[196:199], v[42:45]
	v_mfma_f32_16x16x32_bf16 v[30:33], v[156:159], v[204:207], v[30:33]
	v_mfma_f32_16x16x32_bf16 v[26:29], v[164:167], v[204:207], v[26:29]
	v_mfma_f32_16x16x32_bf16 v[14:17], v[156:159], v[212:215], v[14:17]
	v_mfma_f32_16x16x32_bf16 v[10:13], v[164:167], v[212:215], v[10:13]
	v_mfma_f32_16x16x32_bf16 v[62:65], v[160:163], v[192:195], v[62:65]
	v_mfma_f32_16x16x32_bf16 v[58:61], v[168:171], v[192:195], v[58:61]
	v_mfma_f32_16x16x32_bf16 v[46:49], v[160:163], v[200:203], v[46:49]
	v_mfma_f32_16x16x32_bf16 v[42:45], v[168:171], v[200:203], v[42:45]
	v_mfma_f32_16x16x32_bf16 v[30:33], v[160:163], v[208:211], v[30:33]
	v_mfma_f32_16x16x32_bf16 v[26:29], v[168:171], v[208:211], v[26:29]
	v_mfma_f32_16x16x32_bf16 v[14:17], v[160:163], v[216:219], v[14:17]
	v_mfma_f32_16x16x32_bf16 v[10:13], v[168:171], v[216:219], v[10:13]
	v_mfma_f32_16x16x32_bf16 v[54:57], v[172:175], v[188:191], v[54:57]
	v_mfma_f32_16x16x32_bf16 v[50:53], v[180:183], v[188:191], v[50:53]
	v_mfma_f32_16x16x32_bf16 v[38:41], v[172:175], v[196:199], v[38:41]
	v_mfma_f32_16x16x32_bf16 v[34:37], v[180:183], v[196:199], v[34:37]
	v_mfma_f32_16x16x32_bf16 v[22:25], v[172:175], v[204:207], v[22:25]
	v_mfma_f32_16x16x32_bf16 v[18:21], v[180:183], v[204:207], v[18:21]
	v_mfma_f32_16x16x32_bf16 v[6:9], v[172:175], v[212:215], v[6:9]
	v_mfma_f32_16x16x32_bf16 v[2:5], v[180:183], v[212:215], v[2:5]
	v_mfma_f32_16x16x32_bf16 v[54:57], v[176:179], v[192:195], v[54:57]
	v_mfma_f32_16x16x32_bf16 v[50:53], v[184:187], v[192:195], v[50:53]
	v_mfma_f32_16x16x32_bf16 v[38:41], v[176:179], v[200:203], v[38:41]
	v_mfma_f32_16x16x32_bf16 v[34:37], v[184:187], v[200:203], v[34:37]
	v_mfma_f32_16x16x32_bf16 v[22:25], v[176:179], v[208:211], v[22:25]
	v_mfma_f32_16x16x32_bf16 v[18:21], v[184:187], v[208:211], v[18:21]
	v_mfma_f32_16x16x32_bf16 v[6:9], v[176:179], v[216:219], v[6:9]
	v_mfma_f32_16x16x32_bf16 v[2:5], v[184:187], v[216:219], v[2:5]
	s_barrier
	s_add_u32 s52, s52, 0x10000
	s_addc_u32 s53, s53, 0
	s_add_u32 s26, s26, 0x100
	s_addc_u32 s27, s27, 0
	s_cmp_ge_u32 s57, s47
	s_cbranch_scc0 .LBB0_1716
	s_and_b64 vcc, exec, s[6:7]
	s_cbranch_vccz .LBB0_1719
	s_barrier

; #define PG8_STAGE(bufoff, gbase, voff) do { _Pragma("unroll") for (int _i = 0; _i < 2; ++_i) \
;         __builtin_amdgcn_global_load_lds((const unsigned*)((const char*)(gbase) + (voff)[_i]), (LAS unsigned*)(lds + (bufoff) + ldsw + _i * 8192), 16, 0, 0); } while (0)
; #define PG8_LDA(dst, b, h) do { _Pragma("unroll") for (int m = 0; m < 4; ++m) _Pragma("unroll") for (int k = 0; k < 2; ++k) dst[m][k] = *(const LAS bf16x8*)(lds + PG8_SA(b, h) + aoff + m * 2048 + k * 1024); } while (0)
; #define PG8_LDB(dst, b, h) do { _Pragma("unroll") for (int n = 0; n < 2; ++n) _Pragma("unroll") for (int k = 0; k < 2; ++k) dst[n][k] = *(const LAS bf16x8*)(lds + PG8_SB(b, h) + boff + n * 2048 + k * 1024); } while (0)
; #define PG8_MMA(ai, bj, At, Bt) do { __builtin_amdgcn_s_setprio(1); _Pragma("unroll") for (int m = 0; m < 4; ++m) _Pragma("unroll") for (int n = 0; n < 2; ++n) _Pragma("unroll") for (int k = 0; k < 2; ++k) \
;         acc[ai][bj][m][n] = __builtin_amdgcn_mfma_f32_16x16x32_bf16(Bt[n][k], At[m][k], acc[ai][bj][m][n], 0, 0, 0); __builtin_amdgcn_s_setprio(0); } while (0)
; #define PG8_WAIT_V(n) asm volatile("s_waitcnt vmcnt(" #n ")" ::: "memory")
; #define PG8_BAR __builtin_amdgcn_s_barrier()
; template <class Epi, class Sched, bool ABLK = false, bool ALIGN_EPI = true, bool SP2 = true, bool BBLK = true>
; __device__ __forceinline__ void gemm_phase(LAS unsigned char* lds, const Gemm g, const Sched& S, const Epi& E) {
;     ...
;             const bool last = (t == nt - 2);
;             const char* a1 = a_tile(uA, tbA + t + 1);
;             const char* a2 = last ? a_tile(nuA, ntbA) : a_tile(uA, tbA + t + 2); const char* b2 = last ? nB : cB + (size_t)(t + 2) * kstepB;
;             const char* a3 = last ? a_tile(nuA, ntbA + 1) : a_tile(uA, tbA + t + 3); const char* b3 = b2 + kstepB;
;             if (last && has_next) S.a_ready(nxt);
;             if constexpr (SP2) {
;             PG8_LDB(B0, 0, 0); PG8_LDB(B1, 0, 1); PG8_SCHED; PG8_LDA(At, 0, 0); PG8_STAGE(PG8_SA(1, 1), a1 + hstepA, voffA);
;             PG8_WAIT_V(8); PG8_WAIT_L(0); PG8_BAR; PG8_MMA(0, 0, At, B0); PG8_MMA(0, 1, At, B1); PG8_BAR; PG8_SCHED;
;             PG8_LDA(At, 0, 1); PG8_STAGE(PG8_SB(0, 0), b2, voffB); PG8_STAGE(PG8_SB(0, 1), b2 + hstepB, voffB); PG8_STAGE(PG8_SA(0, 0), a2, voffA);
;             PG8_WAIT_V(8); PG8_WAIT_L(0); PG8_BAR; PG8_MMA(1, 0, At, B0); PG8_MMA(1, 1, At, B1); PG8_BAR; PG8_SCHED;
.LBB0_1842:
	ds_read_b128 v[172:175], v168
	ds_read_b128 v[176:179], v168 offset:1024
	ds_read_b128 v[180:183], v168 offset:2048
	ds_read_b128 v[184:187], v168 offset:3072
	ds_read_b128 v[188:191], v169
	ds_read_b128 v[192:195], v169 offset:1024
	ds_read_b128 v[196:199], v169 offset:2048
	ds_read_b128 v[200:203], v169 offset:3072
	s_add_u32 s30, s26, s28
	s_addc_u32 s31, s27, s29
	s_add_u32 s36, s30, 0x100
	s_addc_u32 s37, s31, 0
	s_add_u32 s30, s30, 0x180
	s_addc_u32 s31, s31, 0
	s_cmpk_eq_i32 s28, 0xf00
	s_cselect_b32 s31, s51, s31
	s_cselect_b32 s30, s23, s30
	s_cselect_b32 s35, s11, s53
	s_cselect_b32 s34, s15, s52
	s_cselect_b32 s37, s4, s37
	s_cselect_b32 s36, s5, s36
	s_mov_b32 m0, s47
	v_lshl_add_u64 v[236:237], v[164:165], 0, s[28:29]
	ds_read_b128 v[204:207], v170
	ds_read_b128 v[208:211], v170 offset:1024
	ds_read_b128 v[212:215], v170 offset:2048
	ds_read_b128 v[216:219], v170 offset:3072
	ds_read_b128 v[220:223], v170 offset:4096
	ds_read_b128 v[224:227], v170 offset:5120
	ds_read_b128 v[228:231], v170 offset:6144
	ds_read_b128 v[232:235], v170 offset:7168
	global_load_lds_dwordx4 v[236:237], off
	v_lshl_add_u64 v[236:237], v[166:167], 0, s[28:29]
	s_mov_b32 m0, s48
	s_nop 0
	global_load_lds_dwordx4 v[236:237], off
	s_waitcnt vmcnt(8) lgkmcnt(0)
	s_barrier
	v_mfma_f32_16x16x32_bf16 v[126:129], v[172:175], v[204:207], v[126:129]
	v_mfma_f32_16x16x32_bf16 v[122:125], v[180:183], v[204:207], v[122:125]
	v_mfma_f32_16x16x32_bf16 v[110:113], v[172:175], v[212:215], v[110:113]
	v_mfma_f32_16x16x32_bf16 v[106:109], v[180:183], v[212:215], v[106:109]
	v_mfma_f32_16x16x32_bf16 v[94:97], v[172:175], v[220:223], v[94:97]
	v_mfma_f32_16x16x32_bf16 v[90:93], v[180:183], v[220:223], v[90:93]
	v_mfma_f32_16x16x32_bf16 v[78:81], v[172:175], v[228:231], v[78:81]
	v_mfma_f32_16x16x32_bf16 v[74:77], v[180:183], v[228:231], v[74:77]
	v_mfma_f32_16x16x32_bf16 v[126:129], v[176:179], v[208:211], v[126:129]
	v_mfma_f32_16x16x32_bf16 v[122:125], v[184:187], v[208:211], v[122:125]
	v_mfma_f32_16x16x32_bf16 v[110:113], v[176:179], v[216:219], v[110:113]
	v_mfma_f32_16x16x32_bf16 v[106:109], v[184:187], v[216:219], v[106:109]
	v_mfma_f32_16x16x32_bf16 v[94:97], v[176:179], v[224:227], v[94:97]
	v_mfma_f32_16x16x32_bf16 v[90:93], v[184:187], v[224:227], v[90:93]
	v_mfma_f32_16x16x32_bf16 v[78:81], v[176:179], v[232:235], v[78:81]
	v_mfma_f32_16x16x32_bf16 v[74:77], v[184:187], v[232:235], v[74:77]
	v_mfma_f32_16x16x32_bf16 v[118:121], v[188:191], v[204:207], v[118:121]
	v_mfma_f32_16x16x32_bf16 v[114:117], v[196:199], v[204:207], v[114:117]
	v_mfma_f32_16x16x32_bf16 v[102:105], v[188:191], v[212:215], v[102:105]
	v_mfma_f32_16x16x32_bf16 v[98:101], v[196:199], v[212:215], v[98:101]
	v_mfma_f32_16x16x32_bf16 v[86:89], v[188:191], v[220:223], v[86:89]
	v_mfma_f32_16x16x32_bf16 v[82:85], v[196:199], v[220:223], v[82:85]
	v_mfma_f32_16x16x32_bf16 v[70:73], v[188:191], v[228:231], v[70:73]
	v_mfma_f32_16x16x32_bf16 v[66:69], v[196:199], v[228:231], v[66:69]
	v_mfma_f32_16x16x32_bf16 v[118:121], v[192:195], v[208:211], v[118:121]
	v_mfma_f32_16x16x32_bf16 v[114:117], v[200:203], v[208:211], v[114:117]
	v_mfma_f32_16x16x32_bf16 v[102:105], v[192:195], v[216:219], v[102:105]
	v_mfma_f32_16x16x32_bf16 v[98:101], v[200:203], v[216:219], v[98:101]
	v_mfma_f32_16x16x32_bf16 v[86:89], v[192:195], v[224:227], v[86:89]
	v_mfma_f32_16x16x32_bf16 v[82:85], v[200:203], v[224:227], v[82:85]
	v_mfma_f32_16x16x32_bf16 v[70:73], v[192:195], v[232:235], v[70:73]
	v_mfma_f32_16x16x32_bf16 v[66:69], v[200:203], v[232:235], v[66:69]
	s_barrier
	s_mov_b32 m0, s49
	s_add_u32 s56, s34, 0x4000
	ds_read_b128 v[204:207], v170 offset:16384
	ds_read_b128 v[208:211], v170 offset:17408
	ds_read_b128 v[212:215], v170 offset:18432
	ds_read_b128 v[216:219], v170 offset:19456
	ds_read_b128 v[220:223], v170 offset:20480
	ds_read_b128 v[224:227], v170 offset:21504
	ds_read_b128 v[228:231], v170 offset:22528
	ds_read_b128 v[232:235], v170 offset:23552
	global_load_lds_dwordx4 v134, s[34:35]
	s_mov_b32 m0, s50
	s_addc_u32 s57, s35, 0
	s_add_i32 s55, s73, s39
	global_load_lds_dwordx4 v130, s[34:35]
	s_mov_b32 m0, s55
	s_nop 0
	global_load_lds_dwordx4 v134, s[56:57]
	s_add_i32 m0, s55, 0x2000
	s_nop 0
	global_load_lds_dwordx4 v130, s[56:57]
	s_mov_b32 m0, s25
	s_nop 0
	global_load_lds_dwordx4 v136, s[36:37]
	s_mov_b32 m0, s40
	s_nop 0
	global_load_lds_dwordx4 v132, s[36:37]
	s_waitcnt vmcnt(8) lgkmcnt(0)
	s_barrier
	v_mfma_f32_16x16x32_bf16 v[62:65], v[172:175], v[204:207], v[62:65]
	v_mfma_f32_16x16x32_bf16 v[58:61], v[180:183], v[204:207], v[58:61]
	v_mfma_f32_16x16x32_bf16 v[46:49], v[172:175], v[212:215], v[46:49]
	v_mfma_f32_16x16x32_bf16 v[42:45], v[180:183], v[212:215], v[42:45]
	v_mfma_f32_16x16x32_bf16 v[30:33], v[172:175], v[220:223], v[30:33]
	v_mfma_f32_16x16x32_bf16 v[26:29], v[180:183], v[220:223], v[26:29]
	v_mfma_f32_16x16x32_bf16 v[14:17], v[172:175], v[228:231], v[14:17]
	v_mfma_f32_16x16x32_bf16 v[10:13], v[180:183], v[228:231], v[10:13]
	v_mfma_f32_16x16x32_bf16 v[62:65], v[176:179], v[208:211], v[62:65]
	v_mfma_f32_16x16x32_bf16 v[58:61], v[184:187], v[208:211], v[58:61]
	v_mfma_f32_16x16x32_bf16 v[46:49], v[176:179], v[216:219], v[46:49]
	v_mfma_f32_16x16x32_bf16 v[42:45], v[184:187], v[216:219], v[42:45]
	v_mfma_f32_16x16x32_bf16 v[30:33], v[176:179], v[224:227], v[30:33]
	v_mfma_f32_16x16x32_bf16 v[26:29], v[184:187], v[224:227], v[26:29]
	v_mfma_f32_16x16x32_bf16 v[14:17], v[176:179], v[232:235], v[14:17]
	v_mfma_f32_16x16x32_bf16 v[10:13], v[184:187], v[232:235], v[10:13]
	v_mfma_f32_16x16x32_bf16 v[54:57], v[188:191], v[204:207], v[54:57]
	v_mfma_f32_16x16x32_bf16 v[50:53], v[196:199], v[204:207], v[50:53]
	v_mfma_f32_16x16x32_bf16 v[38:41], v[188:191], v[212:215], v[38:41]
	v_mfma_f32_16x16x32_bf16 v[34:37], v[196:199], v[212:215], v[34:37]
	v_mfma_f32_16x16x32_bf16 v[22:25], v[188:191], v[220:223], v[22:25]
	v_mfma_f32_16x16x32_bf16 v[18:21], v[196:199], v[220:223], v[18:21]
	v_mfma_f32_16x16x32_bf16 v[6:9], v[188:191], v[228:231], v[6:9]
	v_mfma_f32_16x16x32_bf16 v[2:5], v[196:199], v[228:231], v[2:5]
	v_mfma_f32_16x16x32_bf16 v[54:57], v[192:195], v[208:211], v[54:57]
	v_mfma_f32_16x16x32_bf16 v[50:53], v[200:203], v[208:211], v[50:53]
	v_mfma_f32_16x16x32_bf16 v[38:41], v[192:195], v[216:219], v[38:41]
	v_mfma_f32_16x16x32_bf16 v[34:37], v[200:203], v[216:219], v[34:37]
	v_mfma_f32_16x16x32_bf16 v[22:25], v[192:195], v[224:227], v[22:25]
	v_mfma_f32_16x16x32_bf16 v[18:21], v[200:203], v[224:227], v[18:21]
	v_mfma_f32_16x16x32_bf16 v[6:9], v[192:195], v[232:235], v[6:9]
	v_mfma_f32_16x16x32_bf16 v[2:5], v[200:203], v[232:235], v[2:5]
	s_barrier
; #define PG8_STAGE(bufoff, gbase, voff) do { _Pragma("unroll") for (int _i = 0; _i < 2; ++_i) \
;         __builtin_amdgcn_global_load_lds((const unsigned*)((const char*)(gbase) + (voff)[_i]), (LAS unsigned*)(lds + (bufoff) + ldsw + _i * 8192), 16, 0, 0); } while (0)
; #define PG8_LDA(dst, b, h) do { _Pragma("unroll") for (int m = 0; m < 4; ++m) _Pragma("unroll") for (int k = 0; k < 2; ++k) dst[m][k] = *(const LAS bf16x8*)(lds + PG8_SA(b, h) + aoff + m * 2048 + k * 1024); } while (0)
; #define PG8_LDB(dst, b, h) do { _Pragma("unroll") for (int n = 0; n < 2; ++n) _Pragma("unroll") for (int k = 0; k < 2; ++k) dst[n][k] = *(const LAS bf16x8*)(lds + PG8_SB(b, h) + boff + n * 2048 + k * 1024); } while (0)
; #define PG8_MMA(ai, bj, At, Bt) do { __builtin_amdgcn_s_setprio(1); _Pragma("unroll") for (int m = 0; m < 4; ++m) _Pragma("unroll") for (int n = 0; n < 2; ++n) _Pragma("unroll") for (int k = 0; k < 2; ++k) \
;         acc[ai][bj][m][n] = __builtin_amdgcn_mfma_f32_16x16x32_bf16(Bt[n][k], At[m][k], acc[ai][bj][m][n], 0, 0, 0); __builtin_amdgcn_s_setprio(0); } while (0)
; #define PG8_WAIT_V(n) asm volatile("s_waitcnt vmcnt(" #n ")" ::: "memory")
; #define PG8_WAIT_L(n) asm volatile("s_waitcnt lgkmcnt(" #n ")" ::: "memory")
; #define PG8_BAR __builtin_amdgcn_s_barrier()
; #define PG8_SCHED __builtin_amdgcn_sched_barrier(0)
; template <class Epi, class Sched, bool ABLK = false, bool ALIGN_EPI = true, bool SP2 = true, bool BBLK = true>
; __device__ __forceinline__ void gemm_phase(LAS unsigned char* lds, const Gemm g, const Sched& S, const Epi& E) {
;     ...
;         for (int t = 0; t < nt; t += 2) {
;     ...
;             PG8_LDB(B0, 1, 0); PG8_LDB(B1, 1, 1); PG8_SCHED; PG8_LDA(At, 1, 0); PG8_STAGE(PG8_SA(0, 1), a2 + hstepA, voffA);
;             PG8_WAIT_V(8); PG8_WAIT_L(0); PG8_BAR; PG8_MMA(0, 0, At, B0); PG8_MMA(0, 1, At, B1); PG8_BAR; PG8_SCHED;
;             PG8_LDA(At, 1, 1); PG8_STAGE(PG8_SB(1, 0), b3, voffB); PG8_STAGE(PG8_SB(1, 1), b3 + hstepB, voffB); PG8_STAGE(PG8_SA(1, 0), a3, voffA);
;             PG8_WAIT_V(8); PG8_WAIT_L(0); PG8_BAR; PG8_MMA(1, 0, At, B0); PG8_MMA(1, 1, At, B1); PG8_BAR; PG8_SCHED;
	v_add_u32_e32 v171, s60, v1
	ds_read_b128 v[172:175], v171
	ds_read_b128 v[176:179], v171 offset:1024
	ds_read_b128 v[180:183], v171 offset:2048
	ds_read_b128 v[184:187], v171 offset:3072
	v_add_u32_e32 v171, s61, v1
	ds_read_b128 v[188:191], v171
	ds_read_b128 v[192:195], v171 offset:1024
	ds_read_b128 v[196:199], v171 offset:2048
	ds_read_b128 v[200:203], v171 offset:3072
	s_add_u32 s36, s36, 0x80000
	s_addc_u32 s37, s37, 0
	s_mov_b32 m0, s41
	ds_read_b128 v[204:207], v170 offset:32768
	ds_read_b128 v[208:211], v170 offset:33792
	ds_read_b128 v[212:215], v170 offset:34816
	ds_read_b128 v[216:219], v170 offset:35840
	ds_read_b128 v[220:223], v170 offset:36864
	ds_read_b128 v[224:227], v170 offset:37888
	ds_read_b128 v[228:231], v170 offset:38912
	ds_read_b128 v[232:235], v170 offset:39936
	global_load_lds_dwordx4 v136, s[36:37]
	s_mov_b32 m0, s42
	s_nop 0
	global_load_lds_dwordx4 v132, s[36:37]
	s_waitcnt vmcnt(8) lgkmcnt(0)
	s_barrier
	v_mfma_f32_16x16x32_bf16 v[126:129], v[172:175], v[204:207], v[126:129]
	v_mfma_f32_16x16x32_bf16 v[122:125], v[180:183], v[204:207], v[122:125]
	v_mfma_f32_16x16x32_bf16 v[110:113], v[172:175], v[212:215], v[110:113]
	v_mfma_f32_16x16x32_bf16 v[106:109], v[180:183], v[212:215], v[106:109]
	v_mfma_f32_16x16x32_bf16 v[94:97], v[172:175], v[220:223], v[94:97]
	v_mfma_f32_16x16x32_bf16 v[90:93], v[180:183], v[220:223], v[90:93]
	v_mfma_f32_16x16x32_bf16 v[78:81], v[172:175], v[228:231], v[78:81]
	v_mfma_f32_16x16x32_bf16 v[74:77], v[180:183], v[228:231], v[74:77]
	v_mfma_f32_16x16x32_bf16 v[126:129], v[176:179], v[208:211], v[126:129]
	v_mfma_f32_16x16x32_bf16 v[122:125], v[184:187], v[208:211], v[122:125]
	v_mfma_f32_16x16x32_bf16 v[110:113], v[176:179], v[216:219], v[110:113]
	v_mfma_f32_16x16x32_bf16 v[106:109], v[184:187], v[216:219], v[106:109]
	v_mfma_f32_16x16x32_bf16 v[94:97], v[176:179], v[224:227], v[94:97]
	v_mfma_f32_16x16x32_bf16 v[90:93], v[184:187], v[224:227], v[90:93]
	v_mfma_f32_16x16x32_bf16 v[78:81], v[176:179], v[232:235], v[78:81]
	v_mfma_f32_16x16x32_bf16 v[74:77], v[184:187], v[232:235], v[74:77]
	v_mfma_f32_16x16x32_bf16 v[118:121], v[188:191], v[204:207], v[118:121]
	v_mfma_f32_16x16x32_bf16 v[114:117], v[196:199], v[204:207], v[114:117]
	v_mfma_f32_16x16x32_bf16 v[102:105], v[188:191], v[212:215], v[102:105]
	v_mfma_f32_16x16x32_bf16 v[98:101], v[196:199], v[212:215], v[98:101]
	v_mfma_f32_16x16x32_bf16 v[86:89], v[188:191], v[220:223], v[86:89]
	v_mfma_f32_16x16x32_bf16 v[82:85], v[196:199], v[220:223], v[82:85]
	v_mfma_f32_16x16x32_bf16 v[70:73], v[188:191], v[228:231], v[70:73]
	v_mfma_f32_16x16x32_bf16 v[66:69], v[196:199], v[228:231], v[66:69]
	v_mfma_f32_16x16x32_bf16 v[118:121], v[192:195], v[208:211], v[118:121]
	v_mfma_f32_16x16x32_bf16 v[114:117], v[200:203], v[208:211], v[114:117]
	v_mfma_f32_16x16x32_bf16 v[102:105], v[192:195], v[216:219], v[102:105]
	v_mfma_f32_16x16x32_bf16 v[98:101], v[200:203], v[216:219], v[98:101]
	v_mfma_f32_16x16x32_bf16 v[86:89], v[192:195], v[224:227], v[86:89]
	v_mfma_f32_16x16x32_bf16 v[82:85], v[200:203], v[224:227], v[82:85]
	v_mfma_f32_16x16x32_bf16 v[70:73], v[192:195], v[232:235], v[70:73]
	v_mfma_f32_16x16x32_bf16 v[66:69], v[200:203], v[232:235], v[66:69]
	s_barrier
	s_add_u32 s36, s34, 0x8000
	s_addc_u32 s37, s35, 0
	s_add_i32 s55, s60, s39
	s_mov_b32 m0, s55
	ds_read_b128 v[204:207], v170 offset:49152
	ds_read_b128 v[208:211], v170 offset:50176
	ds_read_b128 v[212:215], v170 offset:51200
	ds_read_b128 v[216:219], v170 offset:52224
	ds_read_b128 v[220:223], v170 offset:53248
	ds_read_b128 v[224:227], v170 offset:54272
	ds_read_b128 v[228:231], v170 offset:55296
	ds_read_b128 v[232:235], v170 offset:56320
	global_load_lds_dwordx4 v134, s[36:37]
	s_add_i32 m0, s55, 0x2000
	s_add_u32 s34, s34, 0xc000
	v_lshl_add_u64 v[236:237], s[36:37], 0, v[130:131]
	s_addc_u32 s35, s35, 0
	s_add_i32 s36, s61, s39
	global_load_lds_dwordx4 v[236:237], off
	s_mov_b32 m0, s36
	s_nop 0
	global_load_lds_dwordx4 v134, s[34:35]
	s_add_i32 m0, s36, 0x2000
	s_nop 0
	global_load_lds_dwordx4 v130, s[34:35]
	s_mov_b32 m0, s45
	s_nop 0
	global_load_lds_dwordx4 v136, s[30:31]
	s_mov_b32 m0, s46
	s_nop 0
	global_load_lds_dwordx4 v132, s[30:31]
	s_waitcnt vmcnt(8) lgkmcnt(0)
	s_barrier
	v_mfma_f32_16x16x32_bf16 v[62:65], v[172:175], v[204:207], v[62:65]
	v_mfma_f32_16x16x32_bf16 v[58:61], v[180:183], v[204:207], v[58:61]
	v_mfma_f32_16x16x32_bf16 v[46:49], v[172:175], v[212:215], v[46:49]
	v_mfma_f32_16x16x32_bf16 v[42:45], v[180:183], v[212:215], v[42:45]
	v_mfma_f32_16x16x32_bf16 v[30:33], v[172:175], v[220:223], v[30:33]
	v_mfma_f32_16x16x32_bf16 v[26:29], v[180:183], v[220:223], v[26:29]
	v_mfma_f32_16x16x32_bf16 v[14:17], v[172:175], v[228:231], v[14:17]
	v_mfma_f32_16x16x32_bf16 v[10:13], v[180:183], v[228:231], v[10:13]
	v_mfma_f32_16x16x32_bf16 v[62:65], v[176:179], v[208:211], v[62:65]
	v_mfma_f32_16x16x32_bf16 v[58:61], v[184:187], v[208:211], v[58:61]
	v_mfma_f32_16x16x32_bf16 v[46:49], v[176:179], v[216:219], v[46:49]
	v_mfma_f32_16x16x32_bf16 v[42:45], v[184:187], v[216:219], v[42:45]
	v_mfma_f32_16x16x32_bf16 v[30:33], v[176:179], v[224:227], v[30:33]
	v_mfma_f32_16x16x32_bf16 v[26:29], v[184:187], v[224:227], v[26:29]
	v_mfma_f32_16x16x32_bf16 v[14:17], v[176:179], v[232:235], v[14:17]
	v_mfma_f32_16x16x32_bf16 v[10:13], v[184:187], v[232:235], v[10:13]
	v_mfma_f32_16x16x32_bf16 v[54:57], v[188:191], v[204:207], v[54:57]
	v_mfma_f32_16x16x32_bf16 v[50:53], v[196:199], v[204:207], v[50:53]
	v_mfma_f32_16x16x32_bf16 v[38:41], v[188:191], v[212:215], v[38:41]
	v_mfma_f32_16x16x32_bf16 v[34:37], v[196:199], v[212:215], v[34:37]
	v_mfma_f32_16x16x32_bf16 v[22:25], v[188:191], v[220:223], v[22:25]
	v_mfma_f32_16x16x32_bf16 v[18:21], v[196:199], v[220:223], v[18:21]
	v_mfma_f32_16x16x32_bf16 v[6:9], v[188:191], v[228:231], v[6:9]
	v_mfma_f32_16x16x32_bf16 v[2:5], v[196:199], v[228:231], v[2:5]
	v_mfma_f32_16x16x32_bf16 v[54:57], v[192:195], v[208:211], v[54:57]
	v_mfma_f32_16x16x32_bf16 v[50:53], v[200:203], v[208:211], v[50:53]
	v_mfma_f32_16x16x32_bf16 v[38:41], v[192:195], v[216:219], v[38:41]
	v_mfma_f32_16x16x32_bf16 v[34:37], v[200:203], v[216:219], v[34:37]
	v_mfma_f32_16x16x32_bf16 v[22:25], v[192:195], v[224:227], v[22:25]
	v_mfma_f32_16x16x32_bf16 v[18:21], v[200:203], v[224:227], v[18:21]
	v_mfma_f32_16x16x32_bf16 v[6:9], v[192:195], v[232:235], v[6:9]
	v_mfma_f32_16x16x32_bf16 v[2:5], v[200:203], v[232:235], v[2:5]
	s_barrier
	s_add_i32 s54, s54, 2
	s_add_u32 s28, s28, 0x100
	s_addc_u32 s29, s29, 0
	s_add_u32 s52, s52, 0x10000
	s_addc_u32 s53, s53, 0
	s_cmp_gt_u32 s54, 29
	s_cbranch_scc0 .LBB0_1842
	s_and_b64 vcc, exec, s[6:7]
	s_cbranch_vccz .LBB0_1845
	s_barrier

; #define PG8_STAGE(bufoff, gbase, voff) do { _Pragma("unroll") for (int _i = 0; _i < 2; ++_i) \
;         __builtin_amdgcn_global_load_lds((const unsigned*)((const char*)(gbase) + (voff)[_i]), (LAS unsigned*)(lds + (bufoff) + ldsw + _i * 8192), 16, 0, 0); } while (0)
; #define PG8_LDA(dst, b, h) do { _Pragma("unroll") for (int m = 0; m < 4; ++m) _Pragma("unroll") for (int k = 0; k < 2; ++k) dst[m][k] = *(const LAS bf16x8*)(lds + PG8_SA(b, h) + aoff + m * 2048 + k * 1024); } while (0)
; #define PG8_LDB(dst, b, h) do { _Pragma("unroll") for (int n = 0; n < 2; ++n) _Pragma("unroll") for (int k = 0; k < 2; ++k) dst[n][k] = *(const LAS bf16x8*)(lds + PG8_SB(b, h) + boff + n * 2048 + k * 1024); } while (0)
; #define PG8_MMA(ai, bj, At, Bt) do { __builtin_amdgcn_s_setprio(1); _Pragma("unroll") for (int m = 0; m < 4; ++m) _Pragma("unroll") for (int n = 0; n < 2; ++n) _Pragma("unroll") for (int k = 0; k < 2; ++k) \
;         acc[ai][bj][m][n] = __builtin_amdgcn_mfma_f32_16x16x32_bf16(Bt[n][k], At[m][k], acc[ai][bj][m][n], 0, 0, 0); __builtin_amdgcn_s_setprio(0); } while (0)
; #define PG8_WAIT_V(n) asm volatile("s_waitcnt vmcnt(" #n ")" ::: "memory")
; #define PG8_WAIT_L(n) asm volatile("s_waitcnt lgkmcnt(" #n ")" ::: "memory")
; #define PG8_BAR __builtin_amdgcn_s_barrier()
; template <class Epi, class Sched, bool ABLK = false, bool ALIGN_EPI = true, bool SP2 = true, bool BBLK = true>
; __device__ __forceinline__ void gemm_phase(LAS unsigned char* lds, const Gemm g, const Sched& S, const Epi& E) {
;     ...
;             const bool last = (t == nt - 2);
;             const char* a1 = a_tile(uA, tbA + t + 1);
;             const char* a2 = last ? a_tile(nuA, ntbA) : a_tile(uA, tbA + t + 2); const char* b2 = last ? nB : cB + (size_t)(t + 2) * kstepB;
;             const char* a3 = last ? a_tile(nuA, ntbA + 1) : a_tile(uA, tbA + t + 3); const char* b3 = b2 + kstepB;
;             if (last && has_next) S.a_ready(nxt);
;             if constexpr (SP2) {
;             PG8_LDB(B0, 0, 0); PG8_LDB(B1, 0, 1); PG8_SCHED; PG8_LDA(At, 0, 0); PG8_STAGE(PG8_SA(1, 1), a1 + hstepA, voffA);
;             PG8_WAIT_V(8); PG8_WAIT_L(0); PG8_BAR; PG8_MMA(0, 0, At, B0); PG8_MMA(0, 1, At, B1); PG8_BAR; PG8_SCHED;
;             PG8_LDA(At, 0, 1); PG8_STAGE(PG8_SB(0, 0), b2, voffB); PG8_STAGE(PG8_SB(0, 1), b2 + hstepB, voffB); PG8_STAGE(PG8_SA(0, 0), a2, voffA);
.LBB0_1907:
	ds_read_b128 v[152:155], v148
	ds_read_b128 v[156:159], v148 offset:1024
	ds_read_b128 v[160:163], v148 offset:2048
	ds_read_b128 v[164:167], v148 offset:3072
	ds_read_b128 v[168:171], v149
	ds_read_b128 v[172:175], v149 offset:1024
	ds_read_b128 v[176:179], v149 offset:2048
	ds_read_b128 v[180:183], v149 offset:3072
	s_add_u32 s34, s55, s30
	s_addc_u32 s35, s56, s31
	s_add_u32 s38, s34, 0x10000
	s_addc_u32 s39, s35, 0
	s_add_i32 s58, s58, 2
	s_add_u32 s36, s53, s30
	s_addc_u32 s37, s54, s31
	s_add_u32 s34, s34, 0x18000
	s_addc_u32 s35, s35, 0
	s_cmp_eq_u32 s57, s30
	s_cselect_b32 s35, s52, s35
	s_cselect_b32 s34, s51, s34
	s_cselect_b32 s37, s4, s37
	s_cselect_b32 s36, s5, s36
	s_cselect_b32 s39, s50, s39
	s_cselect_b32 s38, s27, s38
	v_lshl_add_u64 v[216:217], v[142:143], 0, s[30:31]
	s_add_i32 m0, s41, 0xc000
	ds_read_b128 v[184:187], v150
	ds_read_b128 v[188:191], v150 offset:1024
	ds_read_b128 v[192:195], v150 offset:2048
	ds_read_b128 v[196:199], v150 offset:3072
	ds_read_b128 v[200:203], v150 offset:4096
	ds_read_b128 v[204:207], v150 offset:5120
	ds_read_b128 v[208:211], v150 offset:6144
	ds_read_b128 v[212:215], v150 offset:7168
	global_load_lds_dwordx4 v[216:217], off
	v_lshl_add_u64 v[216:217], v[144:145], 0, s[30:31]
	s_add_i32 m0, s41, 0xe000
	s_nop 0
	global_load_lds_dwordx4 v[216:217], off
	s_waitcnt vmcnt(8) lgkmcnt(0)
	s_barrier
	v_mfma_f32_16x16x32_bf16 v[126:129], v[152:155], v[184:187], v[126:129]
	v_mfma_f32_16x16x32_bf16 v[122:125], v[160:163], v[184:187], v[122:125]
	v_mfma_f32_16x16x32_bf16 v[110:113], v[152:155], v[192:195], v[110:113]
	v_mfma_f32_16x16x32_bf16 v[106:109], v[160:163], v[192:195], v[106:109]
	v_mfma_f32_16x16x32_bf16 v[94:97], v[152:155], v[200:203], v[94:97]
	v_mfma_f32_16x16x32_bf16 v[90:93], v[160:163], v[200:203], v[90:93]
	v_mfma_f32_16x16x32_bf16 v[78:81], v[152:155], v[208:211], v[78:81]
	v_mfma_f32_16x16x32_bf16 v[74:77], v[160:163], v[208:211], v[74:77]
	v_mfma_f32_16x16x32_bf16 v[126:129], v[156:159], v[188:191], v[126:129]
	v_mfma_f32_16x16x32_bf16 v[122:125], v[164:167], v[188:191], v[122:125]
	v_mfma_f32_16x16x32_bf16 v[110:113], v[156:159], v[196:199], v[110:113]
	v_mfma_f32_16x16x32_bf16 v[106:109], v[164:167], v[196:199], v[106:109]
	v_mfma_f32_16x16x32_bf16 v[94:97], v[156:159], v[204:207], v[94:97]
	v_mfma_f32_16x16x32_bf16 v[90:93], v[164:167], v[204:207], v[90:93]
	v_mfma_f32_16x16x32_bf16 v[78:81], v[156:159], v[212:215], v[78:81]
	v_mfma_f32_16x16x32_bf16 v[74:77], v[164:167], v[212:215], v[74:77]
	v_mfma_f32_16x16x32_bf16 v[118:121], v[168:171], v[184:187], v[118:121]
	v_mfma_f32_16x16x32_bf16 v[114:117], v[176:179], v[184:187], v[114:117]
	v_mfma_f32_16x16x32_bf16 v[102:105], v[168:171], v[192:195], v[102:105]
	v_mfma_f32_16x16x32_bf16 v[98:101], v[176:179], v[192:195], v[98:101]
	v_mfma_f32_16x16x32_bf16 v[86:89], v[168:171], v[200:203], v[86:89]
	v_mfma_f32_16x16x32_bf16 v[82:85], v[176:179], v[200:203], v[82:85]
	v_mfma_f32_16x16x32_bf16 v[70:73], v[168:171], v[208:211], v[70:73]
	v_mfma_f32_16x16x32_bf16 v[66:69], v[176:179], v[208:211], v[66:69]
	v_mfma_f32_16x16x32_bf16 v[118:121], v[172:175], v[188:191], v[118:121]
	v_mfma_f32_16x16x32_bf16 v[114:117], v[180:183], v[188:191], v[114:117]
	v_mfma_f32_16x16x32_bf16 v[102:105], v[172:175], v[196:199], v[102:105]
	v_mfma_f32_16x16x32_bf16 v[98:101], v[180:183], v[196:199], v[98:101]
	v_mfma_f32_16x16x32_bf16 v[86:89], v[172:175], v[204:207], v[86:89]
	v_mfma_f32_16x16x32_bf16 v[82:85], v[180:183], v[204:207], v[82:85]
	v_mfma_f32_16x16x32_bf16 v[70:73], v[172:175], v[212:215], v[70:73]
	v_mfma_f32_16x16x32_bf16 v[66:69], v[180:183], v[212:215], v[66:69]
	s_barrier
	s_add_i32 s59, s72, s40
	s_mov_b32 m0, s59
	ds_read_b128 v[184:187], v150 offset:16384
	ds_read_b128 v[188:191], v150 offset:17408
	ds_read_b128 v[192:195], v150 offset:18432
	ds_read_b128 v[196:199], v150 offset:19456
	ds_read_b128 v[200:203], v150 offset:20480
	ds_read_b128 v[204:207], v150 offset:21504
	ds_read_b128 v[208:211], v150 offset:22528
	ds_read_b128 v[212:215], v150 offset:23552
	global_load_lds_dwordx4 v130, s[36:37]
	s_add_i32 m0, s59, 0x2000
	s_add_u32 s64, s36, 0x4000
	s_addc_u32 s65, s37, 0
	s_add_i32 s59, s73, s40
	global_load_lds_dwordx4 v132, s[36:37]
	s_mov_b32 m0, s59
	s_nop 0
	global_load_lds_dwordx4 v130, s[64:65]
	s_add_i32 m0, s59, 0x2000
	s_nop 0
	global_load_lds_dwordx4 v132, s[64:65]
	s_mov_b32 m0, s41
	s_nop 0
	global_load_lds_dwordx4 v130, s[38:39]
	s_mov_b32 m0, s42
	s_nop 0
	global_load_lds_dwordx4 v132, s[38:39]
	s_waitcnt vmcnt(8) lgkmcnt(0)
	s_barrier
; #define PG8_STAGE(bufoff, gbase, voff) do { _Pragma("unroll") for (int _i = 0; _i < 2; ++_i) \
;         __builtin_amdgcn_global_load_lds((const unsigned*)((const char*)(gbase) + (voff)[_i]), (LAS unsigned*)(lds + (bufoff) + ldsw + _i * 8192), 16, 0, 0); } while (0)
; #define PG8_LDA(dst, b, h) do { _Pragma("unroll") for (int m = 0; m < 4; ++m) _Pragma("unroll") for (int k = 0; k < 2; ++k) dst[m][k] = *(const LAS bf16x8*)(lds + PG8_SA(b, h) + aoff + m * 2048 + k * 1024); } while (0)
; #define PG8_LDB(dst, b, h) do { _Pragma("unroll") for (int n = 0; n < 2; ++n) _Pragma("unroll") for (int k = 0; k < 2; ++k) dst[n][k] = *(const LAS bf16x8*)(lds + PG8_SB(b, h) + boff + n * 2048 + k * 1024); } while (0)
; #define PG8_MMA(ai, bj, At, Bt) do { __builtin_amdgcn_s_setprio(1); _Pragma("unroll") for (int m = 0; m < 4; ++m) _Pragma("unroll") for (int n = 0; n < 2; ++n) _Pragma("unroll") for (int k = 0; k < 2; ++k) \
;         acc[ai][bj][m][n] = __builtin_amdgcn_mfma_f32_16x16x32_bf16(Bt[n][k], At[m][k], acc[ai][bj][m][n], 0, 0, 0); __builtin_amdgcn_s_setprio(0); } while (0)
; #define PG8_WAIT_V(n) asm volatile("s_waitcnt vmcnt(" #n ")" ::: "memory")
; #define PG8_WAIT_L(n) asm volatile("s_waitcnt lgkmcnt(" #n ")" ::: "memory")
; #define PG8_BAR __builtin_amdgcn_s_barrier()
; #define PG8_SCHED __builtin_amdgcn_sched_barrier(0)
; template <class Epi, class Sched, bool ABLK = false, bool ALIGN_EPI = true, bool SP2 = true, bool BBLK = true>
; __device__ __forceinline__ void gemm_phase(LAS unsigned char* lds, const Gemm g, const Sched& S, const Epi& E) {
;     ...
;             PG8_WAIT_V(8); PG8_WAIT_L(0); PG8_BAR; PG8_MMA(1, 0, At, B0); PG8_MMA(1, 1, At, B1); PG8_BAR; PG8_SCHED;
;             PG8_LDB(B0, 1, 0); PG8_LDB(B1, 1, 1); PG8_SCHED; PG8_LDA(At, 1, 0); PG8_STAGE(PG8_SA(0, 1), a2 + hstepA, voffA);
;             PG8_WAIT_V(8); PG8_WAIT_L(0); PG8_BAR; PG8_MMA(0, 0, At, B0); PG8_MMA(0, 1, At, B1); PG8_BAR; PG8_SCHED;
	v_mfma_f32_16x16x32_bf16 v[62:65], v[152:155], v[184:187], v[62:65]
	v_mfma_f32_16x16x32_bf16 v[58:61], v[160:163], v[184:187], v[58:61]
	v_mfma_f32_16x16x32_bf16 v[46:49], v[152:155], v[192:195], v[46:49]
	v_mfma_f32_16x16x32_bf16 v[42:45], v[160:163], v[192:195], v[42:45]
	v_mfma_f32_16x16x32_bf16 v[30:33], v[152:155], v[200:203], v[30:33]
	v_mfma_f32_16x16x32_bf16 v[26:29], v[160:163], v[200:203], v[26:29]
	v_mfma_f32_16x16x32_bf16 v[14:17], v[152:155], v[208:211], v[14:17]
	v_mfma_f32_16x16x32_bf16 v[10:13], v[160:163], v[208:211], v[10:13]
	v_mfma_f32_16x16x32_bf16 v[62:65], v[156:159], v[188:191], v[62:65]
	v_mfma_f32_16x16x32_bf16 v[58:61], v[164:167], v[188:191], v[58:61]
	v_mfma_f32_16x16x32_bf16 v[46:49], v[156:159], v[196:199], v[46:49]
	v_mfma_f32_16x16x32_bf16 v[42:45], v[164:167], v[196:199], v[42:45]
	v_mfma_f32_16x16x32_bf16 v[30:33], v[156:159], v[204:207], v[30:33]
	v_mfma_f32_16x16x32_bf16 v[26:29], v[164:167], v[204:207], v[26:29]
	v_mfma_f32_16x16x32_bf16 v[14:17], v[156:159], v[212:215], v[14:17]
	v_mfma_f32_16x16x32_bf16 v[10:13], v[164:167], v[212:215], v[10:13]
	v_mfma_f32_16x16x32_bf16 v[54:57], v[168:171], v[184:187], v[54:57]
	v_mfma_f32_16x16x32_bf16 v[50:53], v[176:179], v[184:187], v[50:53]
	v_mfma_f32_16x16x32_bf16 v[38:41], v[168:171], v[192:195], v[38:41]
	v_mfma_f32_16x16x32_bf16 v[34:37], v[176:179], v[192:195], v[34:37]
	v_mfma_f32_16x16x32_bf16 v[22:25], v[168:171], v[200:203], v[22:25]
	v_mfma_f32_16x16x32_bf16 v[18:21], v[176:179], v[200:203], v[18:21]
	v_mfma_f32_16x16x32_bf16 v[6:9], v[168:171], v[208:211], v[6:9]
	v_mfma_f32_16x16x32_bf16 v[2:5], v[176:179], v[208:211], v[2:5]
	v_mfma_f32_16x16x32_bf16 v[54:57], v[172:175], v[188:191], v[54:57]
	v_mfma_f32_16x16x32_bf16 v[50:53], v[180:183], v[188:191], v[50:53]
	v_mfma_f32_16x16x32_bf16 v[38:41], v[172:175], v[196:199], v[38:41]
	v_mfma_f32_16x16x32_bf16 v[34:37], v[180:183], v[196:199], v[34:37]
	v_mfma_f32_16x16x32_bf16 v[22:25], v[172:175], v[204:207], v[22:25]
	v_mfma_f32_16x16x32_bf16 v[18:21], v[180:183], v[204:207], v[18:21]
	v_mfma_f32_16x16x32_bf16 v[6:9], v[172:175], v[212:215], v[6:9]
	v_mfma_f32_16x16x32_bf16 v[2:5], v[180:183], v[212:215], v[2:5]
	s_barrier
	v_add_u32_e32 v151, s60, v146
	ds_read_b128 v[152:155], v151
	ds_read_b128 v[156:159], v151 offset:1024
	ds_read_b128 v[160:163], v151 offset:2048
	ds_read_b128 v[164:167], v151 offset:3072
	v_add_u32_e32 v151, s61, v146
	ds_read_b128 v[168:171], v151
	ds_read_b128 v[172:175], v151 offset:1024
	ds_read_b128 v[176:179], v151 offset:2048
	ds_read_b128 v[180:183], v151 offset:3072
	s_add_u32 s38, s38, 0x4000
	s_addc_u32 s39, s39, 0
	s_mov_b32 m0, s43
	ds_read_b128 v[184:187], v150 offset:32768
	ds_read_b128 v[188:191], v150 offset:33792
	ds_read_b128 v[192:195], v150 offset:34816
	ds_read_b128 v[196:199], v150 offset:35840
	ds_read_b128 v[200:203], v150 offset:36864
	ds_read_b128 v[204:207], v150 offset:37888
	ds_read_b128 v[208:211], v150 offset:38912
	ds_read_b128 v[212:215], v150 offset:39936
	global_load_lds_dwordx4 v130, s[38:39]
	s_mov_b32 m0, s44
	s_nop 0
	global_load_lds_dwordx4 v132, s[38:39]
	s_waitcnt vmcnt(8) lgkmcnt(0)
	s_barrier
	v_mfma_f32_16x16x32_bf16 v[126:129], v[152:155], v[184:187], v[126:129]
	v_mfma_f32_16x16x32_bf16 v[122:125], v[160:163], v[184:187], v[122:125]
	v_mfma_f32_16x16x32_bf16 v[110:113], v[152:155], v[192:195], v[110:113]
	v_mfma_f32_16x16x32_bf16 v[106:109], v[160:163], v[192:195], v[106:109]
	v_mfma_f32_16x16x32_bf16 v[94:97], v[152:155], v[200:203], v[94:97]
	v_mfma_f32_16x16x32_bf16 v[90:93], v[160:163], v[200:203], v[90:93]
	v_mfma_f32_16x16x32_bf16 v[78:81], v[152:155], v[208:211], v[78:81]
	v_mfma_f32_16x16x32_bf16 v[74:77], v[160:163], v[208:211], v[74:77]
	v_mfma_f32_16x16x32_bf16 v[126:129], v[156:159], v[188:191], v[126:129]
	v_mfma_f32_16x16x32_bf16 v[122:125], v[164:167], v[188:191], v[122:125]
	v_mfma_f32_16x16x32_bf16 v[110:113], v[156:159], v[196:199], v[110:113]
	v_mfma_f32_16x16x32_bf16 v[106:109], v[164:167], v[196:199], v[106:109]
	v_mfma_f32_16x16x32_bf16 v[94:97], v[156:159], v[204:207], v[94:97]
	v_mfma_f32_16x16x32_bf16 v[90:93], v[164:167], v[204:207], v[90:93]
	v_mfma_f32_16x16x32_bf16 v[78:81], v[156:159], v[212:215], v[78:81]
	v_mfma_f32_16x16x32_bf16 v[74:77], v[164:167], v[212:215], v[74:77]
	v_mfma_f32_16x16x32_bf16 v[118:121], v[168:171], v[184:187], v[118:121]
	v_mfma_f32_16x16x32_bf16 v[114:117], v[176:179], v[184:187], v[114:117]
	v_mfma_f32_16x16x32_bf16 v[102:105], v[168:171], v[192:195], v[102:105]
	v_mfma_f32_16x16x32_bf16 v[98:101], v[176:179], v[192:195], v[98:101]
	v_mfma_f32_16x16x32_bf16 v[86:89], v[168:171], v[200:203], v[86:89]
	v_mfma_f32_16x16x32_bf16 v[82:85], v[176:179], v[200:203], v[82:85]
	v_mfma_f32_16x16x32_bf16 v[70:73], v[168:171], v[208:211], v[70:73]
	v_mfma_f32_16x16x32_bf16 v[66:69], v[176:179], v[208:211], v[66:69]
	v_mfma_f32_16x16x32_bf16 v[118:121], v[172:175], v[188:191], v[118:121]
	v_mfma_f32_16x16x32_bf16 v[114:117], v[180:183], v[188:191], v[114:117]
	v_mfma_f32_16x16x32_bf16 v[102:105], v[172:175], v[196:199], v[102:105]
	v_mfma_f32_16x16x32_bf16 v[98:101], v[180:183], v[196:199], v[98:101]
	v_mfma_f32_16x16x32_bf16 v[86:89], v[172:175], v[204:207], v[86:89]
	v_mfma_f32_16x16x32_bf16 v[82:85], v[180:183], v[204:207], v[82:85]
	v_mfma_f32_16x16x32_bf16 v[70:73], v[172:175], v[212:215], v[70:73]
	v_mfma_f32_16x16x32_bf16 v[66:69], v[180:183], v[212:215], v[66:69]
	s_barrier
; #define PG8_STAGE(bufoff, gbase, voff) do { _Pragma("unroll") for (int _i = 0; _i < 2; ++_i) \
;         __builtin_amdgcn_global_load_lds((const unsigned*)((const char*)(gbase) + (voff)[_i]), (LAS unsigned*)(lds + (bufoff) + ldsw + _i * 8192), 16, 0, 0); } while (0)
; #define PG8_LDA(dst, b, h) do { _Pragma("unroll") for (int m = 0; m < 4; ++m) _Pragma("unroll") for (int k = 0; k < 2; ++k) dst[m][k] = *(const LAS bf16x8*)(lds + PG8_SA(b, h) + aoff + m * 2048 + k * 1024); } while (0)
; #define PG8_MMA(ai, bj, At, Bt) do { __builtin_amdgcn_s_setprio(1); _Pragma("unroll") for (int m = 0; m < 4; ++m) _Pragma("unroll") for (int n = 0; n < 2; ++n) _Pragma("unroll") for (int k = 0; k < 2; ++k) \
;         acc[ai][bj][m][n] = __builtin_amdgcn_mfma_f32_16x16x32_bf16(Bt[n][k], At[m][k], acc[ai][bj][m][n], 0, 0, 0); __builtin_amdgcn_s_setprio(0); } while (0)
; #define PG8_WAIT_V(n) asm volatile("s_waitcnt vmcnt(" #n ")" ::: "memory")
; #define PG8_WAIT_L(n) asm volatile("s_waitcnt lgkmcnt(" #n ")" ::: "memory")
; #define PG8_BAR __builtin_amdgcn_s_barrier()
; #define PG8_SCHED __builtin_amdgcn_sched_barrier(0)
; template <class Epi, class Sched, bool ABLK = false, bool ALIGN_EPI = true, bool SP2 = true, bool BBLK = true>
; __device__ __forceinline__ void gemm_phase(LAS unsigned char* lds, const Gemm g, const Sched& S, const Epi& E) {
;     ...
;         for (int t = 0; t < nt; t += 2) {
;     ...
;             PG8_LDA(At, 1, 1); PG8_STAGE(PG8_SB(1, 0), b3, voffB); PG8_STAGE(PG8_SB(1, 1), b3 + hstepB, voffB); PG8_STAGE(PG8_SA(1, 0), a3, voffA);
;             PG8_WAIT_V(8); PG8_WAIT_L(0); PG8_BAR; PG8_MMA(1, 0, At, B0); PG8_MMA(1, 1, At, B1); PG8_BAR; PG8_SCHED;
	s_add_u32 s38, s36, 0x8000
	s_addc_u32 s39, s37, 0
	s_add_i32 s59, s60, s40
	s_mov_b32 m0, s59
	ds_read_b128 v[184:187], v150 offset:49152
	ds_read_b128 v[188:191], v150 offset:50176
	ds_read_b128 v[192:195], v150 offset:51200
	ds_read_b128 v[196:199], v150 offset:52224
	ds_read_b128 v[200:203], v150 offset:53248
	ds_read_b128 v[204:207], v150 offset:54272
	ds_read_b128 v[208:211], v150 offset:55296
	ds_read_b128 v[212:215], v150 offset:56320
	global_load_lds_dwordx4 v130, s[38:39]
	s_add_i32 m0, s59, 0x2000
	s_add_u32 s36, s36, 0xc000
	v_lshl_add_u64 v[216:217], s[38:39], 0, v[132:133]
	s_addc_u32 s37, s37, 0
	s_add_i32 s38, s61, s40
	global_load_lds_dwordx4 v[216:217], off
	s_mov_b32 m0, s38
	s_nop 0
	global_load_lds_dwordx4 v130, s[36:37]
	s_add_i32 m0, s38, 0x2000
	s_nop 0
	global_load_lds_dwordx4 v132, s[36:37]
	s_mov_b32 m0, s45
	s_nop 0
	global_load_lds_dwordx4 v130, s[34:35]
	s_mov_b32 m0, s46
	s_nop 0
	global_load_lds_dwordx4 v132, s[34:35]
	s_waitcnt vmcnt(8) lgkmcnt(0)
	s_barrier
	v_mfma_f32_16x16x32_bf16 v[62:65], v[152:155], v[184:187], v[62:65]
	v_mfma_f32_16x16x32_bf16 v[58:61], v[160:163], v[184:187], v[58:61]
	v_mfma_f32_16x16x32_bf16 v[46:49], v[152:155], v[192:195], v[46:49]
	v_mfma_f32_16x16x32_bf16 v[42:45], v[160:163], v[192:195], v[42:45]
	v_mfma_f32_16x16x32_bf16 v[30:33], v[152:155], v[200:203], v[30:33]
	v_mfma_f32_16x16x32_bf16 v[26:29], v[160:163], v[200:203], v[26:29]
	v_mfma_f32_16x16x32_bf16 v[14:17], v[152:155], v[208:211], v[14:17]
	v_mfma_f32_16x16x32_bf16 v[10:13], v[160:163], v[208:211], v[10:13]
	v_mfma_f32_16x16x32_bf16 v[62:65], v[156:159], v[188:191], v[62:65]
	v_mfma_f32_16x16x32_bf16 v[58:61], v[164:167], v[188:191], v[58:61]
	v_mfma_f32_16x16x32_bf16 v[46:49], v[156:159], v[196:199], v[46:49]
	v_mfma_f32_16x16x32_bf16 v[42:45], v[164:167], v[196:199], v[42:45]
	v_mfma_f32_16x16x32_bf16 v[30:33], v[156:159], v[204:207], v[30:33]
	v_mfma_f32_16x16x32_bf16 v[26:29], v[164:167], v[204:207], v[26:29]
	v_mfma_f32_16x16x32_bf16 v[14:17], v[156:159], v[212:215], v[14:17]
	v_mfma_f32_16x16x32_bf16 v[10:13], v[164:167], v[212:215], v[10:13]
	v_mfma_f32_16x16x32_bf16 v[54:57], v[168:171], v[184:187], v[54:57]
	v_mfma_f32_16x16x32_bf16 v[50:53], v[176:179], v[184:187], v[50:53]
	v_mfma_f32_16x16x32_bf16 v[38:41], v[168:171], v[192:195], v[38:41]
	v_mfma_f32_16x16x32_bf16 v[34:37], v[176:179], v[192:195], v[34:37]
	v_mfma_f32_16x16x32_bf16 v[22:25], v[168:171], v[200:203], v[22:25]
	v_mfma_f32_16x16x32_bf16 v[18:21], v[176:179], v[200:203], v[18:21]
	v_mfma_f32_16x16x32_bf16 v[6:9], v[168:171], v[208:211], v[6:9]
	v_mfma_f32_16x16x32_bf16 v[2:5], v[176:179], v[208:211], v[2:5]
	v_mfma_f32_16x16x32_bf16 v[54:57], v[172:175], v[188:191], v[54:57]
	v_mfma_f32_16x16x32_bf16 v[50:53], v[180:183], v[188:191], v[50:53]
	v_mfma_f32_16x16x32_bf16 v[38:41], v[172:175], v[196:199], v[38:41]
	v_mfma_f32_16x16x32_bf16 v[34:37], v[180:183], v[196:199], v[34:37]
	v_mfma_f32_16x16x32_bf16 v[22:25], v[172:175], v[204:207], v[22:25]
	v_mfma_f32_16x16x32_bf16 v[18:21], v[180:183], v[204:207], v[18:21]
	v_mfma_f32_16x16x32_bf16 v[6:9], v[172:175], v[212:215], v[6:9]
	v_mfma_f32_16x16x32_bf16 v[2:5], v[180:183], v[212:215], v[2:5]
	s_barrier
	s_add_u32 s30, s30, 0x10000
	s_addc_u32 s31, s31, 0
	s_cmp_ge_u32 s58, s48
	s_cbranch_scc0 .LBB0_1907
	s_and_b64 vcc, exec, s[6:7]
	s_cbranch_vccz .LBB0_1910
	s_barrier

; #define PG8_STAGE(bufoff, gbase, voff) do { _Pragma("unroll") for (int _i = 0; _i < 2; ++_i) \
;         __builtin_amdgcn_global_load_lds((const unsigned*)((const char*)(gbase) + (voff)[_i]), (LAS unsigned*)(lds + (bufoff) + ldsw + _i * 8192), 16, 0, 0); } while (0)
; #define PG8_LDA(dst, b, h) do { _Pragma("unroll") for (int m = 0; m < 4; ++m) _Pragma("unroll") for (int k = 0; k < 2; ++k) dst[m][k] = *(const LAS bf16x8*)(lds + PG8_SA(b, h) + aoff + m * 2048 + k * 1024); } while (0)
; #define PG8_LDB(dst, b, h) do { _Pragma("unroll") for (int n = 0; n < 2; ++n) _Pragma("unroll") for (int k = 0; k < 2; ++k) dst[n][k] = *(const LAS bf16x8*)(lds + PG8_SB(b, h) + boff + n * 2048 + k * 1024); } while (0)
; #define PG8_MMA(ai, bj, At, Bt) do { __builtin_amdgcn_s_setprio(1); _Pragma("unroll") for (int m = 0; m < 4; ++m) _Pragma("unroll") for (int n = 0; n < 2; ++n) _Pragma("unroll") for (int k = 0; k < 2; ++k) \
;         acc[ai][bj][m][n] = __builtin_amdgcn_mfma_f32_16x16x32_bf16(Bt[n][k], At[m][k], acc[ai][bj][m][n], 0, 0, 0); __builtin_amdgcn_s_setprio(0); } while (0)
; #define PG8_WAIT_V(n) asm volatile("s_waitcnt vmcnt(" #n ")" ::: "memory")
; #define PG8_BAR __builtin_amdgcn_s_barrier()
; template <class Epi, class Sched, bool ABLK = false, bool ALIGN_EPI = true, bool SP2 = true, bool BBLK = true>
; __device__ __forceinline__ void gemm_phase(LAS unsigned char* lds, const Gemm g, const Sched& S, const Epi& E) {
;     ...
;             const bool last = (t == nt - 2);
;             const char* a1 = a_tile(uA, tbA + t + 1);
;             const char* a2 = last ? a_tile(nuA, ntbA) : a_tile(uA, tbA + t + 2); const char* b2 = last ? nB : cB + (size_t)(t + 2) * kstepB;
;             const char* a3 = last ? a_tile(nuA, ntbA + 1) : a_tile(uA, tbA + t + 3); const char* b3 = b2 + kstepB;
;             if (last && has_next) S.a_ready(nxt);
;             if constexpr (SP2) {
;             PG8_LDB(B0, 0, 0); PG8_LDB(B1, 0, 1); PG8_SCHED; PG8_LDA(At, 0, 0); PG8_STAGE(PG8_SA(1, 1), a1 + hstepA, voffA);
;             PG8_WAIT_V(8); PG8_WAIT_L(0); PG8_BAR; PG8_MMA(0, 0, At, B0); PG8_MMA(0, 1, At, B1); PG8_BAR; PG8_SCHED;
;             PG8_LDA(At, 0, 1); PG8_STAGE(PG8_SB(0, 0), b2, voffB); PG8_STAGE(PG8_SB(0, 1), b2 + hstepB, voffB); PG8_STAGE(PG8_SA(0, 0), a2, voffA);
;             PG8_WAIT_V(8); PG8_WAIT_L(0); PG8_BAR; PG8_MMA(1, 0, At, B0); PG8_MMA(1, 1, At, B1); PG8_BAR; PG8_SCHED;
.LBB0_2138:
	ds_read_b128 v[152:155], v148
	ds_read_b128 v[156:159], v148 offset:1024
	ds_read_b128 v[160:163], v148 offset:2048
	ds_read_b128 v[164:167], v148 offset:3072
	ds_read_b128 v[168:171], v149
	ds_read_b128 v[172:175], v149 offset:1024
	ds_read_b128 v[176:179], v149 offset:2048
	ds_read_b128 v[180:183], v149 offset:3072
	s_add_u32 s28, s24, s26
	s_addc_u32 s29, s25, s27
	s_add_u32 s34, s28, 0x100
	s_addc_u32 s35, s29, 0
	s_add_u32 s28, s28, 0x180
	s_addc_u32 s29, s29, 0
	s_cmpk_eq_i32 s26, 0xf00
	s_cselect_b32 s29, s49, s29
	s_cselect_b32 s28, s48, s28
	s_cselect_b32 s31, s11, s51
	s_cselect_b32 s30, s13, s50
	s_cselect_b32 s35, s4, s35
	s_cselect_b32 s34, s5, s34
	s_mov_b32 m0, s47
	v_lshl_add_u64 v[216:217], v[142:143], 0, s[26:27]
	ds_read_b128 v[184:187], v150
	ds_read_b128 v[188:191], v150 offset:1024
	ds_read_b128 v[192:195], v150 offset:2048
	ds_read_b128 v[196:199], v150 offset:3072
	ds_read_b128 v[200:203], v150 offset:4096
	ds_read_b128 v[204:207], v150 offset:5120
	ds_read_b128 v[208:211], v150 offset:6144
	ds_read_b128 v[212:215], v150 offset:7168
	global_load_lds_dwordx4 v[216:217], off
	v_lshl_add_u64 v[216:217], v[144:145], 0, s[26:27]
	s_add_i32 m0, s21, 0xe000
	s_nop 0
	global_load_lds_dwordx4 v[216:217], off
	s_waitcnt vmcnt(8) lgkmcnt(0)
	s_barrier
	v_mfma_f32_16x16x32_bf16 v[122:125], v[152:155], v[184:187], v[122:125]
	v_mfma_f32_16x16x32_bf16 v[118:121], v[160:163], v[184:187], v[118:121]
	v_mfma_f32_16x16x32_bf16 v[106:109], v[152:155], v[192:195], v[106:109]
	v_mfma_f32_16x16x32_bf16 v[102:105], v[160:163], v[192:195], v[102:105]
	v_mfma_f32_16x16x32_bf16 v[90:93], v[152:155], v[200:203], v[90:93]
	v_mfma_f32_16x16x32_bf16 v[86:89], v[160:163], v[200:203], v[86:89]
	v_mfma_f32_16x16x32_bf16 v[74:77], v[152:155], v[208:211], v[74:77]
	v_mfma_f32_16x16x32_bf16 v[70:73], v[160:163], v[208:211], v[70:73]
	v_mfma_f32_16x16x32_bf16 v[122:125], v[156:159], v[188:191], v[122:125]
	v_mfma_f32_16x16x32_bf16 v[118:121], v[164:167], v[188:191], v[118:121]
	v_mfma_f32_16x16x32_bf16 v[106:109], v[156:159], v[196:199], v[106:109]
	v_mfma_f32_16x16x32_bf16 v[102:105], v[164:167], v[196:199], v[102:105]
	v_mfma_f32_16x16x32_bf16 v[90:93], v[156:159], v[204:207], v[90:93]
	v_mfma_f32_16x16x32_bf16 v[86:89], v[164:167], v[204:207], v[86:89]
	v_mfma_f32_16x16x32_bf16 v[74:77], v[156:159], v[212:215], v[74:77]
	v_mfma_f32_16x16x32_bf16 v[70:73], v[164:167], v[212:215], v[70:73]
	v_mfma_f32_16x16x32_bf16 v[126:129], v[168:171], v[184:187], v[126:129]
	v_mfma_f32_16x16x32_bf16 v[114:117], v[176:179], v[184:187], v[114:117]
	v_mfma_f32_16x16x32_bf16 v[110:113], v[168:171], v[192:195], v[110:113]
	v_mfma_f32_16x16x32_bf16 v[98:101], v[176:179], v[192:195], v[98:101]
	v_mfma_f32_16x16x32_bf16 v[94:97], v[168:171], v[200:203], v[94:97]
	v_mfma_f32_16x16x32_bf16 v[82:85], v[176:179], v[200:203], v[82:85]
	v_mfma_f32_16x16x32_bf16 v[78:81], v[168:171], v[208:211], v[78:81]
	v_mfma_f32_16x16x32_bf16 v[66:69], v[176:179], v[208:211], v[66:69]
	v_mfma_f32_16x16x32_bf16 v[126:129], v[172:175], v[188:191], v[126:129]
	v_mfma_f32_16x16x32_bf16 v[114:117], v[180:183], v[188:191], v[114:117]
	v_mfma_f32_16x16x32_bf16 v[110:113], v[172:175], v[196:199], v[110:113]
	v_mfma_f32_16x16x32_bf16 v[98:101], v[180:183], v[196:199], v[98:101]
	v_mfma_f32_16x16x32_bf16 v[94:97], v[172:175], v[204:207], v[94:97]
	v_mfma_f32_16x16x32_bf16 v[82:85], v[180:183], v[204:207], v[82:85]
	v_mfma_f32_16x16x32_bf16 v[78:81], v[172:175], v[212:215], v[78:81]
	v_mfma_f32_16x16x32_bf16 v[66:69], v[180:183], v[212:215], v[66:69]
	s_barrier
	s_add_i32 s53, s72, s36
	s_mov_b32 m0, s53
	ds_read_b128 v[184:187], v150 offset:16384
	ds_read_b128 v[188:191], v150 offset:17408
	ds_read_b128 v[192:195], v150 offset:18432
	ds_read_b128 v[196:199], v150 offset:19456
	ds_read_b128 v[200:203], v150 offset:20480
	ds_read_b128 v[204:207], v150 offset:21504
	ds_read_b128 v[208:211], v150 offset:22528
	ds_read_b128 v[212:215], v150 offset:23552
	global_load_lds_dwordx4 v134, s[30:31]
	s_add_i32 m0, s53, 0x2000
	s_add_u32 s54, s30, 0x4000
	s_addc_u32 s55, s31, 0
	s_add_i32 s53, s73, s36
	global_load_lds_dwordx4 v130, s[30:31]
	s_mov_b32 m0, s53
	s_nop 0
	global_load_lds_dwordx4 v134, s[54:55]
	s_add_i32 m0, s53, 0x2000
	s_nop 0
	global_load_lds_dwordx4 v130, s[54:55]
	s_mov_b32 m0, s21
	s_nop 0
	global_load_lds_dwordx4 v136, s[34:35]
	s_mov_b32 m0, s23
	s_nop 0
	global_load_lds_dwordx4 v132, s[34:35]
	s_waitcnt vmcnt(8) lgkmcnt(0)
	s_barrier
	v_mfma_f32_16x16x32_bf16 v[58:61], v[152:155], v[184:187], v[58:61]
	v_mfma_f32_16x16x32_bf16 v[54:57], v[160:163], v[184:187], v[54:57]
	v_mfma_f32_16x16x32_bf16 v[42:45], v[152:155], v[192:195], v[42:45]
	v_mfma_f32_16x16x32_bf16 v[38:41], v[160:163], v[192:195], v[38:41]
	v_mfma_f32_16x16x32_bf16 v[26:29], v[152:155], v[200:203], v[26:29]
	v_mfma_f32_16x16x32_bf16 v[22:25], v[160:163], v[200:203], v[22:25]
	v_mfma_f32_16x16x32_bf16 v[10:13], v[152:155], v[208:211], v[10:13]
	v_mfma_f32_16x16x32_bf16 v[6:9], v[160:163], v[208:211], v[6:9]
	v_mfma_f32_16x16x32_bf16 v[58:61], v[156:159], v[188:191], v[58:61]
	v_mfma_f32_16x16x32_bf16 v[54:57], v[164:167], v[188:191], v[54:57]
	v_mfma_f32_16x16x32_bf16 v[42:45], v[156:159], v[196:199], v[42:45]
	v_mfma_f32_16x16x32_bf16 v[38:41], v[164:167], v[196:199], v[38:41]
	v_mfma_f32_16x16x32_bf16 v[26:29], v[156:159], v[204:207], v[26:29]
	v_mfma_f32_16x16x32_bf16 v[22:25], v[164:167], v[204:207], v[22:25]
	v_mfma_f32_16x16x32_bf16 v[10:13], v[156:159], v[212:215], v[10:13]
	v_mfma_f32_16x16x32_bf16 v[6:9], v[164:167], v[212:215], v[6:9]
	v_mfma_f32_16x16x32_bf16 v[62:65], v[168:171], v[184:187], v[62:65]
	v_mfma_f32_16x16x32_bf16 v[50:53], v[176:179], v[184:187], v[50:53]
	v_mfma_f32_16x16x32_bf16 v[46:49], v[168:171], v[192:195], v[46:49]
	v_mfma_f32_16x16x32_bf16 v[34:37], v[176:179], v[192:195], v[34:37]
	v_mfma_f32_16x16x32_bf16 v[30:33], v[168:171], v[200:203], v[30:33]
	v_mfma_f32_16x16x32_bf16 v[18:21], v[176:179], v[200:203], v[18:21]
	v_mfma_f32_16x16x32_bf16 v[14:17], v[168:171], v[208:211], v[14:17]
	v_mfma_f32_16x16x32_bf16 v[2:5], v[176:179], v[208:211], v[2:5]
	v_mfma_f32_16x16x32_bf16 v[62:65], v[172:175], v[188:191], v[62:65]
	v_mfma_f32_16x16x32_bf16 v[50:53], v[180:183], v[188:191], v[50:53]
	v_mfma_f32_16x16x32_bf16 v[46:49], v[172:175], v[196:199], v[46:49]
	v_mfma_f32_16x16x32_bf16 v[34:37], v[180:183], v[196:199], v[34:37]
	v_mfma_f32_16x16x32_bf16 v[30:33], v[172:175], v[204:207], v[30:33]
	v_mfma_f32_16x16x32_bf16 v[18:21], v[180:183], v[204:207], v[18:21]
	v_mfma_f32_16x16x32_bf16 v[14:17], v[172:175], v[212:215], v[14:17]
	v_mfma_f32_16x16x32_bf16 v[2:5], v[180:183], v[212:215], v[2:5]
	s_barrier
; #define PG8_STAGE(bufoff, gbase, voff) do { _Pragma("unroll") for (int _i = 0; _i < 2; ++_i) \
;         __builtin_amdgcn_global_load_lds((const unsigned*)((const char*)(gbase) + (voff)[_i]), (LAS unsigned*)(lds + (bufoff) + ldsw + _i * 8192), 16, 0, 0); } while (0)
; #define PG8_LDA(dst, b, h) do { _Pragma("unroll") for (int m = 0; m < 4; ++m) _Pragma("unroll") for (int k = 0; k < 2; ++k) dst[m][k] = *(const LAS bf16x8*)(lds + PG8_SA(b, h) + aoff + m * 2048 + k * 1024); } while (0)
; #define PG8_LDB(dst, b, h) do { _Pragma("unroll") for (int n = 0; n < 2; ++n) _Pragma("unroll") for (int k = 0; k < 2; ++k) dst[n][k] = *(const LAS bf16x8*)(lds + PG8_SB(b, h) + boff + n * 2048 + k * 1024); } while (0)
; #define PG8_MMA(ai, bj, At, Bt) do { __builtin_amdgcn_s_setprio(1); _Pragma("unroll") for (int m = 0; m < 4; ++m) _Pragma("unroll") for (int n = 0; n < 2; ++n) _Pragma("unroll") for (int k = 0; k < 2; ++k) \
;         acc[ai][bj][m][n] = __builtin_amdgcn_mfma_f32_16x16x32_bf16(Bt[n][k], At[m][k], acc[ai][bj][m][n], 0, 0, 0); __builtin_amdgcn_s_setprio(0); } while (0)
; #define PG8_WAIT_V(n) asm volatile("s_waitcnt vmcnt(" #n ")" ::: "memory")
; #define PG8_WAIT_L(n) asm volatile("s_waitcnt lgkmcnt(" #n ")" ::: "memory")
; #define PG8_BAR __builtin_amdgcn_s_barrier()
; #define PG8_SCHED __builtin_amdgcn_sched_barrier(0)
; template <class Epi, class Sched, bool ABLK = false, bool ALIGN_EPI = true, bool SP2 = true, bool BBLK = true>
; __device__ __forceinline__ void gemm_phase(LAS unsigned char* lds, const Gemm g, const Sched& S, const Epi& E) {
;     ...
;         for (int t = 0; t < nt; t += 2) {
;     ...
;             PG8_LDB(B0, 1, 0); PG8_LDB(B1, 1, 1); PG8_SCHED; PG8_LDA(At, 1, 0); PG8_STAGE(PG8_SA(0, 1), a2 + hstepA, voffA);
;             PG8_WAIT_V(8); PG8_WAIT_L(0); PG8_BAR; PG8_MMA(0, 0, At, B0); PG8_MMA(0, 1, At, B1); PG8_BAR; PG8_SCHED;
;             PG8_LDA(At, 1, 1); PG8_STAGE(PG8_SB(1, 0), b3, voffB); PG8_STAGE(PG8_SB(1, 1), b3 + hstepB, voffB); PG8_STAGE(PG8_SA(1, 0), a3, voffA);
;             PG8_WAIT_V(8); PG8_WAIT_L(0); PG8_BAR; PG8_MMA(1, 0, At, B0); PG8_MMA(1, 1, At, B1); PG8_BAR; PG8_SCHED;
	v_add_u32_e32 v151, s60, v146
	ds_read_b128 v[152:155], v151
	ds_read_b128 v[156:159], v151 offset:1024
	ds_read_b128 v[160:163], v151 offset:2048
	ds_read_b128 v[164:167], v151 offset:3072
	v_add_u32_e32 v151, s61, v146
	ds_read_b128 v[168:171], v151
	ds_read_b128 v[172:175], v151 offset:1024
	ds_read_b128 v[176:179], v151 offset:2048
	ds_read_b128 v[180:183], v151 offset:3072
	s_add_u32 s34, s34, 0x80000
	s_addc_u32 s35, s35, 0
	s_mov_b32 m0, s39
	ds_read_b128 v[184:187], v150 offset:32768
	ds_read_b128 v[188:191], v150 offset:33792
	ds_read_b128 v[192:195], v150 offset:34816
	ds_read_b128 v[196:199], v150 offset:35840
	ds_read_b128 v[200:203], v150 offset:36864
	ds_read_b128 v[204:207], v150 offset:37888
	ds_read_b128 v[208:211], v150 offset:38912
	ds_read_b128 v[212:215], v150 offset:39936
	global_load_lds_dwordx4 v136, s[34:35]
	s_mov_b32 m0, s40
	s_nop 0
	global_load_lds_dwordx4 v132, s[34:35]
	s_waitcnt vmcnt(8) lgkmcnt(0)
	s_barrier
	v_mfma_f32_16x16x32_bf16 v[122:125], v[152:155], v[184:187], v[122:125]
	v_mfma_f32_16x16x32_bf16 v[118:121], v[160:163], v[184:187], v[118:121]
	v_mfma_f32_16x16x32_bf16 v[106:109], v[152:155], v[192:195], v[106:109]
	v_mfma_f32_16x16x32_bf16 v[102:105], v[160:163], v[192:195], v[102:105]
	v_mfma_f32_16x16x32_bf16 v[90:93], v[152:155], v[200:203], v[90:93]
	v_mfma_f32_16x16x32_bf16 v[86:89], v[160:163], v[200:203], v[86:89]
	v_mfma_f32_16x16x32_bf16 v[74:77], v[152:155], v[208:211], v[74:77]
	v_mfma_f32_16x16x32_bf16 v[70:73], v[160:163], v[208:211], v[70:73]
	v_mfma_f32_16x16x32_bf16 v[122:125], v[156:159], v[188:191], v[122:125]
	v_mfma_f32_16x16x32_bf16 v[118:121], v[164:167], v[188:191], v[118:121]
	v_mfma_f32_16x16x32_bf16 v[106:109], v[156:159], v[196:199], v[106:109]
	v_mfma_f32_16x16x32_bf16 v[102:105], v[164:167], v[196:199], v[102:105]
	v_mfma_f32_16x16x32_bf16 v[90:93], v[156:159], v[204:207], v[90:93]
	v_mfma_f32_16x16x32_bf16 v[86:89], v[164:167], v[204:207], v[86:89]
	v_mfma_f32_16x16x32_bf16 v[74:77], v[156:159], v[212:215], v[74:77]
	v_mfma_f32_16x16x32_bf16 v[70:73], v[164:167], v[212:215], v[70:73]
	v_mfma_f32_16x16x32_bf16 v[126:129], v[168:171], v[184:187], v[126:129]
	v_mfma_f32_16x16x32_bf16 v[114:117], v[176:179], v[184:187], v[114:117]
	v_mfma_f32_16x16x32_bf16 v[110:113], v[168:171], v[192:195], v[110:113]
	v_mfma_f32_16x16x32_bf16 v[98:101], v[176:179], v[192:195], v[98:101]
	v_mfma_f32_16x16x32_bf16 v[94:97], v[168:171], v[200:203], v[94:97]
	v_mfma_f32_16x16x32_bf16 v[82:85], v[176:179], v[200:203], v[82:85]
	v_mfma_f32_16x16x32_bf16 v[78:81], v[168:171], v[208:211], v[78:81]
	v_mfma_f32_16x16x32_bf16 v[66:69], v[176:179], v[208:211], v[66:69]
	v_mfma_f32_16x16x32_bf16 v[126:129], v[172:175], v[188:191], v[126:129]
	v_mfma_f32_16x16x32_bf16 v[114:117], v[180:183], v[188:191], v[114:117]
	v_mfma_f32_16x16x32_bf16 v[110:113], v[172:175], v[196:199], v[110:113]
	v_mfma_f32_16x16x32_bf16 v[98:101], v[180:183], v[196:199], v[98:101]
	v_mfma_f32_16x16x32_bf16 v[94:97], v[172:175], v[204:207], v[94:97]
	v_mfma_f32_16x16x32_bf16 v[82:85], v[180:183], v[204:207], v[82:85]
	v_mfma_f32_16x16x32_bf16 v[78:81], v[172:175], v[212:215], v[78:81]
	v_mfma_f32_16x16x32_bf16 v[66:69], v[180:183], v[212:215], v[66:69]
	s_barrier
	s_add_u32 s34, s30, 0x8000
	s_addc_u32 s35, s31, 0
	s_add_i32 s53, s60, s36
	s_mov_b32 m0, s53
	ds_read_b128 v[184:187], v150 offset:49152
	ds_read_b128 v[188:191], v150 offset:50176
	ds_read_b128 v[192:195], v150 offset:51200
	ds_read_b128 v[196:199], v150 offset:52224
	ds_read_b128 v[200:203], v150 offset:53248
	ds_read_b128 v[204:207], v150 offset:54272
	ds_read_b128 v[208:211], v150 offset:55296
	ds_read_b128 v[212:215], v150 offset:56320
	global_load_lds_dwordx4 v134, s[34:35]
	s_add_i32 m0, s53, 0x2000
	s_add_u32 s30, s30, 0xc000
	v_lshl_add_u64 v[216:217], s[34:35], 0, v[130:131]
	s_addc_u32 s31, s31, 0
	s_add_i32 s34, s61, s36
	global_load_lds_dwordx4 v[216:217], off
	s_mov_b32 m0, s34
	s_nop 0
	global_load_lds_dwordx4 v134, s[30:31]
	s_add_i32 m0, s34, 0x2000
	s_nop 0
	global_load_lds_dwordx4 v130, s[30:31]
	s_mov_b32 m0, s42
	s_nop 0
	global_load_lds_dwordx4 v136, s[28:29]
	s_mov_b32 m0, s43
	s_nop 0
	global_load_lds_dwordx4 v132, s[28:29]
	s_waitcnt vmcnt(8) lgkmcnt(0)
	s_barrier
	v_mfma_f32_16x16x32_bf16 v[58:61], v[152:155], v[184:187], v[58:61]
	v_mfma_f32_16x16x32_bf16 v[54:57], v[160:163], v[184:187], v[54:57]
	v_mfma_f32_16x16x32_bf16 v[42:45], v[152:155], v[192:195], v[42:45]
	v_mfma_f32_16x16x32_bf16 v[38:41], v[160:163], v[192:195], v[38:41]
	v_mfma_f32_16x16x32_bf16 v[26:29], v[152:155], v[200:203], v[26:29]
	v_mfma_f32_16x16x32_bf16 v[22:25], v[160:163], v[200:203], v[22:25]
	v_mfma_f32_16x16x32_bf16 v[10:13], v[152:155], v[208:211], v[10:13]
	v_mfma_f32_16x16x32_bf16 v[6:9], v[160:163], v[208:211], v[6:9]
	v_mfma_f32_16x16x32_bf16 v[58:61], v[156:159], v[188:191], v[58:61]
	v_mfma_f32_16x16x32_bf16 v[54:57], v[164:167], v[188:191], v[54:57]
	v_mfma_f32_16x16x32_bf16 v[42:45], v[156:159], v[196:199], v[42:45]
	v_mfma_f32_16x16x32_bf16 v[38:41], v[164:167], v[196:199], v[38:41]
	v_mfma_f32_16x16x32_bf16 v[26:29], v[156:159], v[204:207], v[26:29]
	v_mfma_f32_16x16x32_bf16 v[22:25], v[164:167], v[204:207], v[22:25]
	v_mfma_f32_16x16x32_bf16 v[10:13], v[156:159], v[212:215], v[10:13]
	v_mfma_f32_16x16x32_bf16 v[6:9], v[164:167], v[212:215], v[6:9]
	v_mfma_f32_16x16x32_bf16 v[62:65], v[168:171], v[184:187], v[62:65]
	v_mfma_f32_16x16x32_bf16 v[50:53], v[176:179], v[184:187], v[50:53]
	v_mfma_f32_16x16x32_bf16 v[46:49], v[168:171], v[192:195], v[46:49]
	v_mfma_f32_16x16x32_bf16 v[34:37], v[176:179], v[192:195], v[34:37]
	v_mfma_f32_16x16x32_bf16 v[30:33], v[168:171], v[200:203], v[30:33]
	v_mfma_f32_16x16x32_bf16 v[18:21], v[176:179], v[200:203], v[18:21]
	v_mfma_f32_16x16x32_bf16 v[14:17], v[168:171], v[208:211], v[14:17]
	v_mfma_f32_16x16x32_bf16 v[2:5], v[176:179], v[208:211], v[2:5]
	v_mfma_f32_16x16x32_bf16 v[62:65], v[172:175], v[188:191], v[62:65]
	v_mfma_f32_16x16x32_bf16 v[50:53], v[180:183], v[188:191], v[50:53]
	v_mfma_f32_16x16x32_bf16 v[46:49], v[172:175], v[196:199], v[46:49]
	v_mfma_f32_16x16x32_bf16 v[34:37], v[180:183], v[196:199], v[34:37]
	v_mfma_f32_16x16x32_bf16 v[30:33], v[172:175], v[204:207], v[30:33]
	v_mfma_f32_16x16x32_bf16 v[18:21], v[180:183], v[204:207], v[18:21]
	v_mfma_f32_16x16x32_bf16 v[14:17], v[172:175], v[212:215], v[14:17]
	v_mfma_f32_16x16x32_bf16 v[2:5], v[180:183], v[212:215], v[2:5]
	s_barrier
	s_add_i32 s52, s52, 2
	s_add_u32 s26, s26, 0x100
	s_addc_u32 s27, s27, 0
	s_add_u32 s50, s50, 0x10000
	s_addc_u32 s51, s51, 0
	s_cmp_gt_u32 s52, 29
	s_cbranch_scc0 .LBB0_2138
	s_and_b64 vcc, exec, s[6:7]
	s_cbranch_vccz .LBB0_2141
	s_barrier

; #define PG8_STAGE(bufoff, gbase, voff) do { _Pragma("unroll") for (int _i = 0; _i < 2; ++_i) \
;         __builtin_amdgcn_global_load_lds((const unsigned*)((const char*)(gbase) + (voff)[_i]), (LAS unsigned*)(lds + (bufoff) + ldsw + _i * 8192), 16, 0, 0); } while (0)
; #define PG8_LDA(dst, b, h) do { _Pragma("unroll") for (int m = 0; m < 4; ++m) _Pragma("unroll") for (int k = 0; k < 2; ++k) dst[m][k] = *(const LAS bf16x8*)(lds + PG8_SA(b, h) + aoff + m * 2048 + k * 1024); } while (0)
; #define PG8_LDB(dst, b, h) do { _Pragma("unroll") for (int n = 0; n < 2; ++n) _Pragma("unroll") for (int k = 0; k < 2; ++k) dst[n][k] = *(const LAS bf16x8*)(lds + PG8_SB(b, h) + boff + n * 2048 + k * 1024); } while (0)
; #define PG8_MMA(ai, bj, At, Bt) do { __builtin_amdgcn_s_setprio(1); _Pragma("unroll") for (int m = 0; m < 4; ++m) _Pragma("unroll") for (int n = 0; n < 2; ++n) _Pragma("unroll") for (int k = 0; k < 2; ++k) \
;         acc[ai][bj][m][n] = __builtin_amdgcn_mfma_f32_16x16x32_bf16(Bt[n][k], At[m][k], acc[ai][bj][m][n], 0, 0, 0); __builtin_amdgcn_s_setprio(0); } while (0)
; #define PG8_WAIT_V(n) asm volatile("s_waitcnt vmcnt(" #n ")" ::: "memory")
; #define PG8_BAR __builtin_amdgcn_s_barrier()
; template <class Epi, class Sched, bool ABLK = false, bool ALIGN_EPI = true, bool SP2 = true, bool BBLK = true>
; __device__ __forceinline__ void gemm_phase(LAS unsigned char* lds, const Gemm g, const Sched& S, const Epi& E) {
;     ...
;             const bool last = (t == nt - 2);
;             const char* a1 = a_tile(uA, tbA + t + 1);
;             const char* a2 = last ? a_tile(nuA, ntbA) : a_tile(uA, tbA + t + 2); const char* b2 = last ? nB : cB + (size_t)(t + 2) * kstepB;
;             const char* a3 = last ? a_tile(nuA, ntbA + 1) : a_tile(uA, tbA + t + 3); const char* b3 = b2 + kstepB;
;             if (last && has_next) S.a_ready(nxt);
;             if constexpr (SP2) {
;             PG8_LDB(B0, 0, 0); PG8_LDB(B1, 0, 1); PG8_SCHED; PG8_LDA(At, 0, 0); PG8_STAGE(PG8_SA(1, 1), a1 + hstepA, voffA);
;             PG8_WAIT_V(8); PG8_WAIT_L(0); PG8_BAR; PG8_MMA(0, 0, At, B0); PG8_MMA(0, 1, At, B1); PG8_BAR; PG8_SCHED;
;             PG8_LDA(At, 0, 1); PG8_STAGE(PG8_SB(0, 0), b2, voffB); PG8_STAGE(PG8_SB(0, 1), b2 + hstepB, voffB); PG8_STAGE(PG8_SA(0, 0), a2, voffA);
;             PG8_WAIT_V(8); PG8_WAIT_L(0); PG8_BAR; PG8_MMA(1, 0, At, B0); PG8_MMA(1, 1, At, B1); PG8_BAR; PG8_SCHED;
.LBB0_2263:
	ds_read_b128 v[172:175], v168
	ds_read_b128 v[176:179], v168 offset:1024
	ds_read_b128 v[180:183], v168 offset:2048
	ds_read_b128 v[184:187], v168 offset:3072
	ds_read_b128 v[188:191], v169
	ds_read_b128 v[192:195], v169 offset:1024
	ds_read_b128 v[196:199], v169 offset:2048
	ds_read_b128 v[200:203], v169 offset:3072
	s_add_u32 s30, s26, s28
	s_addc_u32 s31, s27, s29
	s_add_u32 s36, s30, 0x100
	s_addc_u32 s37, s31, 0
	s_add_u32 s30, s30, 0x180
	s_addc_u32 s31, s31, 0
	s_cmpk_eq_i32 s28, 0xf00
	s_cselect_b32 s31, s54, s31
	s_cselect_b32 s30, s23, s30
	s_cselect_b32 s35, s13, s56
	s_cselect_b32 s34, s15, s55
	s_cselect_b32 s37, s4, s37
	s_cselect_b32 s36, s5, s36
	s_mov_b32 m0, s50
	v_lshl_add_u64 v[236:237], v[164:165], 0, s[28:29]
	ds_read_b128 v[204:207], v170
	ds_read_b128 v[208:211], v170 offset:1024
	ds_read_b128 v[212:215], v170 offset:2048
	ds_read_b128 v[216:219], v170 offset:3072
	ds_read_b128 v[220:223], v170 offset:4096
	ds_read_b128 v[224:227], v170 offset:5120
	ds_read_b128 v[228:231], v170 offset:6144
	ds_read_b128 v[232:235], v170 offset:7168
	global_load_lds_dwordx4 v[236:237], off
	v_lshl_add_u64 v[236:237], v[166:167], 0, s[28:29]
	s_mov_b32 m0, s51
	s_nop 0
	global_load_lds_dwordx4 v[236:237], off
	s_waitcnt vmcnt(8) lgkmcnt(0)
	s_barrier
	v_mfma_f32_16x16x32_bf16 v[126:129], v[172:175], v[204:207], v[126:129]
	v_mfma_f32_16x16x32_bf16 v[122:125], v[180:183], v[204:207], v[122:125]
	v_mfma_f32_16x16x32_bf16 v[110:113], v[172:175], v[212:215], v[110:113]
	v_mfma_f32_16x16x32_bf16 v[106:109], v[180:183], v[212:215], v[106:109]
	v_mfma_f32_16x16x32_bf16 v[94:97], v[172:175], v[220:223], v[94:97]
	v_mfma_f32_16x16x32_bf16 v[90:93], v[180:183], v[220:223], v[90:93]
	v_mfma_f32_16x16x32_bf16 v[78:81], v[172:175], v[228:231], v[78:81]
	v_mfma_f32_16x16x32_bf16 v[74:77], v[180:183], v[228:231], v[74:77]
	v_mfma_f32_16x16x32_bf16 v[126:129], v[176:179], v[208:211], v[126:129]
	v_mfma_f32_16x16x32_bf16 v[122:125], v[184:187], v[208:211], v[122:125]
	v_mfma_f32_16x16x32_bf16 v[110:113], v[176:179], v[216:219], v[110:113]
	v_mfma_f32_16x16x32_bf16 v[106:109], v[184:187], v[216:219], v[106:109]
	v_mfma_f32_16x16x32_bf16 v[94:97], v[176:179], v[224:227], v[94:97]
	v_mfma_f32_16x16x32_bf16 v[90:93], v[184:187], v[224:227], v[90:93]
	v_mfma_f32_16x16x32_bf16 v[78:81], v[176:179], v[232:235], v[78:81]
	v_mfma_f32_16x16x32_bf16 v[74:77], v[184:187], v[232:235], v[74:77]
	v_mfma_f32_16x16x32_bf16 v[118:121], v[188:191], v[204:207], v[118:121]
	v_mfma_f32_16x16x32_bf16 v[114:117], v[196:199], v[204:207], v[114:117]
	v_mfma_f32_16x16x32_bf16 v[102:105], v[188:191], v[212:215], v[102:105]
	v_mfma_f32_16x16x32_bf16 v[98:101], v[196:199], v[212:215], v[98:101]
	v_mfma_f32_16x16x32_bf16 v[86:89], v[188:191], v[220:223], v[86:89]
	v_mfma_f32_16x16x32_bf16 v[82:85], v[196:199], v[220:223], v[82:85]
	v_mfma_f32_16x16x32_bf16 v[70:73], v[188:191], v[228:231], v[70:73]
	v_mfma_f32_16x16x32_bf16 v[66:69], v[196:199], v[228:231], v[66:69]
	v_mfma_f32_16x16x32_bf16 v[118:121], v[192:195], v[208:211], v[118:121]
	v_mfma_f32_16x16x32_bf16 v[114:117], v[200:203], v[208:211], v[114:117]
	v_mfma_f32_16x16x32_bf16 v[102:105], v[192:195], v[216:219], v[102:105]
	v_mfma_f32_16x16x32_bf16 v[98:101], v[200:203], v[216:219], v[98:101]
	v_mfma_f32_16x16x32_bf16 v[86:89], v[192:195], v[224:227], v[86:89]
	v_mfma_f32_16x16x32_bf16 v[82:85], v[200:203], v[224:227], v[82:85]
	v_mfma_f32_16x16x32_bf16 v[70:73], v[192:195], v[232:235], v[70:73]
	v_mfma_f32_16x16x32_bf16 v[66:69], v[200:203], v[232:235], v[66:69]
	s_barrier
	s_mov_b32 m0, s52
	s_add_u32 s58, s34, 0x4000
	ds_read_b128 v[204:207], v170 offset:16384
	ds_read_b128 v[208:211], v170 offset:17408
	ds_read_b128 v[212:215], v170 offset:18432
	ds_read_b128 v[216:219], v170 offset:19456
	ds_read_b128 v[220:223], v170 offset:20480
	ds_read_b128 v[224:227], v170 offset:21504
	ds_read_b128 v[228:231], v170 offset:22528
	ds_read_b128 v[232:235], v170 offset:23552
	global_load_lds_dwordx4 v134, s[34:35]
	s_mov_b32 m0, s53
	s_addc_u32 s59, s35, 0
	s_add_i32 s62, s73, s40
	global_load_lds_dwordx4 v130, s[34:35]
	s_mov_b32 m0, s62
	s_nop 0
	global_load_lds_dwordx4 v134, s[58:59]
	s_add_i32 m0, s62, 0x2000
	s_nop 0
	global_load_lds_dwordx4 v130, s[58:59]
	s_mov_b32 m0, s25
	s_nop 0
	global_load_lds_dwordx4 v136, s[36:37]
	s_mov_b32 m0, s43
	s_nop 0
	global_load_lds_dwordx4 v132, s[36:37]
	s_waitcnt vmcnt(8) lgkmcnt(0)
	s_barrier
	v_mfma_f32_16x16x32_bf16 v[62:65], v[172:175], v[204:207], v[62:65]
	v_mfma_f32_16x16x32_bf16 v[58:61], v[180:183], v[204:207], v[58:61]
	v_mfma_f32_16x16x32_bf16 v[46:49], v[172:175], v[212:215], v[46:49]
	v_mfma_f32_16x16x32_bf16 v[42:45], v[180:183], v[212:215], v[42:45]
	v_mfma_f32_16x16x32_bf16 v[30:33], v[172:175], v[220:223], v[30:33]
	v_mfma_f32_16x16x32_bf16 v[26:29], v[180:183], v[220:223], v[26:29]
	v_mfma_f32_16x16x32_bf16 v[14:17], v[172:175], v[228:231], v[14:17]
	v_mfma_f32_16x16x32_bf16 v[10:13], v[180:183], v[228:231], v[10:13]
	v_mfma_f32_16x16x32_bf16 v[62:65], v[176:179], v[208:211], v[62:65]
	v_mfma_f32_16x16x32_bf16 v[58:61], v[184:187], v[208:211], v[58:61]
	v_mfma_f32_16x16x32_bf16 v[46:49], v[176:179], v[216:219], v[46:49]
	v_mfma_f32_16x16x32_bf16 v[42:45], v[184:187], v[216:219], v[42:45]
	v_mfma_f32_16x16x32_bf16 v[30:33], v[176:179], v[224:227], v[30:33]
	v_mfma_f32_16x16x32_bf16 v[26:29], v[184:187], v[224:227], v[26:29]
	v_mfma_f32_16x16x32_bf16 v[14:17], v[176:179], v[232:235], v[14:17]
	v_mfma_f32_16x16x32_bf16 v[10:13], v[184:187], v[232:235], v[10:13]
	v_mfma_f32_16x16x32_bf16 v[54:57], v[188:191], v[204:207], v[54:57]
	v_mfma_f32_16x16x32_bf16 v[50:53], v[196:199], v[204:207], v[50:53]
	v_mfma_f32_16x16x32_bf16 v[38:41], v[188:191], v[212:215], v[38:41]
	v_mfma_f32_16x16x32_bf16 v[34:37], v[196:199], v[212:215], v[34:37]
	v_mfma_f32_16x16x32_bf16 v[22:25], v[188:191], v[220:223], v[22:25]
	v_mfma_f32_16x16x32_bf16 v[18:21], v[196:199], v[220:223], v[18:21]
	v_mfma_f32_16x16x32_bf16 v[6:9], v[188:191], v[228:231], v[6:9]
	v_mfma_f32_16x16x32_bf16 v[2:5], v[196:199], v[228:231], v[2:5]
	v_mfma_f32_16x16x32_bf16 v[54:57], v[192:195], v[208:211], v[54:57]
	v_mfma_f32_16x16x32_bf16 v[50:53], v[200:203], v[208:211], v[50:53]
	v_mfma_f32_16x16x32_bf16 v[38:41], v[192:195], v[216:219], v[38:41]
	v_mfma_f32_16x16x32_bf16 v[34:37], v[200:203], v[216:219], v[34:37]
	v_mfma_f32_16x16x32_bf16 v[22:25], v[192:195], v[224:227], v[22:25]
	v_mfma_f32_16x16x32_bf16 v[18:21], v[200:203], v[224:227], v[18:21]
	v_mfma_f32_16x16x32_bf16 v[6:9], v[192:195], v[232:235], v[6:9]
	v_mfma_f32_16x16x32_bf16 v[2:5], v[200:203], v[232:235], v[2:5]
	s_barrier
; #define PG8_STAGE(bufoff, gbase, voff) do { _Pragma("unroll") for (int _i = 0; _i < 2; ++_i) \
;         __builtin_amdgcn_global_load_lds((const unsigned*)((const char*)(gbase) + (voff)[_i]), (LAS unsigned*)(lds + (bufoff) + ldsw + _i * 8192), 16, 0, 0); } while (0)
; #define PG8_LDA(dst, b, h) do { _Pragma("unroll") for (int m = 0; m < 4; ++m) _Pragma("unroll") for (int k = 0; k < 2; ++k) dst[m][k] = *(const LAS bf16x8*)(lds + PG8_SA(b, h) + aoff + m * 2048 + k * 1024); } while (0)
; #define PG8_LDB(dst, b, h) do { _Pragma("unroll") for (int n = 0; n < 2; ++n) _Pragma("unroll") for (int k = 0; k < 2; ++k) dst[n][k] = *(const LAS bf16x8*)(lds + PG8_SB(b, h) + boff + n * 2048 + k * 1024); } while (0)
; #define PG8_MMA(ai, bj, At, Bt) do { __builtin_amdgcn_s_setprio(1); _Pragma("unroll") for (int m = 0; m < 4; ++m) _Pragma("unroll") for (int n = 0; n < 2; ++n) _Pragma("unroll") for (int k = 0; k < 2; ++k) \
;         acc[ai][bj][m][n] = __builtin_amdgcn_mfma_f32_16x16x32_bf16(Bt[n][k], At[m][k], acc[ai][bj][m][n], 0, 0, 0); __builtin_amdgcn_s_setprio(0); } while (0)
; #define PG8_WAIT_V(n) asm volatile("s_waitcnt vmcnt(" #n ")" ::: "memory")
; #define PG8_WAIT_L(n) asm volatile("s_waitcnt lgkmcnt(" #n ")" ::: "memory")
; #define PG8_BAR __builtin_amdgcn_s_barrier()
; #define PG8_SCHED __builtin_amdgcn_sched_barrier(0)
; template <class Epi, class Sched, bool ABLK = false, bool ALIGN_EPI = true, bool SP2 = true, bool BBLK = true>
; __device__ __forceinline__ void gemm_phase(LAS unsigned char* lds, const Gemm g, const Sched& S, const Epi& E) {
;     ...
;         for (int t = 0; t < nt; t += 2) {
;     ...
;             PG8_LDB(B0, 1, 0); PG8_LDB(B1, 1, 1); PG8_SCHED; PG8_LDA(At, 1, 0); PG8_STAGE(PG8_SA(0, 1), a2 + hstepA, voffA);
;             PG8_WAIT_V(8); PG8_WAIT_L(0); PG8_BAR; PG8_MMA(0, 0, At, B0); PG8_MMA(0, 1, At, B1); PG8_BAR; PG8_SCHED;
;             PG8_LDA(At, 1, 1); PG8_STAGE(PG8_SB(1, 0), b3, voffB); PG8_STAGE(PG8_SB(1, 1), b3 + hstepB, voffB); PG8_STAGE(PG8_SA(1, 0), a3, voffA);
;             PG8_WAIT_V(8); PG8_WAIT_L(0); PG8_BAR; PG8_MMA(1, 0, At, B0); PG8_MMA(1, 1, At, B1); PG8_BAR; PG8_SCHED;
	v_add_u32_e32 v171, s60, v1
	ds_read_b128 v[172:175], v171
	ds_read_b128 v[176:179], v171 offset:1024
	ds_read_b128 v[180:183], v171 offset:2048
	ds_read_b128 v[184:187], v171 offset:3072
	v_add_u32_e32 v171, s61, v1
	ds_read_b128 v[188:191], v171
	ds_read_b128 v[192:195], v171 offset:1024
	ds_read_b128 v[196:199], v171 offset:2048
	ds_read_b128 v[200:203], v171 offset:3072
	s_add_u32 s36, s36, 0x80000
	s_addc_u32 s37, s37, 0
	s_mov_b32 m0, s44
	ds_read_b128 v[204:207], v170 offset:32768
	ds_read_b128 v[208:211], v170 offset:33792
	ds_read_b128 v[212:215], v170 offset:34816
	ds_read_b128 v[216:219], v170 offset:35840
	ds_read_b128 v[220:223], v170 offset:36864
	ds_read_b128 v[224:227], v170 offset:37888
	ds_read_b128 v[228:231], v170 offset:38912
	ds_read_b128 v[232:235], v170 offset:39936
	global_load_lds_dwordx4 v136, s[36:37]
	s_mov_b32 m0, s45
	s_nop 0
	global_load_lds_dwordx4 v132, s[36:37]
	s_waitcnt vmcnt(8) lgkmcnt(0)
	s_barrier
	v_mfma_f32_16x16x32_bf16 v[126:129], v[172:175], v[204:207], v[126:129]
	v_mfma_f32_16x16x32_bf16 v[122:125], v[180:183], v[204:207], v[122:125]
	v_mfma_f32_16x16x32_bf16 v[110:113], v[172:175], v[212:215], v[110:113]
	v_mfma_f32_16x16x32_bf16 v[106:109], v[180:183], v[212:215], v[106:109]
	v_mfma_f32_16x16x32_bf16 v[94:97], v[172:175], v[220:223], v[94:97]
	v_mfma_f32_16x16x32_bf16 v[90:93], v[180:183], v[220:223], v[90:93]
	v_mfma_f32_16x16x32_bf16 v[78:81], v[172:175], v[228:231], v[78:81]
	v_mfma_f32_16x16x32_bf16 v[74:77], v[180:183], v[228:231], v[74:77]
	v_mfma_f32_16x16x32_bf16 v[126:129], v[176:179], v[208:211], v[126:129]
	v_mfma_f32_16x16x32_bf16 v[122:125], v[184:187], v[208:211], v[122:125]
	v_mfma_f32_16x16x32_bf16 v[110:113], v[176:179], v[216:219], v[110:113]
	v_mfma_f32_16x16x32_bf16 v[106:109], v[184:187], v[216:219], v[106:109]
	v_mfma_f32_16x16x32_bf16 v[94:97], v[176:179], v[224:227], v[94:97]
	v_mfma_f32_16x16x32_bf16 v[90:93], v[184:187], v[224:227], v[90:93]
	v_mfma_f32_16x16x32_bf16 v[78:81], v[176:179], v[232:235], v[78:81]
	v_mfma_f32_16x16x32_bf16 v[74:77], v[184:187], v[232:235], v[74:77]
	v_mfma_f32_16x16x32_bf16 v[118:121], v[188:191], v[204:207], v[118:121]
	v_mfma_f32_16x16x32_bf16 v[114:117], v[196:199], v[204:207], v[114:117]
	v_mfma_f32_16x16x32_bf16 v[102:105], v[188:191], v[212:215], v[102:105]
	v_mfma_f32_16x16x32_bf16 v[98:101], v[196:199], v[212:215], v[98:101]
	v_mfma_f32_16x16x32_bf16 v[86:89], v[188:191], v[220:223], v[86:89]
	v_mfma_f32_16x16x32_bf16 v[82:85], v[196:199], v[220:223], v[82:85]
	v_mfma_f32_16x16x32_bf16 v[70:73], v[188:191], v[228:231], v[70:73]
	v_mfma_f32_16x16x32_bf16 v[66:69], v[196:199], v[228:231], v[66:69]
	v_mfma_f32_16x16x32_bf16 v[118:121], v[192:195], v[208:211], v[118:121]
	v_mfma_f32_16x16x32_bf16 v[114:117], v[200:203], v[208:211], v[114:117]
	v_mfma_f32_16x16x32_bf16 v[102:105], v[192:195], v[216:219], v[102:105]
	v_mfma_f32_16x16x32_bf16 v[98:101], v[200:203], v[216:219], v[98:101]
	v_mfma_f32_16x16x32_bf16 v[86:89], v[192:195], v[224:227], v[86:89]
	v_mfma_f32_16x16x32_bf16 v[82:85], v[200:203], v[224:227], v[82:85]
	v_mfma_f32_16x16x32_bf16 v[70:73], v[192:195], v[232:235], v[70:73]
	v_mfma_f32_16x16x32_bf16 v[66:69], v[200:203], v[232:235], v[66:69]
	s_barrier
	s_add_u32 s36, s34, 0x8000
	s_addc_u32 s37, s35, 0
	s_add_i32 s58, s60, s40
	s_mov_b32 m0, s58
	ds_read_b128 v[204:207], v170 offset:49152
	ds_read_b128 v[208:211], v170 offset:50176
	ds_read_b128 v[212:215], v170 offset:51200
	ds_read_b128 v[216:219], v170 offset:52224
	ds_read_b128 v[220:223], v170 offset:53248
	ds_read_b128 v[224:227], v170 offset:54272
	ds_read_b128 v[228:231], v170 offset:55296
	ds_read_b128 v[232:235], v170 offset:56320
	global_load_lds_dwordx4 v134, s[36:37]
	s_add_i32 m0, s58, 0x2000
	s_add_u32 s34, s34, 0xc000
	v_lshl_add_u64 v[236:237], s[36:37], 0, v[130:131]
	s_addc_u32 s35, s35, 0
	s_add_i32 s36, s61, s40
	global_load_lds_dwordx4 v[236:237], off
	s_mov_b32 m0, s36
	s_nop 0
	global_load_lds_dwordx4 v134, s[34:35]
	s_add_i32 m0, s36, 0x2000
	s_nop 0
	global_load_lds_dwordx4 v130, s[34:35]
	s_mov_b32 m0, s48
	s_nop 0
	global_load_lds_dwordx4 v136, s[30:31]
	s_mov_b32 m0, s49
	s_nop 0
	global_load_lds_dwordx4 v132, s[30:31]
	s_waitcnt vmcnt(8) lgkmcnt(0)
	s_barrier
	v_mfma_f32_16x16x32_bf16 v[62:65], v[172:175], v[204:207], v[62:65]
	v_mfma_f32_16x16x32_bf16 v[58:61], v[180:183], v[204:207], v[58:61]
	v_mfma_f32_16x16x32_bf16 v[46:49], v[172:175], v[212:215], v[46:49]
	v_mfma_f32_16x16x32_bf16 v[42:45], v[180:183], v[212:215], v[42:45]
	v_mfma_f32_16x16x32_bf16 v[30:33], v[172:175], v[220:223], v[30:33]
	v_mfma_f32_16x16x32_bf16 v[26:29], v[180:183], v[220:223], v[26:29]
	v_mfma_f32_16x16x32_bf16 v[14:17], v[172:175], v[228:231], v[14:17]
	v_mfma_f32_16x16x32_bf16 v[10:13], v[180:183], v[228:231], v[10:13]
	v_mfma_f32_16x16x32_bf16 v[62:65], v[176:179], v[208:211], v[62:65]
	v_mfma_f32_16x16x32_bf16 v[58:61], v[184:187], v[208:211], v[58:61]
	v_mfma_f32_16x16x32_bf16 v[46:49], v[176:179], v[216:219], v[46:49]
	v_mfma_f32_16x16x32_bf16 v[42:45], v[184:187], v[216:219], v[42:45]
	v_mfma_f32_16x16x32_bf16 v[30:33], v[176:179], v[224:227], v[30:33]
	v_mfma_f32_16x16x32_bf16 v[26:29], v[184:187], v[224:227], v[26:29]
	v_mfma_f32_16x16x32_bf16 v[14:17], v[176:179], v[232:235], v[14:17]
	v_mfma_f32_16x16x32_bf16 v[10:13], v[184:187], v[232:235], v[10:13]
	v_mfma_f32_16x16x32_bf16 v[54:57], v[188:191], v[204:207], v[54:57]
	v_mfma_f32_16x16x32_bf16 v[50:53], v[196:199], v[204:207], v[50:53]
	v_mfma_f32_16x16x32_bf16 v[38:41], v[188:191], v[212:215], v[38:41]
	v_mfma_f32_16x16x32_bf16 v[34:37], v[196:199], v[212:215], v[34:37]
	v_mfma_f32_16x16x32_bf16 v[22:25], v[188:191], v[220:223], v[22:25]
	v_mfma_f32_16x16x32_bf16 v[18:21], v[196:199], v[220:223], v[18:21]
	v_mfma_f32_16x16x32_bf16 v[6:9], v[188:191], v[228:231], v[6:9]
	v_mfma_f32_16x16x32_bf16 v[2:5], v[196:199], v[228:231], v[2:5]
	v_mfma_f32_16x16x32_bf16 v[54:57], v[192:195], v[208:211], v[54:57]
	v_mfma_f32_16x16x32_bf16 v[50:53], v[200:203], v[208:211], v[50:53]
	v_mfma_f32_16x16x32_bf16 v[38:41], v[192:195], v[216:219], v[38:41]
	v_mfma_f32_16x16x32_bf16 v[34:37], v[200:203], v[216:219], v[34:37]
	v_mfma_f32_16x16x32_bf16 v[22:25], v[192:195], v[224:227], v[22:25]
	v_mfma_f32_16x16x32_bf16 v[18:21], v[200:203], v[224:227], v[18:21]
	v_mfma_f32_16x16x32_bf16 v[6:9], v[192:195], v[232:235], v[6:9]
	v_mfma_f32_16x16x32_bf16 v[2:5], v[200:203], v[232:235], v[2:5]
	s_barrier
	s_add_i32 s57, s57, 2
	s_add_u32 s28, s28, 0x100
	s_addc_u32 s29, s29, 0
	s_add_u32 s55, s55, 0x10000
	s_addc_u32 s56, s56, 0
	s_cmp_gt_u32 s57, 29
	s_cbranch_scc0 .LBB0_2263
	s_and_b64 vcc, exec, s[10:11]
	s_cbranch_vccz .LBB0_2266
	s_barrier

; #define PG8_STAGE(bufoff, gbase, voff) do { _Pragma("unroll") for (int _i = 0; _i < 2; ++_i) \
;         __builtin_amdgcn_global_load_lds((const unsigned*)((const char*)(gbase) + (voff)[_i]), (LAS unsigned*)(lds + (bufoff) + ldsw + _i * 8192), 16, 0, 0); } while (0)
; #define PG8_LDA(dst, b, h) do { _Pragma("unroll") for (int m = 0; m < 4; ++m) _Pragma("unroll") for (int k = 0; k < 2; ++k) dst[m][k] = *(const LAS bf16x8*)(lds + PG8_SA(b, h) + aoff + m * 2048 + k * 1024); } while (0)
; #define PG8_LDB(dst, b, h) do { _Pragma("unroll") for (int n = 0; n < 2; ++n) _Pragma("unroll") for (int k = 0; k < 2; ++k) dst[n][k] = *(const LAS bf16x8*)(lds + PG8_SB(b, h) + boff + n * 2048 + k * 1024); } while (0)
; #define PG8_MMA(ai, bj, At, Bt) do { __builtin_amdgcn_s_setprio(1); _Pragma("unroll") for (int m = 0; m < 4; ++m) _Pragma("unroll") for (int n = 0; n < 2; ++n) _Pragma("unroll") for (int k = 0; k < 2; ++k) \
;         acc[ai][bj][m][n] = __builtin_amdgcn_mfma_f32_16x16x32_bf16(Bt[n][k], At[m][k], acc[ai][bj][m][n], 0, 0, 0); __builtin_amdgcn_s_setprio(0); } while (0)
; #define PG8_WAIT_V(n) asm volatile("s_waitcnt vmcnt(" #n ")" ::: "memory")
; #define PG8_WAIT_L(n) asm volatile("s_waitcnt lgkmcnt(" #n ")" ::: "memory")
; #define PG8_BAR __builtin_amdgcn_s_barrier()
; template <class Epi, class Sched, bool ABLK = false, bool ALIGN_EPI = true, bool SP2 = true, bool BBLK = true>
; __device__ __forceinline__ void gemm_phase(LAS unsigned char* lds, const Gemm g, const Sched& S, const Epi& E) {
;     ...
;             const bool last = (t == nt - 2);
;             const char* a1 = a_tile(uA, tbA + t + 1);
;             const char* a2 = last ? a_tile(nuA, ntbA) : a_tile(uA, tbA + t + 2); const char* b2 = last ? nB : cB + (size_t)(t + 2) * kstepB;
;             const char* a3 = last ? a_tile(nuA, ntbA + 1) : a_tile(uA, tbA + t + 3); const char* b3 = b2 + kstepB;
;             if (last && has_next) S.a_ready(nxt);
;             if constexpr (SP2) {
;             PG8_LDB(B0, 0, 0); PG8_LDB(B1, 0, 1); PG8_SCHED; PG8_LDA(At, 0, 0); PG8_STAGE(PG8_SA(1, 1), a1 + hstepA, voffA);
;             PG8_WAIT_V(8); PG8_WAIT_L(0); PG8_BAR; PG8_MMA(0, 0, At, B0); PG8_MMA(0, 1, At, B1); PG8_BAR; PG8_SCHED;
;             PG8_LDA(At, 0, 1); PG8_STAGE(PG8_SB(0, 0), b2, voffB); PG8_STAGE(PG8_SB(0, 1), b2 + hstepB, voffB); PG8_STAGE(PG8_SA(0, 0), a2, voffA);
.LBB0_2328:
	ds_read_b128 v[152:155], v148
	ds_read_b128 v[156:159], v148 offset:1024
	ds_read_b128 v[160:163], v148 offset:2048
	ds_read_b128 v[164:167], v148 offset:3072
	ds_read_b128 v[168:171], v149
	ds_read_b128 v[172:175], v149 offset:1024
	ds_read_b128 v[176:179], v149 offset:2048
	ds_read_b128 v[180:183], v149 offset:3072
	s_add_u32 s40, s64, s38
	s_addc_u32 s41, s65, s39
	s_add_u32 s44, s40, 0x10000
	s_addc_u32 s45, s41, 0
	s_add_i32 s67, s67, 2
	s_add_u32 s42, s62, s38
	s_addc_u32 s43, s63, s39
	s_add_u32 s40, s40, 0x18000
	s_addc_u32 s41, s41, 0
	s_cmp_eq_u32 s66, s38
	s_cselect_b32 s41, s59, s41
	s_cselect_b32 s40, s58, s40
	s_cselect_b32 s43, s4, s43
	s_cselect_b32 s42, s5, s42
	s_cselect_b32 s45, s57, s45
	s_cselect_b32 s44, s35, s44
	v_lshl_add_u64 v[216:217], v[142:143], 0, s[38:39]
	s_add_i32 m0, s49, 0xc000
	ds_read_b128 v[184:187], v150
	ds_read_b128 v[188:191], v150 offset:1024
	ds_read_b128 v[192:195], v150 offset:2048
	ds_read_b128 v[196:199], v150 offset:3072
	ds_read_b128 v[200:203], v150 offset:4096
	ds_read_b128 v[204:207], v150 offset:5120
	ds_read_b128 v[208:211], v150 offset:6144
	ds_read_b128 v[212:215], v150 offset:7168
	global_load_lds_dwordx4 v[216:217], off
	v_lshl_add_u64 v[216:217], v[144:145], 0, s[38:39]
	s_add_i32 m0, s49, 0xe000
	s_nop 0
	global_load_lds_dwordx4 v[216:217], off
	s_waitcnt vmcnt(8) lgkmcnt(0)
	s_barrier
	v_mfma_f32_16x16x32_bf16 v[126:129], v[152:155], v[184:187], v[126:129]
	v_mfma_f32_16x16x32_bf16 v[122:125], v[160:163], v[184:187], v[122:125]
	v_mfma_f32_16x16x32_bf16 v[110:113], v[152:155], v[192:195], v[110:113]
	v_mfma_f32_16x16x32_bf16 v[106:109], v[160:163], v[192:195], v[106:109]
	v_mfma_f32_16x16x32_bf16 v[94:97], v[152:155], v[200:203], v[94:97]
	v_mfma_f32_16x16x32_bf16 v[90:93], v[160:163], v[200:203], v[90:93]
	v_mfma_f32_16x16x32_bf16 v[78:81], v[152:155], v[208:211], v[78:81]
	v_mfma_f32_16x16x32_bf16 v[74:77], v[160:163], v[208:211], v[74:77]
	v_mfma_f32_16x16x32_bf16 v[126:129], v[156:159], v[188:191], v[126:129]
	v_mfma_f32_16x16x32_bf16 v[122:125], v[164:167], v[188:191], v[122:125]
	v_mfma_f32_16x16x32_bf16 v[110:113], v[156:159], v[196:199], v[110:113]
	v_mfma_f32_16x16x32_bf16 v[106:109], v[164:167], v[196:199], v[106:109]
	v_mfma_f32_16x16x32_bf16 v[94:97], v[156:159], v[204:207], v[94:97]
	v_mfma_f32_16x16x32_bf16 v[90:93], v[164:167], v[204:207], v[90:93]
	v_mfma_f32_16x16x32_bf16 v[78:81], v[156:159], v[212:215], v[78:81]
	v_mfma_f32_16x16x32_bf16 v[74:77], v[164:167], v[212:215], v[74:77]
	v_mfma_f32_16x16x32_bf16 v[118:121], v[168:171], v[184:187], v[118:121]
	v_mfma_f32_16x16x32_bf16 v[114:117], v[176:179], v[184:187], v[114:117]
	v_mfma_f32_16x16x32_bf16 v[102:105], v[168:171], v[192:195], v[102:105]
	v_mfma_f32_16x16x32_bf16 v[98:101], v[176:179], v[192:195], v[98:101]
	v_mfma_f32_16x16x32_bf16 v[86:89], v[168:171], v[200:203], v[86:89]
	v_mfma_f32_16x16x32_bf16 v[82:85], v[176:179], v[200:203], v[82:85]
	v_mfma_f32_16x16x32_bf16 v[70:73], v[168:171], v[208:211], v[70:73]
	v_mfma_f32_16x16x32_bf16 v[66:69], v[176:179], v[208:211], v[66:69]
	v_mfma_f32_16x16x32_bf16 v[118:121], v[172:175], v[188:191], v[118:121]
	v_mfma_f32_16x16x32_bf16 v[114:117], v[180:183], v[188:191], v[114:117]
	v_mfma_f32_16x16x32_bf16 v[102:105], v[172:175], v[196:199], v[102:105]
	v_mfma_f32_16x16x32_bf16 v[98:101], v[180:183], v[196:199], v[98:101]
	v_mfma_f32_16x16x32_bf16 v[86:89], v[172:175], v[204:207], v[86:89]
	v_mfma_f32_16x16x32_bf16 v[82:85], v[180:183], v[204:207], v[82:85]
	v_mfma_f32_16x16x32_bf16 v[70:73], v[172:175], v[212:215], v[70:73]
	v_mfma_f32_16x16x32_bf16 v[66:69], v[180:183], v[212:215], v[66:69]
	s_barrier
	s_add_i32 s70, s72, s48
	s_mov_b32 m0, s70
	ds_read_b128 v[184:187], v150 offset:16384
	ds_read_b128 v[188:191], v150 offset:17408
	ds_read_b128 v[192:195], v150 offset:18432
	ds_read_b128 v[196:199], v150 offset:19456
	ds_read_b128 v[200:203], v150 offset:20480
	ds_read_b128 v[204:207], v150 offset:21504
	ds_read_b128 v[208:211], v150 offset:22528
	ds_read_b128 v[212:215], v150 offset:23552
	global_load_lds_dwordx4 v130, s[42:43]
	s_add_i32 m0, s70, 0x2000
	s_add_u32 s76, s42, 0x4000
	s_addc_u32 s77, s43, 0
	s_add_i32 s70, s73, s48
	global_load_lds_dwordx4 v132, s[42:43]
	s_mov_b32 m0, s70
	s_nop 0
	global_load_lds_dwordx4 v130, s[76:77]
	s_add_i32 m0, s70, 0x2000
	s_nop 0
	global_load_lds_dwordx4 v132, s[76:77]
	s_mov_b32 m0, s49
	s_nop 0
	global_load_lds_dwordx4 v130, s[44:45]
	s_mov_b32 m0, s50
	s_nop 0
	global_load_lds_dwordx4 v132, s[44:45]
	s_waitcnt vmcnt(8) lgkmcnt(0)
	s_barrier
; #define PG8_STAGE(bufoff, gbase, voff) do { _Pragma("unroll") for (int _i = 0; _i < 2; ++_i) \
;         __builtin_amdgcn_global_load_lds((const unsigned*)((const char*)(gbase) + (voff)[_i]), (LAS unsigned*)(lds + (bufoff) + ldsw + _i * 8192), 16, 0, 0); } while (0)
; #define PG8_LDA(dst, b, h) do { _Pragma("unroll") for (int m = 0; m < 4; ++m) _Pragma("unroll") for (int k = 0; k < 2; ++k) dst[m][k] = *(const LAS bf16x8*)(lds + PG8_SA(b, h) + aoff + m * 2048 + k * 1024); } while (0)
; #define PG8_LDB(dst, b, h) do { _Pragma("unroll") for (int n = 0; n < 2; ++n) _Pragma("unroll") for (int k = 0; k < 2; ++k) dst[n][k] = *(const LAS bf16x8*)(lds + PG8_SB(b, h) + boff + n * 2048 + k * 1024); } while (0)
; #define PG8_MMA(ai, bj, At, Bt) do { __builtin_amdgcn_s_setprio(1); _Pragma("unroll") for (int m = 0; m < 4; ++m) _Pragma("unroll") for (int n = 0; n < 2; ++n) _Pragma("unroll") for (int k = 0; k < 2; ++k) \
;         acc[ai][bj][m][n] = __builtin_amdgcn_mfma_f32_16x16x32_bf16(Bt[n][k], At[m][k], acc[ai][bj][m][n], 0, 0, 0); __builtin_amdgcn_s_setprio(0); } while (0)
; #define PG8_WAIT_V(n) asm volatile("s_waitcnt vmcnt(" #n ")" ::: "memory")
; #define PG8_WAIT_L(n) asm volatile("s_waitcnt lgkmcnt(" #n ")" ::: "memory")
; #define PG8_BAR __builtin_amdgcn_s_barrier()
; #define PG8_SCHED __builtin_amdgcn_sched_barrier(0)
; template <class Epi, class Sched, bool ABLK = false, bool ALIGN_EPI = true, bool SP2 = true, bool BBLK = true>
; __device__ __forceinline__ void gemm_phase(LAS unsigned char* lds, const Gemm g, const Sched& S, const Epi& E) {
;     ...
;             PG8_WAIT_V(8); PG8_WAIT_L(0); PG8_BAR; PG8_MMA(1, 0, At, B0); PG8_MMA(1, 1, At, B1); PG8_BAR; PG8_SCHED;
;             PG8_LDB(B0, 1, 0); PG8_LDB(B1, 1, 1); PG8_SCHED; PG8_LDA(At, 1, 0); PG8_STAGE(PG8_SA(0, 1), a2 + hstepA, voffA);
;             PG8_WAIT_V(8); PG8_WAIT_L(0); PG8_BAR; PG8_MMA(0, 0, At, B0); PG8_MMA(0, 1, At, B1); PG8_BAR; PG8_SCHED;
	v_mfma_f32_16x16x32_bf16 v[62:65], v[152:155], v[184:187], v[62:65]
	v_mfma_f32_16x16x32_bf16 v[58:61], v[160:163], v[184:187], v[58:61]
	v_mfma_f32_16x16x32_bf16 v[46:49], v[152:155], v[192:195], v[46:49]
	v_mfma_f32_16x16x32_bf16 v[42:45], v[160:163], v[192:195], v[42:45]
	v_mfma_f32_16x16x32_bf16 v[30:33], v[152:155], v[200:203], v[30:33]
	v_mfma_f32_16x16x32_bf16 v[26:29], v[160:163], v[200:203], v[26:29]
	v_mfma_f32_16x16x32_bf16 v[14:17], v[152:155], v[208:211], v[14:17]
	v_mfma_f32_16x16x32_bf16 v[10:13], v[160:163], v[208:211], v[10:13]
	v_mfma_f32_16x16x32_bf16 v[62:65], v[156:159], v[188:191], v[62:65]
	v_mfma_f32_16x16x32_bf16 v[58:61], v[164:167], v[188:191], v[58:61]
	v_mfma_f32_16x16x32_bf16 v[46:49], v[156:159], v[196:199], v[46:49]
	v_mfma_f32_16x16x32_bf16 v[42:45], v[164:167], v[196:199], v[42:45]
	v_mfma_f32_16x16x32_bf16 v[30:33], v[156:159], v[204:207], v[30:33]
	v_mfma_f32_16x16x32_bf16 v[26:29], v[164:167], v[204:207], v[26:29]
	v_mfma_f32_16x16x32_bf16 v[14:17], v[156:159], v[212:215], v[14:17]
	v_mfma_f32_16x16x32_bf16 v[10:13], v[164:167], v[212:215], v[10:13]
	v_mfma_f32_16x16x32_bf16 v[54:57], v[168:171], v[184:187], v[54:57]
	v_mfma_f32_16x16x32_bf16 v[50:53], v[176:179], v[184:187], v[50:53]
	v_mfma_f32_16x16x32_bf16 v[38:41], v[168:171], v[192:195], v[38:41]
	v_mfma_f32_16x16x32_bf16 v[34:37], v[176:179], v[192:195], v[34:37]
	v_mfma_f32_16x16x32_bf16 v[22:25], v[168:171], v[200:203], v[22:25]
	v_mfma_f32_16x16x32_bf16 v[18:21], v[176:179], v[200:203], v[18:21]
	v_mfma_f32_16x16x32_bf16 v[6:9], v[168:171], v[208:211], v[6:9]
	v_mfma_f32_16x16x32_bf16 v[2:5], v[176:179], v[208:211], v[2:5]
	v_mfma_f32_16x16x32_bf16 v[54:57], v[172:175], v[188:191], v[54:57]
	v_mfma_f32_16x16x32_bf16 v[50:53], v[180:183], v[188:191], v[50:53]
	v_mfma_f32_16x16x32_bf16 v[38:41], v[172:175], v[196:199], v[38:41]
	v_mfma_f32_16x16x32_bf16 v[34:37], v[180:183], v[196:199], v[34:37]
	v_mfma_f32_16x16x32_bf16 v[22:25], v[172:175], v[204:207], v[22:25]
	v_mfma_f32_16x16x32_bf16 v[18:21], v[180:183], v[204:207], v[18:21]
	v_mfma_f32_16x16x32_bf16 v[6:9], v[172:175], v[212:215], v[6:9]
	v_mfma_f32_16x16x32_bf16 v[2:5], v[180:183], v[212:215], v[2:5]
	s_barrier
	v_add_u32_e32 v151, s60, v146
	ds_read_b128 v[152:155], v151
	ds_read_b128 v[156:159], v151 offset:1024
	ds_read_b128 v[160:163], v151 offset:2048
	ds_read_b128 v[164:167], v151 offset:3072
	v_add_u32_e32 v151, s61, v146
	ds_read_b128 v[168:171], v151
	ds_read_b128 v[172:175], v151 offset:1024
	ds_read_b128 v[176:179], v151 offset:2048
	ds_read_b128 v[180:183], v151 offset:3072
	s_add_u32 s44, s44, 0x4000
	s_addc_u32 s45, s45, 0
	s_mov_b32 m0, s51
	ds_read_b128 v[184:187], v150 offset:32768
	ds_read_b128 v[188:191], v150 offset:33792
	ds_read_b128 v[192:195], v150 offset:34816
	ds_read_b128 v[196:199], v150 offset:35840
	ds_read_b128 v[200:203], v150 offset:36864
	ds_read_b128 v[204:207], v150 offset:37888
	ds_read_b128 v[208:211], v150 offset:38912
	ds_read_b128 v[212:215], v150 offset:39936
	global_load_lds_dwordx4 v130, s[44:45]
	s_mov_b32 m0, s52
	s_nop 0
	global_load_lds_dwordx4 v132, s[44:45]
	s_waitcnt vmcnt(8) lgkmcnt(0)
	s_barrier
	v_mfma_f32_16x16x32_bf16 v[126:129], v[152:155], v[184:187], v[126:129]
	v_mfma_f32_16x16x32_bf16 v[122:125], v[160:163], v[184:187], v[122:125]
	v_mfma_f32_16x16x32_bf16 v[110:113], v[152:155], v[192:195], v[110:113]
	v_mfma_f32_16x16x32_bf16 v[106:109], v[160:163], v[192:195], v[106:109]
	v_mfma_f32_16x16x32_bf16 v[94:97], v[152:155], v[200:203], v[94:97]
	v_mfma_f32_16x16x32_bf16 v[90:93], v[160:163], v[200:203], v[90:93]
	v_mfma_f32_16x16x32_bf16 v[78:81], v[152:155], v[208:211], v[78:81]
	v_mfma_f32_16x16x32_bf16 v[74:77], v[160:163], v[208:211], v[74:77]
	v_mfma_f32_16x16x32_bf16 v[126:129], v[156:159], v[188:191], v[126:129]
	v_mfma_f32_16x16x32_bf16 v[122:125], v[164:167], v[188:191], v[122:125]
	v_mfma_f32_16x16x32_bf16 v[110:113], v[156:159], v[196:199], v[110:113]
	v_mfma_f32_16x16x32_bf16 v[106:109], v[164:167], v[196:199], v[106:109]
	v_mfma_f32_16x16x32_bf16 v[94:97], v[156:159], v[204:207], v[94:97]
	v_mfma_f32_16x16x32_bf16 v[90:93], v[164:167], v[204:207], v[90:93]
	v_mfma_f32_16x16x32_bf16 v[78:81], v[156:159], v[212:215], v[78:81]
	v_mfma_f32_16x16x32_bf16 v[74:77], v[164:167], v[212:215], v[74:77]
	v_mfma_f32_16x16x32_bf16 v[118:121], v[168:171], v[184:187], v[118:121]
	v_mfma_f32_16x16x32_bf16 v[114:117], v[176:179], v[184:187], v[114:117]
	v_mfma_f32_16x16x32_bf16 v[102:105], v[168:171], v[192:195], v[102:105]
	v_mfma_f32_16x16x32_bf16 v[98:101], v[176:179], v[192:195], v[98:101]
	v_mfma_f32_16x16x32_bf16 v[86:89], v[168:171], v[200:203], v[86:89]
	v_mfma_f32_16x16x32_bf16 v[82:85], v[176:179], v[200:203], v[82:85]
	v_mfma_f32_16x16x32_bf16 v[70:73], v[168:171], v[208:211], v[70:73]
	v_mfma_f32_16x16x32_bf16 v[66:69], v[176:179], v[208:211], v[66:69]
	v_mfma_f32_16x16x32_bf16 v[118:121], v[172:175], v[188:191], v[118:121]
	v_mfma_f32_16x16x32_bf16 v[114:117], v[180:183], v[188:191], v[114:117]
	v_mfma_f32_16x16x32_bf16 v[102:105], v[172:175], v[196:199], v[102:105]
	v_mfma_f32_16x16x32_bf16 v[98:101], v[180:183], v[196:199], v[98:101]
	v_mfma_f32_16x16x32_bf16 v[86:89], v[172:175], v[204:207], v[86:89]
	v_mfma_f32_16x16x32_bf16 v[82:85], v[180:183], v[204:207], v[82:85]
	v_mfma_f32_16x16x32_bf16 v[70:73], v[172:175], v[212:215], v[70:73]
	v_mfma_f32_16x16x32_bf16 v[66:69], v[180:183], v[212:215], v[66:69]
	s_barrier
; #define PG8_STAGE(bufoff, gbase, voff) do { _Pragma("unroll") for (int _i = 0; _i < 2; ++_i) \
;         __builtin_amdgcn_global_load_lds((const unsigned*)((const char*)(gbase) + (voff)[_i]), (LAS unsigned*)(lds + (bufoff) + ldsw + _i * 8192), 16, 0, 0); } while (0)
; #define PG8_LDA(dst, b, h) do { _Pragma("unroll") for (int m = 0; m < 4; ++m) _Pragma("unroll") for (int k = 0; k < 2; ++k) dst[m][k] = *(const LAS bf16x8*)(lds + PG8_SA(b, h) + aoff + m * 2048 + k * 1024); } while (0)
; #define PG8_MMA(ai, bj, At, Bt) do { __builtin_amdgcn_s_setprio(1); _Pragma("unroll") for (int m = 0; m < 4; ++m) _Pragma("unroll") for (int n = 0; n < 2; ++n) _Pragma("unroll") for (int k = 0; k < 2; ++k) \
;         acc[ai][bj][m][n] = __builtin_amdgcn_mfma_f32_16x16x32_bf16(Bt[n][k], At[m][k], acc[ai][bj][m][n], 0, 0, 0); __builtin_amdgcn_s_setprio(0); } while (0)
; #define PG8_WAIT_V(n) asm volatile("s_waitcnt vmcnt(" #n ")" ::: "memory")
; #define PG8_WAIT_L(n) asm volatile("s_waitcnt lgkmcnt(" #n ")" ::: "memory")
; #define PG8_BAR __builtin_amdgcn_s_barrier()
; #define PG8_SCHED __builtin_amdgcn_sched_barrier(0)
; template <class Epi, class Sched, bool ABLK = false, bool ALIGN_EPI = true, bool SP2 = true, bool BBLK = true>
; __device__ __forceinline__ void gemm_phase(LAS unsigned char* lds, const Gemm g, const Sched& S, const Epi& E) {
;     ...
;         for (int t = 0; t < nt; t += 2) {
;     ...
;             PG8_LDA(At, 1, 1); PG8_STAGE(PG8_SB(1, 0), b3, voffB); PG8_STAGE(PG8_SB(1, 1), b3 + hstepB, voffB); PG8_STAGE(PG8_SA(1, 0), a3, voffA);
;             PG8_WAIT_V(8); PG8_WAIT_L(0); PG8_BAR; PG8_MMA(1, 0, At, B0); PG8_MMA(1, 1, At, B1); PG8_BAR; PG8_SCHED;
	s_add_u32 s44, s42, 0x8000
	s_addc_u32 s45, s43, 0
	s_add_i32 s70, s60, s48
	s_mov_b32 m0, s70
	ds_read_b128 v[184:187], v150 offset:49152
	ds_read_b128 v[188:191], v150 offset:50176
	ds_read_b128 v[192:195], v150 offset:51200
	ds_read_b128 v[196:199], v150 offset:52224
	ds_read_b128 v[200:203], v150 offset:53248
	ds_read_b128 v[204:207], v150 offset:54272
	ds_read_b128 v[208:211], v150 offset:55296
	ds_read_b128 v[212:215], v150 offset:56320
	global_load_lds_dwordx4 v130, s[44:45]
	s_add_i32 m0, s70, 0x2000
	s_add_u32 s42, s42, 0xc000
	v_lshl_add_u64 v[216:217], s[44:45], 0, v[132:133]
	s_addc_u32 s43, s43, 0
	s_add_i32 s44, s61, s48
	global_load_lds_dwordx4 v[216:217], off
	s_mov_b32 m0, s44
	s_nop 0
	global_load_lds_dwordx4 v130, s[42:43]
	s_add_i32 m0, s44, 0x2000
	s_nop 0
	global_load_lds_dwordx4 v132, s[42:43]
	s_mov_b32 m0, s53
	s_nop 0
	global_load_lds_dwordx4 v130, s[40:41]
	s_mov_b32 m0, s54
	s_nop 0
	global_load_lds_dwordx4 v132, s[40:41]
	s_waitcnt vmcnt(8) lgkmcnt(0)
	s_barrier
	v_mfma_f32_16x16x32_bf16 v[62:65], v[152:155], v[184:187], v[62:65]
	v_mfma_f32_16x16x32_bf16 v[58:61], v[160:163], v[184:187], v[58:61]
	v_mfma_f32_16x16x32_bf16 v[46:49], v[152:155], v[192:195], v[46:49]
	v_mfma_f32_16x16x32_bf16 v[42:45], v[160:163], v[192:195], v[42:45]
	v_mfma_f32_16x16x32_bf16 v[30:33], v[152:155], v[200:203], v[30:33]
	v_mfma_f32_16x16x32_bf16 v[26:29], v[160:163], v[200:203], v[26:29]
	v_mfma_f32_16x16x32_bf16 v[14:17], v[152:155], v[208:211], v[14:17]
	v_mfma_f32_16x16x32_bf16 v[10:13], v[160:163], v[208:211], v[10:13]
	v_mfma_f32_16x16x32_bf16 v[62:65], v[156:159], v[188:191], v[62:65]
	v_mfma_f32_16x16x32_bf16 v[58:61], v[164:167], v[188:191], v[58:61]
	v_mfma_f32_16x16x32_bf16 v[46:49], v[156:159], v[196:199], v[46:49]
	v_mfma_f32_16x16x32_bf16 v[42:45], v[164:167], v[196:199], v[42:45]
	v_mfma_f32_16x16x32_bf16 v[30:33], v[156:159], v[204:207], v[30:33]
	v_mfma_f32_16x16x32_bf16 v[26:29], v[164:167], v[204:207], v[26:29]
	v_mfma_f32_16x16x32_bf16 v[14:17], v[156:159], v[212:215], v[14:17]
	v_mfma_f32_16x16x32_bf16 v[10:13], v[164:167], v[212:215], v[10:13]
	v_mfma_f32_16x16x32_bf16 v[54:57], v[168:171], v[184:187], v[54:57]
	v_mfma_f32_16x16x32_bf16 v[50:53], v[176:179], v[184:187], v[50:53]
	v_mfma_f32_16x16x32_bf16 v[38:41], v[168:171], v[192:195], v[38:41]
	v_mfma_f32_16x16x32_bf16 v[34:37], v[176:179], v[192:195], v[34:37]
	v_mfma_f32_16x16x32_bf16 v[22:25], v[168:171], v[200:203], v[22:25]
	v_mfma_f32_16x16x32_bf16 v[18:21], v[176:179], v[200:203], v[18:21]
	v_mfma_f32_16x16x32_bf16 v[6:9], v[168:171], v[208:211], v[6:9]
	v_mfma_f32_16x16x32_bf16 v[2:5], v[176:179], v[208:211], v[2:5]
	v_mfma_f32_16x16x32_bf16 v[54:57], v[172:175], v[188:191], v[54:57]
	v_mfma_f32_16x16x32_bf16 v[50:53], v[180:183], v[188:191], v[50:53]
	v_mfma_f32_16x16x32_bf16 v[38:41], v[172:175], v[196:199], v[38:41]
	v_mfma_f32_16x16x32_bf16 v[34:37], v[180:183], v[196:199], v[34:37]
	v_mfma_f32_16x16x32_bf16 v[22:25], v[172:175], v[204:207], v[22:25]
	v_mfma_f32_16x16x32_bf16 v[18:21], v[180:183], v[204:207], v[18:21]
	v_mfma_f32_16x16x32_bf16 v[6:9], v[172:175], v[212:215], v[6:9]
	v_mfma_f32_16x16x32_bf16 v[2:5], v[180:183], v[212:215], v[2:5]
	s_barrier
	s_add_u32 s38, s38, 0x10000
	s_addc_u32 s39, s39, 0
	s_cmp_ge_u32 s67, s56
	s_cbranch_scc0 .LBB0_2328
	s_and_b64 vcc, exec, s[14:15]
	s_cbranch_vccz .LBB0_2331
	s_barrier
